# w2 + first K-loop trip of every GEMM unit peeled: first MFMA of each accumulator chain uses SrcC=0, the 128 accumulator-clearing v_mov per wave per unit removed
# speedup vs baseline: 1.0048x; 1.0048x over previous
.LBB0_159:
	v_readlane_b32 s8, v254, 5
	v_readlane_b32 s9, v254, 6
	s_load_dword s21, s[8:9], 0x0
	s_andn2_b64 vcc, exec, s[2:3]
	s_cbranch_vccnz .LBB0_193
	v_ashrrev_i32_e32 v2, 31, v0
	v_lshrrev_b32_e32 v2, 26, v2
	v_add_u32_e32 v2, v0, v2
	v_ashrrev_i32_e32 v144, 6, v2
	v_bfe_i32 v2, v0, 27, 1
	v_lshlrev_b32_e32 v145, 4, v0
	v_lshrrev_b32_e32 v2, 22, v2
	v_add_u32_e32 v2, v145, v2
	v_and_b32_e32 v2, 0xfffffc00, v2
	v_sub_u32_e32 v2, v145, v2
	v_lshrrev_b32_e32 v3, 4, v2
	v_bitop3_b32 v2, v3, v2, 32 bitop3:0x6c
	v_ashrrev_i32_e32 v4, 31, v2
	v_lshrrev_b32_e32 v4, 26, v4
	v_add_u32_e32 v4, v2, v4
	v_lshlrev_b32_e32 v3, 3, v144
	v_ashrrev_i32_e32 v146, 6, v4
	v_and_b32_e32 v4, 0xc0, v4
	v_and_b32_e32 v3, -16, v3
	v_sub_u32_e32 v2, v2, v4
	s_mov_b64 s[2:3], 0x8200000
	v_add_u32_e32 v3, v146, v3
	v_ashrrev_i16_sdwa v2, v241, sext(v2) dst_sel:DWORD dst_unused:UNUSED_PAD src0_sel:DWORD src1_sel:BYTE_0
	s_waitcnt vmcnt(0) lgkmcnt(0)
	v_lshl_add_u64 v[130:131], v[142:143], 0, s[2:3]
	s_mov_b64 s[2:3], 0x3a200000
	v_lshlrev_b32_e32 v5, 5, v144
	v_bfe_i32 v147, v2, 0, 16
	v_lshlrev_b32_e32 v2, 1, v3
	v_lshrrev_b32_e32 v4, 2, v3
	v_and_b32_e32 v6, 3, v146
	s_mov_b32 s1, 0xfffe0
	v_lshl_add_u64 v[132:133], v[142:143], 0, s[2:3]
	s_ashr_i32 s2, s6, 6
	v_and_b32_e32 v5, 32, v5
	v_and_b32_e32 v2, 24, v2
	v_and_b32_e32 v4, 4, v4
	v_and_or_b32 v6, v3, s1, v6
	s_ashr_i32 s13, s12, 31
	v_or3_b32 v2, v6, v4, v2
	v_add_lshl_u32 v4, v5, v147, 1
	s_lshl_b32 s22, s2, 10
	s_lshl_b64 s[10:11], s[12:13], 20
	v_lshl_add_u32 v136, v2, 12, v4
	v_lshl_add_u64 v[150:151], v[132:133], 0, s[10:11]
	v_mov_b32_e32 v137, v1
	s_add_i32 s13, s22, 0
	v_lshl_add_u64 v[138:139], v[150:151], 0, v[136:137]
	s_add_i32 m0, s13, 0x10000
	v_lshl_add_u32 v134, v3, 12, v4
	s_ashr_i32 s1, s0, 31
	global_load_lds_dwordx4 v[138:139], off
	v_lshl_add_u64 v[140:141], v[138:139], 0, s[52:53]
	s_add_i32 m0, s13, 0x12000
	s_lshl_b64 s[8:9], s[0:1], 20
	global_load_lds_dwordx4 v[140:141], off
	v_lshl_add_u64 v[140:141], v[138:139], 0, s[54:55]
	s_add_i32 m0, s13, 0x14000
	v_lshl_add_u64 v[152:153], v[130:131], 0, s[8:9]
	global_load_lds_dwordx4 v[140:141], off
	v_lshl_add_u64 v[140:141], v[138:139], 0, s[56:57]
	s_add_i32 m0, s13, 0x16000
	v_mov_b32_e32 v135, v1
	global_load_lds_dwordx4 v[140:141], off
	v_lshl_add_u64 v[140:141], v[152:153], 0, v[134:135]
	s_mov_b32 m0, s13
	s_add_i32 s23, s13, 0x2000
	global_load_lds_dwordx4 v[140:141], off
	v_lshl_add_u64 v[148:149], v[140:141], 0, s[52:53]
	s_mov_b32 m0, s23
	s_add_i32 s24, s13, 0x4000
	global_load_lds_dwordx4 v[148:149], off
	v_lshl_add_u64 v[148:149], v[140:141], 0, s[54:55]
	s_mov_b32 m0, s24
	s_add_i32 s25, s13, 0x6000
	global_load_lds_dwordx4 v[148:149], off
	v_lshl_add_u64 v[148:149], v[140:141], 0, s[56:57]
	s_mov_b32 m0, s25
	s_ashr_i32 s1, s6, 8
	global_load_lds_dwordx4 v[148:149], off
	s_cmp_eq_u32 s1, 1
	s_cselect_b64 s[10:11], -1, 0
	s_cmp_lg_u32 s1, 1
	s_cbranch_scc1 .LBB0_162
	s_barrier

.LBB0_167:
	s_lshl_b32 s0, s0, 8
	v_add_u32_e32 v158, s0, v163
	s_ashr_i32 s19, s18, 31
	v_ashrrev_i32_e32 v159, 31, v158
	s_lshl_b64 s[2:3], s[18:19], 20
	s_ashr_i32 s17, s16, 31
	v_lshlrev_b64 v[160:161], 6, v[158:159]
	v_add_u32_e32 v158, s0, v164
	v_lshl_add_u64 v[146:147], v[130:131], 0, s[2:3]
	s_lshl_b64 s[2:3], s[16:17], 20
	v_ashrrev_i32_e32 v159, 31, v158
	v_lshl_add_u64 v[148:149], v[132:133], 0, s[2:3]
	v_lshlrev_b64 v[158:159], 6, v[158:159]
	v_cndmask_b32_e64 v155, v153, v147, s[8:9]
	v_cndmask_b32_e64 v0, v152, v146, s[8:9]
	v_cndmask_b32_e64 v157, v151, v149, s[8:9]
	v_cndmask_b32_e64 v154, v150, v148, s[8:9]
	v_lshl_add_u64 v[158:159], v[142:143], 0, v[158:159]
	v_lshl_add_u64 v[160:161], v[142:143], 0, v[160:161]
	v_lshl_add_u64 v[152:153], v[152:153], 0, s[66:67]
	v_lshl_add_u64 v[150:151], v[150:151], 0, s[72:73]
	s_mov_b32 s1, -2
	s_mov_b64 vcc, 0
	s_add_i32 s2, 0, 0x10000
	s_add_i32 s3, 0, 0x14000
	v_lshl_add_u64 v[168:169], v[152:153], 0, s[74:75]
	v_add_u32_e32 v180, s2, v162
	v_add_u32_e32 v196, s3, v162
	v_cndmask_b32_e32 v205, v169, v155, vcc
	v_cndmask_b32_e32 v204, v168, v0, vcc
	ds_read_b128 v[168:171], v180
	ds_read_b128 v[172:175], v180 offset:1024
	ds_read_b128 v[176:179], v180 offset:2048
	ds_read_b128 v[180:183], v180 offset:3072
	ds_read_b128 v[184:187], v196
	ds_read_b128 v[188:191], v196 offset:1024
	ds_read_b128 v[192:195], v196 offset:2048
	ds_read_b128 v[196:199], v196 offset:3072
	v_cndmask_b32_e32 v207, v151, v157, vcc
	v_cndmask_b32_e32 v206, v150, v154, vcc
	v_lshl_add_u64 v[238:239], v[152:153], 0, v[144:145]
	s_add_i32 m0, s13, 0xc000
	ds_read_b128 v[200:203], v166
	ds_read_b128 v[210:213], v166 offset:1024
	ds_read_b128 v[214:217], v166 offset:2048
	ds_read_b128 v[218:221], v166 offset:3072
	ds_read_b128 v[222:225], v166 offset:4096
	ds_read_b128 v[226:229], v166 offset:5120
	ds_read_b128 v[230:233], v166 offset:6144
	ds_read_b128 v[234:237], v166 offset:7168
	global_load_lds_dwordx4 v[238:239], off
	v_lshl_add_u64 v[238:239], v[238:239], 0, s[52:53]
	s_add_i32 m0, s13, 0xe000
	s_nop 0
	global_load_lds_dwordx4 v[238:239], off
	s_waitcnt vmcnt(8)
	s_waitcnt lgkmcnt(0)
	s_barrier
	s_setprio 1
	s_waitcnt lgkmcnt(0)
	v_mfma_f32_16x16x32_bf16 v[122:125], v[168:171], v[200:203], 0
	v_mfma_f32_16x16x32_bf16 v[126:129], v[176:179], v[200:203], 0
	v_mfma_f32_16x16x32_bf16 v[106:109], v[168:171], v[214:217], 0
	v_mfma_f32_16x16x32_bf16 v[110:113], v[176:179], v[214:217], 0
	v_mfma_f32_16x16x32_bf16 v[90:93], v[168:171], v[222:225], 0
	v_mfma_f32_16x16x32_bf16 v[94:97], v[176:179], v[222:225], 0
	v_mfma_f32_16x16x32_bf16 v[74:77], v[168:171], v[230:233], 0
	v_mfma_f32_16x16x32_bf16 v[78:81], v[176:179], v[230:233], 0
	v_mfma_f32_16x16x32_bf16 v[122:125], v[172:175], v[210:213], v[122:125]
	v_mfma_f32_16x16x32_bf16 v[126:129], v[180:183], v[210:213], v[126:129]
	v_mfma_f32_16x16x32_bf16 v[106:109], v[172:175], v[218:221], v[106:109]
	v_mfma_f32_16x16x32_bf16 v[110:113], v[180:183], v[218:221], v[110:113]
	v_mfma_f32_16x16x32_bf16 v[90:93], v[172:175], v[226:229], v[90:93]
	v_mfma_f32_16x16x32_bf16 v[94:97], v[180:183], v[226:229], v[94:97]
	v_mfma_f32_16x16x32_bf16 v[74:77], v[172:175], v[234:237], v[74:77]
	v_mfma_f32_16x16x32_bf16 v[78:81], v[180:183], v[234:237], v[78:81]
	s_setprio 0
	s_setprio 1
	v_mfma_f32_16x16x32_bf16 v[114:117], v[184:187], v[200:203], 0
	v_mfma_f32_16x16x32_bf16 v[118:121], v[192:195], v[200:203], 0
	v_mfma_f32_16x16x32_bf16 v[98:101], v[184:187], v[214:217], 0
	v_mfma_f32_16x16x32_bf16 v[102:105], v[192:195], v[214:217], 0
	v_mfma_f32_16x16x32_bf16 v[82:85], v[184:187], v[222:225], 0
	v_mfma_f32_16x16x32_bf16 v[86:89], v[192:195], v[222:225], 0
	v_mfma_f32_16x16x32_bf16 v[66:69], v[184:187], v[230:233], 0
	v_mfma_f32_16x16x32_bf16 v[70:73], v[192:195], v[230:233], 0
	v_mfma_f32_16x16x32_bf16 v[114:117], v[188:191], v[210:213], v[114:117]
	v_mfma_f32_16x16x32_bf16 v[118:121], v[196:199], v[210:213], v[118:121]
	v_mfma_f32_16x16x32_bf16 v[98:101], v[188:191], v[218:221], v[98:101]
	v_mfma_f32_16x16x32_bf16 v[102:105], v[196:199], v[218:221], v[102:105]
	v_mfma_f32_16x16x32_bf16 v[82:85], v[188:191], v[226:229], v[82:85]
	v_mfma_f32_16x16x32_bf16 v[86:89], v[196:199], v[226:229], v[86:89]
	v_mfma_f32_16x16x32_bf16 v[66:69], v[188:191], v[234:237], v[66:69]
	v_mfma_f32_16x16x32_bf16 v[70:73], v[196:199], v[234:237], v[70:73]
	s_setprio 0
	s_barrier
	s_add_i32 s2, s2, s22
	v_lshl_add_u64 v[206:207], v[206:207], 0, v[136:137]
	s_mov_b32 m0, s2
	ds_read_b128 v[200:203], v166 offset:16384
	ds_read_b128 v[210:213], v166 offset:17408
	ds_read_b128 v[214:217], v166 offset:18432
	ds_read_b128 v[218:221], v166 offset:19456
	ds_read_b128 v[222:225], v166 offset:20480
	ds_read_b128 v[226:229], v166 offset:21504
	ds_read_b128 v[230:233], v166 offset:22528
	ds_read_b128 v[234:237], v166 offset:23552
	global_load_lds_dwordx4 v[206:207], off
	v_lshl_add_u64 v[238:239], v[206:207], 0, s[52:53]
	s_add_i32 m0, s2, 0x2000
	s_add_i32 s2, s3, s22
	global_load_lds_dwordx4 v[238:239], off
	v_lshl_add_u64 v[238:239], v[206:207], 0, s[54:55]
	s_mov_b32 m0, s2
	v_lshl_add_u64 v[204:205], v[204:205], 0, v[134:135]
	global_load_lds_dwordx4 v[238:239], off
	v_lshl_add_u64 v[238:239], v[206:207], 0, s[56:57]
	s_add_i32 m0, s2, 0x2000
	s_nop 0
	global_load_lds_dwordx4 v[238:239], off
	s_mov_b32 m0, s13
	v_lshl_add_u64 v[238:239], v[204:205], 0, s[52:53]
	global_load_lds_dwordx4 v[204:205], off
	s_mov_b32 m0, s23
	s_nop 0
	global_load_lds_dwordx4 v[238:239], off
	s_waitcnt vmcnt(8)
	s_waitcnt lgkmcnt(0)
	s_barrier
	s_setprio 1
	s_waitcnt lgkmcnt(0)
	v_mfma_f32_16x16x32_bf16 v[58:61], v[168:171], v[200:203], 0
	v_mfma_f32_16x16x32_bf16 v[62:65], v[176:179], v[200:203], 0
	v_mfma_f32_16x16x32_bf16 v[42:45], v[168:171], v[214:217], 0
	v_mfma_f32_16x16x32_bf16 v[46:49], v[176:179], v[214:217], 0
	v_mfma_f32_16x16x32_bf16 v[26:29], v[168:171], v[222:225], 0
	v_mfma_f32_16x16x32_bf16 v[30:33], v[176:179], v[222:225], 0
	v_mfma_f32_16x16x32_bf16 v[10:13], v[168:171], v[230:233], 0
	v_mfma_f32_16x16x32_bf16 v[14:17], v[176:179], v[230:233], 0
	v_mfma_f32_16x16x32_bf16 v[58:61], v[172:175], v[210:213], v[58:61]
	v_mfma_f32_16x16x32_bf16 v[62:65], v[180:183], v[210:213], v[62:65]
	v_mfma_f32_16x16x32_bf16 v[42:45], v[172:175], v[218:221], v[42:45]
	v_mfma_f32_16x16x32_bf16 v[46:49], v[180:183], v[218:221], v[46:49]
	v_mfma_f32_16x16x32_bf16 v[26:29], v[172:175], v[226:229], v[26:29]
	v_mfma_f32_16x16x32_bf16 v[30:33], v[180:183], v[226:229], v[30:33]
	v_mfma_f32_16x16x32_bf16 v[10:13], v[172:175], v[234:237], v[10:13]
	v_mfma_f32_16x16x32_bf16 v[14:17], v[180:183], v[234:237], v[14:17]
	s_setprio 0
	s_setprio 1
	v_mfma_f32_16x16x32_bf16 v[50:53], v[184:187], v[200:203], 0
	v_mfma_f32_16x16x32_bf16 v[54:57], v[192:195], v[200:203], 0
	v_mfma_f32_16x16x32_bf16 v[34:37], v[184:187], v[214:217], 0
	v_mfma_f32_16x16x32_bf16 v[38:41], v[192:195], v[214:217], 0
	v_mfma_f32_16x16x32_bf16 v[18:21], v[184:187], v[222:225], 0
	v_mfma_f32_16x16x32_bf16 v[22:25], v[192:195], v[222:225], 0
	v_mfma_f32_16x16x32_bf16 v[2:5], v[184:187], v[230:233], 0
	v_mfma_f32_16x16x32_bf16 v[6:9], v[192:195], v[230:233], 0
	v_mfma_f32_16x16x32_bf16 v[50:53], v[188:191], v[210:213], v[50:53]
	v_mfma_f32_16x16x32_bf16 v[54:57], v[196:199], v[210:213], v[54:57]
	v_mfma_f32_16x16x32_bf16 v[34:37], v[188:191], v[218:221], v[34:37]
	v_mfma_f32_16x16x32_bf16 v[38:41], v[196:199], v[218:221], v[38:41]
	v_mfma_f32_16x16x32_bf16 v[18:21], v[188:191], v[226:229], v[18:21]
	v_mfma_f32_16x16x32_bf16 v[22:25], v[196:199], v[226:229], v[22:25]
	v_mfma_f32_16x16x32_bf16 v[2:5], v[188:191], v[234:237], v[2:5]
	v_mfma_f32_16x16x32_bf16 v[6:9], v[196:199], v[234:237], v[6:9]
	s_setprio 0
	s_barrier
	s_add_i32 s2, 0, 0x18000
	s_add_i32 s3, 0, 0x1c000
	v_add_u32_e32 v180, s2, v162
	v_add_u32_e32 v196, s3, v162
	ds_read_b128 v[168:171], v180
	ds_read_b128 v[172:175], v180 offset:1024
	ds_read_b128 v[176:179], v180 offset:2048
	ds_read_b128 v[180:183], v180 offset:3072
	ds_read_b128 v[184:187], v196
	ds_read_b128 v[188:191], v196 offset:1024
	ds_read_b128 v[192:195], v196 offset:2048
	ds_read_b128 v[196:199], v196 offset:3072
	s_mov_b32 m0, s24
	v_lshl_add_u64 v[238:239], v[204:205], 0, s[54:55]
	ds_read_b128 v[200:203], v166 offset:32768
	ds_read_b128 v[210:213], v166 offset:33792
	ds_read_b128 v[214:217], v166 offset:34816
	ds_read_b128 v[218:221], v166 offset:35840
	ds_read_b128 v[222:225], v166 offset:36864
	ds_read_b128 v[226:229], v166 offset:37888
	ds_read_b128 v[230:233], v166 offset:38912
	ds_read_b128 v[234:237], v166 offset:39936
	global_load_lds_dwordx4 v[238:239], off
	v_lshl_add_u64 v[238:239], v[204:205], 0, s[56:57]
	s_mov_b32 m0, s25
	s_nop 0
	global_load_lds_dwordx4 v[238:239], off
	s_waitcnt vmcnt(8)
	s_waitcnt lgkmcnt(0)
	s_barrier
	s_setprio 1
	s_waitcnt lgkmcnt(0)
	v_mfma_f32_16x16x32_bf16 v[122:125], v[168:171], v[200:203], v[122:125]
	v_mfma_f32_16x16x32_bf16 v[126:129], v[176:179], v[200:203], v[126:129]
	v_mfma_f32_16x16x32_bf16 v[106:109], v[168:171], v[214:217], v[106:109]
	v_mfma_f32_16x16x32_bf16 v[110:113], v[176:179], v[214:217], v[110:113]
	v_mfma_f32_16x16x32_bf16 v[90:93], v[168:171], v[222:225], v[90:93]
	v_mfma_f32_16x16x32_bf16 v[94:97], v[176:179], v[222:225], v[94:97]
	v_mfma_f32_16x16x32_bf16 v[74:77], v[168:171], v[230:233], v[74:77]
	v_mfma_f32_16x16x32_bf16 v[78:81], v[176:179], v[230:233], v[78:81]
	v_mfma_f32_16x16x32_bf16 v[122:125], v[172:175], v[210:213], v[122:125]
	v_mfma_f32_16x16x32_bf16 v[126:129], v[180:183], v[210:213], v[126:129]
	v_mfma_f32_16x16x32_bf16 v[106:109], v[172:175], v[218:221], v[106:109]
	v_mfma_f32_16x16x32_bf16 v[110:113], v[180:183], v[218:221], v[110:113]
	v_mfma_f32_16x16x32_bf16 v[90:93], v[172:175], v[226:229], v[90:93]
	v_mfma_f32_16x16x32_bf16 v[94:97], v[180:183], v[226:229], v[94:97]
	v_mfma_f32_16x16x32_bf16 v[74:77], v[172:175], v[234:237], v[74:77]
	v_mfma_f32_16x16x32_bf16 v[78:81], v[180:183], v[234:237], v[78:81]
	s_setprio 0
	s_setprio 1
	v_mfma_f32_16x16x32_bf16 v[114:117], v[184:187], v[200:203], v[114:117]
	v_mfma_f32_16x16x32_bf16 v[118:121], v[192:195], v[200:203], v[118:121]
	v_mfma_f32_16x16x32_bf16 v[98:101], v[184:187], v[214:217], v[98:101]
	v_mfma_f32_16x16x32_bf16 v[102:105], v[192:195], v[214:217], v[102:105]
	v_mfma_f32_16x16x32_bf16 v[82:85], v[184:187], v[222:225], v[82:85]
	v_mfma_f32_16x16x32_bf16 v[86:89], v[192:195], v[222:225], v[86:89]
	v_mfma_f32_16x16x32_bf16 v[66:69], v[184:187], v[230:233], v[66:69]
	v_mfma_f32_16x16x32_bf16 v[70:73], v[192:195], v[230:233], v[70:73]
	v_mfma_f32_16x16x32_bf16 v[114:117], v[188:191], v[210:213], v[114:117]
	v_mfma_f32_16x16x32_bf16 v[118:121], v[196:199], v[210:213], v[118:121]
	v_mfma_f32_16x16x32_bf16 v[98:101], v[188:191], v[218:221], v[98:101]
	v_mfma_f32_16x16x32_bf16 v[102:105], v[196:199], v[218:221], v[102:105]
	v_mfma_f32_16x16x32_bf16 v[82:85], v[188:191], v[226:229], v[82:85]
	v_mfma_f32_16x16x32_bf16 v[86:89], v[196:199], v[226:229], v[86:89]
	v_mfma_f32_16x16x32_bf16 v[66:69], v[188:191], v[234:237], v[66:69]
	v_mfma_f32_16x16x32_bf16 v[70:73], v[196:199], v[234:237], v[70:73]
	s_setprio 0
	s_barrier
	s_add_i32 s2, s2, s22
	v_lshl_add_u64 v[238:239], v[206:207], 0, s[62:63]
	s_mov_b32 m0, s2
	ds_read_b128 v[200:203], v166 offset:49152
	ds_read_b128 v[210:213], v166 offset:50176
	ds_read_b128 v[214:217], v166 offset:51200
	ds_read_b128 v[218:221], v166 offset:52224
	ds_read_b128 v[222:225], v166 offset:53248
	ds_read_b128 v[226:229], v166 offset:54272
	ds_read_b128 v[230:233], v166 offset:55296
	ds_read_b128 v[234:237], v166 offset:56320
	global_load_lds_dwordx4 v[238:239], off
	v_lshl_add_u64 v[238:239], v[206:207], 0, s[64:65]
	s_add_i32 m0, s2, 0x2000
	s_add_i32 s2, s3, s22
	global_load_lds_dwordx4 v[238:239], off
	v_lshl_add_u64 v[238:239], v[206:207], 0, s[66:67]
	s_mov_b32 m0, s2
	v_lshl_add_u64 v[206:207], v[206:207], 0, s[68:69]
	global_load_lds_dwordx4 v[238:239], off
	s_add_i32 m0, s2, 0x2000
	s_nop 0
	global_load_lds_dwordx4 v[206:207], off
	v_lshl_add_u64 v[206:207], v[204:205], 0, s[62:63]
	s_mov_b32 m0, s26
	v_lshl_add_u64 v[204:205], v[204:205], 0, s[64:65]
	global_load_lds_dwordx4 v[206:207], off
	s_mov_b32 m0, s27
	s_nop 0
	global_load_lds_dwordx4 v[204:205], off
	s_waitcnt vmcnt(8)
	s_waitcnt lgkmcnt(0)
	s_barrier
	s_setprio 1
	s_waitcnt lgkmcnt(0)
	v_mfma_f32_16x16x32_bf16 v[58:61], v[168:171], v[200:203], v[58:61]
	v_mfma_f32_16x16x32_bf16 v[62:65], v[176:179], v[200:203], v[62:65]
	v_mfma_f32_16x16x32_bf16 v[42:45], v[168:171], v[214:217], v[42:45]
	v_mfma_f32_16x16x32_bf16 v[46:49], v[176:179], v[214:217], v[46:49]
	v_mfma_f32_16x16x32_bf16 v[26:29], v[168:171], v[222:225], v[26:29]
	v_mfma_f32_16x16x32_bf16 v[30:33], v[176:179], v[222:225], v[30:33]
	v_mfma_f32_16x16x32_bf16 v[10:13], v[168:171], v[230:233], v[10:13]
	v_mfma_f32_16x16x32_bf16 v[14:17], v[176:179], v[230:233], v[14:17]
	v_mfma_f32_16x16x32_bf16 v[58:61], v[172:175], v[210:213], v[58:61]
	v_mfma_f32_16x16x32_bf16 v[62:65], v[180:183], v[210:213], v[62:65]
	v_mfma_f32_16x16x32_bf16 v[42:45], v[172:175], v[218:221], v[42:45]
	v_mfma_f32_16x16x32_bf16 v[46:49], v[180:183], v[218:221], v[46:49]
	v_mfma_f32_16x16x32_bf16 v[26:29], v[172:175], v[226:229], v[26:29]
	v_mfma_f32_16x16x32_bf16 v[30:33], v[180:183], v[226:229], v[30:33]
	v_mfma_f32_16x16x32_bf16 v[10:13], v[172:175], v[234:237], v[10:13]
	v_mfma_f32_16x16x32_bf16 v[14:17], v[180:183], v[234:237], v[14:17]
	s_setprio 0
	s_setprio 1
	v_mfma_f32_16x16x32_bf16 v[50:53], v[184:187], v[200:203], v[50:53]
	v_mfma_f32_16x16x32_bf16 v[54:57], v[192:195], v[200:203], v[54:57]
	v_mfma_f32_16x16x32_bf16 v[34:37], v[184:187], v[214:217], v[34:37]
	v_mfma_f32_16x16x32_bf16 v[38:41], v[192:195], v[214:217], v[38:41]
	v_mfma_f32_16x16x32_bf16 v[18:21], v[184:187], v[222:225], v[18:21]
	v_mfma_f32_16x16x32_bf16 v[22:25], v[192:195], v[222:225], v[22:25]
	v_mfma_f32_16x16x32_bf16 v[2:5], v[184:187], v[230:233], v[2:5]
	v_mfma_f32_16x16x32_bf16 v[6:9], v[192:195], v[230:233], v[6:9]
	v_mfma_f32_16x16x32_bf16 v[50:53], v[188:191], v[210:213], v[50:53]
	v_mfma_f32_16x16x32_bf16 v[54:57], v[196:199], v[210:213], v[54:57]
	v_mfma_f32_16x16x32_bf16 v[34:37], v[188:191], v[218:221], v[34:37]
	v_mfma_f32_16x16x32_bf16 v[38:41], v[196:199], v[218:221], v[38:41]
	v_mfma_f32_16x16x32_bf16 v[18:21], v[188:191], v[226:229], v[18:21]
	v_mfma_f32_16x16x32_bf16 v[22:25], v[196:199], v[226:229], v[22:25]
	v_mfma_f32_16x16x32_bf16 v[2:5], v[188:191], v[234:237], v[2:5]
	v_mfma_f32_16x16x32_bf16 v[6:9], v[196:199], v[234:237], v[6:9]
	s_setprio 0
	s_barrier
	s_add_i32 s1, s1, 2
	v_lshl_add_u64 v[152:153], v[152:153], 0, s[72:73]
	s_cmp_gt_u32 s1, 29
	v_lshl_add_u64 v[150:151], v[150:151], 0, s[72:73]
	s_branch .LBB0_169

.LBB0_189:
	s_or_b64 exec, exec, s[0:1]
	s_andn2_b64 vcc, exec, s[8:9]
	s_mov_b64 s[0:1], -1
	s_cbranch_vccnz .LBB0_164
	s_andn2_b64 vcc, exec, s[10:11]
	s_cbranch_vccnz .LBB0_163
	s_barrier
	s_branch .LBB0_163

.LBB0_411:
	v_readlane_b32 s6, v254, 5
	v_readlane_b32 s7, v254, 6
	s_waitcnt lgkmcnt(0)
	s_load_dword s21, s[6:7], 0x0
	s_andn2_b64 vcc, exec, s[0:1]
	s_cbranch_vccnz .LBB0_443
	v_ashrrev_i32_e32 v3, 31, v0
	v_lshrrev_b32_e32 v3, 26, v3
	v_add_u32_e32 v3, v0, v3
	v_ashrrev_i32_e32 v140, 6, v3
	v_bfe_i32 v3, v0, 27, 1
	v_lshlrev_b32_e32 v2, 4, v0
	v_lshrrev_b32_e32 v3, 22, v3
	v_add_u32_e32 v3, v2, v3
	v_and_b32_e32 v3, 0xfffffc00, v3
	v_sub_u32_e32 v2, v2, v3
	v_lshrrev_b32_e32 v3, 4, v2
	v_bitop3_b32 v2, v3, v2, 32 bitop3:0x6c
	v_ashrrev_i32_e32 v4, 31, v2
	v_lshrrev_b32_e32 v4, 26, v4
	v_add_u32_e32 v4, v2, v4
	v_lshlrev_b32_e32 v3, 3, v140
	v_ashrrev_i32_e32 v141, 6, v4
	v_and_b32_e32 v4, 0xc0, v4
	s_mov_b64 s[0:1], 0x12200000
	v_and_b32_e32 v3, -16, v3
	v_sub_u32_e32 v2, v2, v4
	s_waitcnt vmcnt(0)
	v_lshl_add_u64 v[194:195], v[132:133], 0, s[0:1]
	s_mov_b64 s[0:1], 0x3ba00000
	v_add_u32_e32 v3, v141, v3
	v_ashrrev_i16_sdwa v2, v241, sext(v2) dst_sel:DWORD dst_unused:UNUSED_PAD src0_sel:DWORD src1_sel:BYTE_0
	v_lshl_add_u64 v[196:197], v[132:133], 0, s[0:1]
	v_lshlrev_b32_e32 v5, 5, v140
	v_bfe_i32 v142, v2, 0, 16
	v_lshlrev_b32_e32 v2, 1, v3
	v_lshrrev_b32_e32 v4, 2, v3
	v_and_b32_e32 v6, 3, v141
	s_mov_b32 s0, 0xfffe0
	s_ashr_i32 s3, s2, 6
	v_and_b32_e32 v5, 32, v5
	v_and_b32_e32 v2, 24, v2
	v_and_b32_e32 v4, 4, v4
	v_and_or_b32 v6, v3, s0, v6
	s_ashr_i32 s15, s14, 31
	v_or3_b32 v2, v6, v4, v2
	v_add_lshl_u32 v4, v5, v142, 1
	s_lshl_b32 s22, s3, 10
	s_lshl_b64 s[6:7], s[14:15], 20
	v_lshl_add_u32 v200, v2, 12, v4
	v_lshl_add_u64 v[130:131], v[196:197], 0, s[6:7]
	v_mov_b32_e32 v201, v1
	s_add_i32 s23, s22, 0
	v_lshl_add_u64 v[136:137], v[130:131], 0, v[200:201]
	s_add_i32 m0, s23, 0x10000
	v_lshl_add_u32 v198, v3, 13, v4
	global_load_lds_dwordx4 v[136:137], off
	v_lshl_add_u64 v[134:135], v[136:137], 0, s[52:53]
	s_add_i32 m0, s23, 0x12000
	s_ashr_i32 s17, s16, 31
	global_load_lds_dwordx4 v[134:135], off
	v_lshl_add_u64 v[134:135], v[136:137], 0, s[54:55]
	s_add_i32 m0, s23, 0x14000
	s_lshl_b64 s[0:1], s[16:17], 21
	global_load_lds_dwordx4 v[134:135], off
	v_lshl_add_u64 v[134:135], v[136:137], 0, s[56:57]
	s_add_i32 m0, s23, 0x16000
	v_mov_b32_e32 v199, v1
	global_load_lds_dwordx4 v[134:135], off
	v_lshl_add_u64 v[134:135], v[194:195], 0, s[0:1]
	v_lshl_add_u64 v[138:139], v[134:135], 0, v[198:199]
	s_mov_b32 m0, s23
	s_add_i32 s24, s23, 0x2000
	global_load_lds_dwordx4 v[138:139], off
	v_lshl_add_u64 v[144:145], v[138:139], 0, s[54:55]
	s_mov_b32 m0, s24
	s_add_i32 s25, s23, 0x4000
	global_load_lds_dwordx4 v[144:145], off
	v_lshl_add_u64 v[144:145], v[138:139], 0, s[84:85]
	s_mov_b32 m0, s25
	s_add_i32 s26, s23, 0x6000
	global_load_lds_dwordx4 v[144:145], off
	v_lshl_add_u64 v[144:145], v[138:139], 0, s[86:87]
	s_mov_b32 m0, s26
	s_ashr_i32 s6, s2, 8
	global_load_lds_dwordx4 v[144:145], off
	s_cmp_eq_u32 s6, 1
	s_cselect_b64 s[0:1], -1, 0
	s_cmp_lg_u32 s6, 1
	s_cbranch_scc1 .LBB0_414
	s_barrier

.LBB0_419:
	s_ashr_i32 s13, s12, 31
	s_lshl_b64 s[18:19], s[12:13], 21
	s_ashr_i32 s11, s10, 31
	v_lshl_add_u64 v[212:213], v[194:195], 0, s[18:19]
	s_lshl_b64 s[18:19], s[10:11], 20
	v_lshl_add_u64 v[214:215], v[196:197], 0, s[18:19]
	v_cndmask_b32_e64 v133, v135, v213, s[8:9]
	v_cndmask_b32_e64 v0, v134, v212, s[8:9]
	v_cndmask_b32_e64 v137, v131, v215, s[8:9]
	v_cndmask_b32_e64 v132, v130, v214, s[8:9]
	v_lshl_add_u64 v[134:135], v[134:135], 0, s[70:71]
	v_lshl_add_u64 v[130:131], v[130:131], 0, s[72:73]
	s_mov_b32 s11, -2
	s_cmp_eq_u32 s11, 28
	s_cselect_b64 vcc, -1, 0
	s_add_i32 s13, 0, 0x10000
	v_add_u32_e32 v136, s13, v239
	s_add_i32 s15, 0, 0x14000
	ds_read_b128 v[138:141], v136
	ds_read_b128 v[142:145], v136 offset:1024
	ds_read_b128 v[146:149], v136 offset:2048
	ds_read_b128 v[150:153], v136 offset:3072
	v_add_u32_e32 v136, s15, v239
	ds_read_b128 v[154:157], v136
	ds_read_b128 v[158:161], v136 offset:1024
	ds_read_b128 v[162:165], v136 offset:2048
	ds_read_b128 v[166:169], v136 offset:3072
	s_mov_b32 s18, 0xfff00080
	s_mov_b32 s19, -1
	v_lshl_add_u64 v[170:171], v[134:135], 0, s[18:19]
	v_cndmask_b32_e32 v207, v171, v133, vcc
	v_cndmask_b32_e32 v206, v170, v0, vcc
	v_cndmask_b32_e32 v225, v131, v137, vcc
	v_cndmask_b32_e32 v224, v130, v132, vcc
	v_lshl_add_u64 v[226:227], v[134:135], 0, v[210:211]
	s_add_i32 m0, s23, 0xc000
	ds_read_b128 v[170:173], v251
	ds_read_b128 v[174:177], v251 offset:1024
	ds_read_b128 v[178:181], v251 offset:2048
	ds_read_b128 v[182:185], v251 offset:3072
	ds_read_b128 v[186:189], v251 offset:4096
	ds_read_b128 v[190:193], v251 offset:5120
	ds_read_b128 v[216:219], v251 offset:6144
	ds_read_b128 v[220:223], v251 offset:7168
	global_load_lds_dwordx4 v[226:227], off
	v_lshl_add_u64 v[226:227], v[226:227], 0, s[54:55]
	s_add_i32 m0, s23, 0xe000
	s_nop 0
	global_load_lds_dwordx4 v[226:227], off
	s_waitcnt vmcnt(8)
	s_waitcnt lgkmcnt(0)
	s_barrier
	s_setprio 1
	s_waitcnt lgkmcnt(0)
	v_mfma_f32_16x16x32_bf16 v[122:125], v[138:141], v[170:173], 0
	v_mfma_f32_16x16x32_bf16 v[126:129], v[146:149], v[170:173], 0
	v_mfma_f32_16x16x32_bf16 v[110:113], v[138:141], v[178:181], 0
	v_mfma_f32_16x16x32_bf16 v[106:109], v[146:149], v[178:181], 0
	v_mfma_f32_16x16x32_bf16 v[94:97], v[138:141], v[186:189], 0
	v_mfma_f32_16x16x32_bf16 v[90:93], v[146:149], v[186:189], 0
	v_mfma_f32_16x16x32_bf16 v[78:81], v[138:141], v[216:219], 0
	v_mfma_f32_16x16x32_bf16 v[74:77], v[146:149], v[216:219], 0
	v_mfma_f32_16x16x32_bf16 v[122:125], v[142:145], v[174:177], v[122:125]
	v_mfma_f32_16x16x32_bf16 v[126:129], v[150:153], v[174:177], v[126:129]
	v_mfma_f32_16x16x32_bf16 v[110:113], v[142:145], v[182:185], v[110:113]
	v_mfma_f32_16x16x32_bf16 v[106:109], v[150:153], v[182:185], v[106:109]
	v_mfma_f32_16x16x32_bf16 v[94:97], v[142:145], v[190:193], v[94:97]
	v_mfma_f32_16x16x32_bf16 v[90:93], v[150:153], v[190:193], v[90:93]
	v_mfma_f32_16x16x32_bf16 v[78:81], v[142:145], v[220:223], v[78:81]
	v_mfma_f32_16x16x32_bf16 v[74:77], v[150:153], v[220:223], v[74:77]
	s_setprio 0
	s_setprio 1
	v_mfma_f32_16x16x32_bf16 v[118:121], v[154:157], v[170:173], 0
	v_mfma_f32_16x16x32_bf16 v[114:117], v[162:165], v[170:173], 0
	v_mfma_f32_16x16x32_bf16 v[102:105], v[154:157], v[178:181], 0
	v_mfma_f32_16x16x32_bf16 v[98:101], v[162:165], v[178:181], 0
	v_mfma_f32_16x16x32_bf16 v[86:89], v[154:157], v[186:189], 0
	v_mfma_f32_16x16x32_bf16 v[82:85], v[162:165], v[186:189], 0
	v_mfma_f32_16x16x32_bf16 v[70:73], v[154:157], v[216:219], 0
	v_mfma_f32_16x16x32_bf16 v[66:69], v[162:165], v[216:219], 0
	v_mfma_f32_16x16x32_bf16 v[118:121], v[158:161], v[174:177], v[118:121]
	v_mfma_f32_16x16x32_bf16 v[114:117], v[166:169], v[174:177], v[114:117]
	v_mfma_f32_16x16x32_bf16 v[102:105], v[158:161], v[182:185], v[102:105]
	v_mfma_f32_16x16x32_bf16 v[98:101], v[166:169], v[182:185], v[98:101]
	v_mfma_f32_16x16x32_bf16 v[86:89], v[158:161], v[190:193], v[86:89]
	v_mfma_f32_16x16x32_bf16 v[82:85], v[166:169], v[190:193], v[82:85]
	v_mfma_f32_16x16x32_bf16 v[70:73], v[158:161], v[220:223], v[70:73]
	v_mfma_f32_16x16x32_bf16 v[66:69], v[166:169], v[220:223], v[66:69]
	s_setprio 0
	s_barrier
	s_add_i32 s13, s13, s22
	v_lshl_add_u64 v[224:225], v[224:225], 0, v[200:201]
	s_mov_b32 m0, s13
	ds_read_b128 v[170:173], v251 offset:16384
	ds_read_b128 v[174:177], v251 offset:17408
	ds_read_b128 v[178:181], v251 offset:18432
	ds_read_b128 v[182:185], v251 offset:19456
	ds_read_b128 v[186:189], v251 offset:20480
	ds_read_b128 v[190:193], v251 offset:21504
	ds_read_b128 v[216:219], v251 offset:22528
	ds_read_b128 v[220:223], v251 offset:23552
	global_load_lds_dwordx4 v[224:225], off
	v_lshl_add_u64 v[226:227], v[224:225], 0, s[52:53]
	s_add_i32 m0, s13, 0x2000
	s_add_i32 s13, s15, s22
	global_load_lds_dwordx4 v[226:227], off
	v_lshl_add_u64 v[226:227], v[224:225], 0, s[54:55]
	s_mov_b32 m0, s13
	v_lshl_add_u64 v[206:207], v[206:207], 0, v[198:199]
	global_load_lds_dwordx4 v[226:227], off
	v_lshl_add_u64 v[226:227], v[224:225], 0, s[56:57]
	s_add_i32 m0, s13, 0x2000
	s_nop 0
	global_load_lds_dwordx4 v[226:227], off
	s_mov_b32 m0, s23
	v_lshl_add_u64 v[226:227], v[206:207], 0, s[54:55]
	global_load_lds_dwordx4 v[206:207], off
	s_mov_b32 m0, s24
	s_nop 0
	global_load_lds_dwordx4 v[226:227], off
	s_waitcnt vmcnt(8)
	s_waitcnt lgkmcnt(0)
	s_barrier
	s_setprio 1
	s_waitcnt lgkmcnt(0)
	v_mfma_f32_16x16x32_bf16 v[62:65], v[138:141], v[170:173], 0
	v_mfma_f32_16x16x32_bf16 v[58:61], v[146:149], v[170:173], 0
	v_mfma_f32_16x16x32_bf16 v[46:49], v[138:141], v[178:181], 0
	v_mfma_f32_16x16x32_bf16 v[42:45], v[146:149], v[178:181], 0
	v_mfma_f32_16x16x32_bf16 v[30:33], v[138:141], v[186:189], 0
	v_mfma_f32_16x16x32_bf16 v[26:29], v[146:149], v[186:189], 0
	v_mfma_f32_16x16x32_bf16 v[14:17], v[138:141], v[216:219], 0
	v_mfma_f32_16x16x32_bf16 v[10:13], v[146:149], v[216:219], 0
	v_mfma_f32_16x16x32_bf16 v[62:65], v[142:145], v[174:177], v[62:65]
	v_mfma_f32_16x16x32_bf16 v[58:61], v[150:153], v[174:177], v[58:61]
	v_mfma_f32_16x16x32_bf16 v[46:49], v[142:145], v[182:185], v[46:49]
	v_mfma_f32_16x16x32_bf16 v[42:45], v[150:153], v[182:185], v[42:45]
	v_mfma_f32_16x16x32_bf16 v[30:33], v[142:145], v[190:193], v[30:33]
	v_mfma_f32_16x16x32_bf16 v[26:29], v[150:153], v[190:193], v[26:29]
	v_mfma_f32_16x16x32_bf16 v[14:17], v[142:145], v[220:223], v[14:17]
	v_mfma_f32_16x16x32_bf16 v[10:13], v[150:153], v[220:223], v[10:13]
	s_setprio 0
	s_setprio 1
	v_mfma_f32_16x16x32_bf16 v[54:57], v[154:157], v[170:173], 0
	v_mfma_f32_16x16x32_bf16 v[50:53], v[162:165], v[170:173], 0
	v_mfma_f32_16x16x32_bf16 v[38:41], v[154:157], v[178:181], 0
	v_mfma_f32_16x16x32_bf16 v[34:37], v[162:165], v[178:181], 0
	v_mfma_f32_16x16x32_bf16 v[22:25], v[154:157], v[186:189], 0
	v_mfma_f32_16x16x32_bf16 v[18:21], v[162:165], v[186:189], 0
	v_mfma_f32_16x16x32_bf16 v[6:9], v[154:157], v[216:219], 0
	v_mfma_f32_16x16x32_bf16 v[2:5], v[162:165], v[216:219], 0
	v_mfma_f32_16x16x32_bf16 v[54:57], v[158:161], v[174:177], v[54:57]
	v_mfma_f32_16x16x32_bf16 v[50:53], v[166:169], v[174:177], v[50:53]
	v_mfma_f32_16x16x32_bf16 v[38:41], v[158:161], v[182:185], v[38:41]
	v_mfma_f32_16x16x32_bf16 v[34:37], v[166:169], v[182:185], v[34:37]
	v_mfma_f32_16x16x32_bf16 v[22:25], v[158:161], v[190:193], v[22:25]
	v_mfma_f32_16x16x32_bf16 v[18:21], v[166:169], v[190:193], v[18:21]
	v_mfma_f32_16x16x32_bf16 v[6:9], v[158:161], v[220:223], v[6:9]
	v_mfma_f32_16x16x32_bf16 v[2:5], v[166:169], v[220:223], v[2:5]
	s_setprio 0
	s_barrier
	s_add_i32 s13, 0, 0x18000
	v_add_u32_e32 v136, s13, v239
	s_add_i32 s15, 0, 0x1c000
	ds_read_b128 v[138:141], v136
	ds_read_b128 v[142:145], v136 offset:1024
	ds_read_b128 v[146:149], v136 offset:2048
	ds_read_b128 v[150:153], v136 offset:3072
	v_add_u32_e32 v136, s15, v239
	ds_read_b128 v[154:157], v136
	ds_read_b128 v[158:161], v136 offset:1024
	ds_read_b128 v[162:165], v136 offset:2048
	ds_read_b128 v[166:169], v136 offset:3072
	s_mov_b32 m0, s25
	v_lshl_add_u64 v[226:227], v[206:207], 0, s[84:85]
	ds_read_b128 v[170:173], v251 offset:32768
	ds_read_b128 v[174:177], v251 offset:33792
	ds_read_b128 v[178:181], v251 offset:34816
	ds_read_b128 v[182:185], v251 offset:35840
	ds_read_b128 v[186:189], v251 offset:36864
	ds_read_b128 v[190:193], v251 offset:37888
	ds_read_b128 v[216:219], v251 offset:38912
	ds_read_b128 v[220:223], v251 offset:39936
	global_load_lds_dwordx4 v[226:227], off
	v_lshl_add_u64 v[226:227], v[206:207], 0, s[86:87]
	s_mov_b32 m0, s26
	s_nop 0
	global_load_lds_dwordx4 v[226:227], off
	s_waitcnt vmcnt(8)
	s_waitcnt lgkmcnt(0)
	s_barrier
	s_setprio 1
	s_waitcnt lgkmcnt(0)
	v_mfma_f32_16x16x32_bf16 v[122:125], v[138:141], v[170:173], v[122:125]
	v_mfma_f32_16x16x32_bf16 v[126:129], v[146:149], v[170:173], v[126:129]
	v_mfma_f32_16x16x32_bf16 v[110:113], v[138:141], v[178:181], v[110:113]
	v_mfma_f32_16x16x32_bf16 v[106:109], v[146:149], v[178:181], v[106:109]
	v_mfma_f32_16x16x32_bf16 v[94:97], v[138:141], v[186:189], v[94:97]
	v_mfma_f32_16x16x32_bf16 v[90:93], v[146:149], v[186:189], v[90:93]
	v_mfma_f32_16x16x32_bf16 v[78:81], v[138:141], v[216:219], v[78:81]
	v_mfma_f32_16x16x32_bf16 v[74:77], v[146:149], v[216:219], v[74:77]
	v_mfma_f32_16x16x32_bf16 v[122:125], v[142:145], v[174:177], v[122:125]
	v_mfma_f32_16x16x32_bf16 v[126:129], v[150:153], v[174:177], v[126:129]
	v_mfma_f32_16x16x32_bf16 v[110:113], v[142:145], v[182:185], v[110:113]
	v_mfma_f32_16x16x32_bf16 v[106:109], v[150:153], v[182:185], v[106:109]
	v_mfma_f32_16x16x32_bf16 v[94:97], v[142:145], v[190:193], v[94:97]
	v_mfma_f32_16x16x32_bf16 v[90:93], v[150:153], v[190:193], v[90:93]
	v_mfma_f32_16x16x32_bf16 v[78:81], v[142:145], v[220:223], v[78:81]
	v_mfma_f32_16x16x32_bf16 v[74:77], v[150:153], v[220:223], v[74:77]
	s_setprio 0
	s_setprio 1
	v_mfma_f32_16x16x32_bf16 v[118:121], v[154:157], v[170:173], v[118:121]
	v_mfma_f32_16x16x32_bf16 v[114:117], v[162:165], v[170:173], v[114:117]
	v_mfma_f32_16x16x32_bf16 v[102:105], v[154:157], v[178:181], v[102:105]
	v_mfma_f32_16x16x32_bf16 v[98:101], v[162:165], v[178:181], v[98:101]
	v_mfma_f32_16x16x32_bf16 v[86:89], v[154:157], v[186:189], v[86:89]
	v_mfma_f32_16x16x32_bf16 v[82:85], v[162:165], v[186:189], v[82:85]
	v_mfma_f32_16x16x32_bf16 v[70:73], v[154:157], v[216:219], v[70:73]
	v_mfma_f32_16x16x32_bf16 v[66:69], v[162:165], v[216:219], v[66:69]
	v_mfma_f32_16x16x32_bf16 v[118:121], v[158:161], v[174:177], v[118:121]
	v_mfma_f32_16x16x32_bf16 v[114:117], v[166:169], v[174:177], v[114:117]
	v_mfma_f32_16x16x32_bf16 v[102:105], v[158:161], v[182:185], v[102:105]
	v_mfma_f32_16x16x32_bf16 v[98:101], v[166:169], v[182:185], v[98:101]
	v_mfma_f32_16x16x32_bf16 v[86:89], v[158:161], v[190:193], v[86:89]
	v_mfma_f32_16x16x32_bf16 v[82:85], v[166:169], v[190:193], v[82:85]
	v_mfma_f32_16x16x32_bf16 v[70:73], v[158:161], v[220:223], v[70:73]
	v_mfma_f32_16x16x32_bf16 v[66:69], v[166:169], v[220:223], v[66:69]
	s_setprio 0
	s_barrier
	s_add_i32 s13, s13, s22
	v_lshl_add_u64 v[226:227], v[224:225], 0, s[62:63]
	s_mov_b32 m0, s13
	ds_read_b128 v[170:173], v251 offset:49152
	ds_read_b128 v[174:177], v251 offset:50176
	ds_read_b128 v[178:181], v251 offset:51200
	ds_read_b128 v[182:185], v251 offset:52224
	ds_read_b128 v[186:189], v251 offset:53248
	ds_read_b128 v[190:193], v251 offset:54272
	ds_read_b128 v[216:219], v251 offset:55296
	ds_read_b128 v[220:223], v251 offset:56320
	global_load_lds_dwordx4 v[226:227], off
	v_lshl_add_u64 v[226:227], v[224:225], 0, s[64:65]
	s_add_i32 m0, s13, 0x2000
	s_add_i32 s13, s15, s22
	global_load_lds_dwordx4 v[226:227], off
	v_lshl_add_u64 v[226:227], v[224:225], 0, s[66:67]
	s_mov_b32 m0, s13
	v_lshl_add_u64 v[224:225], v[224:225], 0, s[68:69]
	global_load_lds_dwordx4 v[226:227], off
	s_add_i32 m0, s13, 0x2000
	s_nop 0
	global_load_lds_dwordx4 v[224:225], off
	v_lshl_add_u64 v[224:225], v[206:207], 0, s[62:63]
	s_mov_b32 m0, s27
	v_lshl_add_u64 v[206:207], v[206:207], 0, s[66:67]
	global_load_lds_dwordx4 v[224:225], off
	s_mov_b32 m0, s28
	s_nop 0
	global_load_lds_dwordx4 v[206:207], off
	s_waitcnt vmcnt(8)
	s_waitcnt lgkmcnt(0)
	s_barrier
	s_setprio 1
	s_waitcnt lgkmcnt(0)
	v_mfma_f32_16x16x32_bf16 v[62:65], v[138:141], v[170:173], v[62:65]
	v_mfma_f32_16x16x32_bf16 v[58:61], v[146:149], v[170:173], v[58:61]
	v_mfma_f32_16x16x32_bf16 v[46:49], v[138:141], v[178:181], v[46:49]
	v_mfma_f32_16x16x32_bf16 v[42:45], v[146:149], v[178:181], v[42:45]
	v_mfma_f32_16x16x32_bf16 v[30:33], v[138:141], v[186:189], v[30:33]
	v_mfma_f32_16x16x32_bf16 v[26:29], v[146:149], v[186:189], v[26:29]
	v_mfma_f32_16x16x32_bf16 v[14:17], v[138:141], v[216:219], v[14:17]
	v_mfma_f32_16x16x32_bf16 v[10:13], v[146:149], v[216:219], v[10:13]
	v_mfma_f32_16x16x32_bf16 v[62:65], v[142:145], v[174:177], v[62:65]
	v_mfma_f32_16x16x32_bf16 v[58:61], v[150:153], v[174:177], v[58:61]
	v_mfma_f32_16x16x32_bf16 v[46:49], v[142:145], v[182:185], v[46:49]
	v_mfma_f32_16x16x32_bf16 v[42:45], v[150:153], v[182:185], v[42:45]
	v_mfma_f32_16x16x32_bf16 v[30:33], v[142:145], v[190:193], v[30:33]
	v_mfma_f32_16x16x32_bf16 v[26:29], v[150:153], v[190:193], v[26:29]
	v_mfma_f32_16x16x32_bf16 v[14:17], v[142:145], v[220:223], v[14:17]
	v_mfma_f32_16x16x32_bf16 v[10:13], v[150:153], v[220:223], v[10:13]
	s_setprio 0
	s_setprio 1
	v_mfma_f32_16x16x32_bf16 v[54:57], v[154:157], v[170:173], v[54:57]
	v_mfma_f32_16x16x32_bf16 v[50:53], v[162:165], v[170:173], v[50:53]
	v_mfma_f32_16x16x32_bf16 v[38:41], v[154:157], v[178:181], v[38:41]
	v_mfma_f32_16x16x32_bf16 v[34:37], v[162:165], v[178:181], v[34:37]
	v_mfma_f32_16x16x32_bf16 v[22:25], v[154:157], v[186:189], v[22:25]
	v_mfma_f32_16x16x32_bf16 v[18:21], v[162:165], v[186:189], v[18:21]
	v_mfma_f32_16x16x32_bf16 v[6:9], v[154:157], v[216:219], v[6:9]
	v_mfma_f32_16x16x32_bf16 v[2:5], v[162:165], v[216:219], v[2:5]
	v_mfma_f32_16x16x32_bf16 v[54:57], v[158:161], v[174:177], v[54:57]
	v_mfma_f32_16x16x32_bf16 v[50:53], v[166:169], v[174:177], v[50:53]
	v_mfma_f32_16x16x32_bf16 v[38:41], v[158:161], v[182:185], v[38:41]
	v_mfma_f32_16x16x32_bf16 v[34:37], v[166:169], v[182:185], v[34:37]
	v_mfma_f32_16x16x32_bf16 v[22:25], v[158:161], v[190:193], v[22:25]
	v_mfma_f32_16x16x32_bf16 v[18:21], v[166:169], v[190:193], v[18:21]
	v_mfma_f32_16x16x32_bf16 v[6:9], v[158:161], v[220:223], v[6:9]
	v_mfma_f32_16x16x32_bf16 v[2:5], v[166:169], v[220:223], v[2:5]
	s_setprio 0
	s_barrier
	s_add_i32 s11, s11, 2
	v_lshl_add_u64 v[134:135], v[134:135], 0, s[72:73]
	s_cmp_gt_u32 s11, 29
	v_lshl_add_u64 v[130:131], v[130:131], 0, s[72:73]

.LBB0_439:
	s_or_b64 exec, exec, s[16:17]
	s_andn2_b64 vcc, exec, s[8:9]
	s_mov_b64 s[8:9], -1
	s_cbranch_vccnz .LBB0_416
	s_andn2_b64 vcc, exec, s[0:1]
	s_cbranch_vccnz .LBB0_415
	s_barrier
	s_branch .LBB0_415

.LBB0_496:
	v_readlane_b32 s6, v254, 5
	v_readlane_b32 s7, v254, 6
	s_load_dword s19, s[6:7], 0x0
	s_andn2_b64 vcc, exec, s[0:1]
	s_cbranch_vccnz .LBB0_546
	v_ashrrev_i32_e32 v2, 31, v0
	v_lshrrev_b32_e32 v2, 26, v2
	v_add_u32_e32 v2, v0, v2
	v_ashrrev_i32_e32 v144, 6, v2
	v_bfe_i32 v2, v0, 27, 1
	v_lshlrev_b32_e32 v145, 4, v0
	v_lshrrev_b32_e32 v2, 22, v2
	v_add_u32_e32 v2, v145, v2
	v_and_b32_e32 v2, 0xfffffc00, v2
	v_sub_u32_e32 v2, v145, v2
	v_lshrrev_b32_e32 v3, 4, v2
	v_bitop3_b32 v2, v3, v2, 32 bitop3:0x6c
	v_ashrrev_i32_e32 v4, 31, v2
	v_lshrrev_b32_e32 v4, 26, v4
	v_add_u32_e32 v4, v2, v4
	v_lshlrev_b32_e32 v3, 3, v144
	v_ashrrev_i32_e32 v146, 6, v4
	v_and_b32_e32 v4, 0xc0, v4
	v_and_b32_e32 v3, -16, v3
	v_sub_u32_e32 v2, v2, v4
	s_mov_b64 s[0:1], 0x8200000
	v_add_u32_e32 v3, v146, v3
	v_ashrrev_i16_sdwa v2, v241, sext(v2) dst_sel:DWORD dst_unused:UNUSED_PAD src0_sel:DWORD src1_sel:BYTE_0
	s_waitcnt vmcnt(0) lgkmcnt(0)
	v_lshl_add_u64 v[130:131], v[142:143], 0, s[0:1]
	v_lshlrev_b32_e32 v5, 5, v144
	v_bfe_i32 v147, v2, 0, 16
	v_lshlrev_b32_e32 v2, 1, v3
	v_lshrrev_b32_e32 v4, 2, v3
	v_and_b32_e32 v6, 3, v146
	s_mov_b32 s0, 0xfffe0
	s_ashr_i32 s5, s4, 6
	v_and_b32_e32 v5, 32, v5
	v_and_b32_e32 v2, 24, v2
	v_and_b32_e32 v4, 4, v4
	v_and_or_b32 v6, v3, s0, v6
	s_ashr_i32 s3, s2, 31
	v_lshl_add_u64 v[132:133], v[142:143], 0, s[50:51]
	v_or3_b32 v2, v6, v4, v2
	v_add_lshl_u32 v4, v5, v147, 1
	s_lshl_b32 s20, s5, 10
	s_lshl_b64 s[6:7], s[2:3], 20
	v_lshl_add_u32 v136, v2, 12, v4
	v_lshl_add_u64 v[150:151], v[132:133], 0, s[6:7]
	v_mov_b32_e32 v137, v1
	s_add_i32 s21, s20, 0
	v_lshl_add_u64 v[138:139], v[150:151], 0, v[136:137]
	s_add_i32 m0, s21, 0x10000
	v_lshl_add_u32 v134, v3, 12, v4
	s_ashr_i32 s9, s8, 31
	global_load_lds_dwordx4 v[138:139], off
	v_lshl_add_u64 v[140:141], v[138:139], 0, s[52:53]
	s_add_i32 m0, s21, 0x12000
	s_lshl_b64 s[0:1], s[8:9], 20
	global_load_lds_dwordx4 v[140:141], off
	v_lshl_add_u64 v[140:141], v[138:139], 0, s[54:55]
	s_add_i32 m0, s21, 0x14000
	v_lshl_add_u64 v[152:153], v[130:131], 0, s[0:1]
	global_load_lds_dwordx4 v[140:141], off
	v_lshl_add_u64 v[140:141], v[138:139], 0, s[56:57]
	s_add_i32 m0, s21, 0x16000
	v_mov_b32_e32 v135, v1
	global_load_lds_dwordx4 v[140:141], off
	v_lshl_add_u64 v[140:141], v[152:153], 0, v[134:135]
	s_mov_b32 m0, s21
	s_add_i32 s22, s21, 0x2000
	global_load_lds_dwordx4 v[140:141], off
	v_lshl_add_u64 v[148:149], v[140:141], 0, s[52:53]
	s_mov_b32 m0, s22
	s_add_i32 s23, s21, 0x4000
	global_load_lds_dwordx4 v[148:149], off
	v_lshl_add_u64 v[148:149], v[140:141], 0, s[54:55]
	s_mov_b32 m0, s23
	s_add_i32 s24, s21, 0x6000
	global_load_lds_dwordx4 v[148:149], off
	v_lshl_add_u64 v[148:149], v[140:141], 0, s[56:57]
	s_mov_b32 m0, s24
	s_ashr_i32 s3, s4, 8
	global_load_lds_dwordx4 v[148:149], off
	s_cmp_eq_u32 s3, 1
	s_cselect_b64 s[0:1], -1, 0
	s_cmp_lg_u32 s3, 1
	s_cbranch_scc1 .LBB0_499
	s_barrier

.LBB0_504:
	s_lshl_b32 s3, s8, 8
	v_add_u32_e32 v158, s3, v163
	s_ashr_i32 s15, s14, 31
	v_ashrrev_i32_e32 v159, 31, v158
	s_lshl_b64 s[16:17], s[14:15], 20
	s_ashr_i32 s13, s12, 31
	v_lshlrev_b64 v[160:161], 6, v[158:159]
	v_add_u32_e32 v158, s3, v164
	v_lshl_add_u64 v[146:147], v[130:131], 0, s[16:17]
	s_lshl_b64 s[16:17], s[12:13], 20
	v_ashrrev_i32_e32 v159, 31, v158
	v_lshl_add_u64 v[148:149], v[132:133], 0, s[16:17]
	v_lshlrev_b64 v[158:159], 6, v[158:159]
	v_cndmask_b32_e64 v155, v153, v147, s[6:7]
	v_cndmask_b32_e64 v0, v152, v146, s[6:7]
	v_cndmask_b32_e64 v157, v151, v149, s[6:7]
	v_cndmask_b32_e64 v154, v150, v148, s[6:7]
	v_lshl_add_u64 v[158:159], v[142:143], 0, v[158:159]
	v_lshl_add_u64 v[160:161], v[142:143], 0, v[160:161]
	v_lshl_add_u64 v[152:153], v[152:153], 0, s[66:67]
	v_lshl_add_u64 v[150:151], v[150:151], 0, s[72:73]
	s_mov_b32 s8, -2
	s_mov_b64 vcc, 0
	s_add_i32 s9, 0, 0x10000
	s_add_i32 s13, 0, 0x14000
	v_lshl_add_u64 v[168:169], v[152:153], 0, s[74:75]
	v_add_u32_e32 v180, s9, v162
	v_add_u32_e32 v196, s13, v162
	v_cndmask_b32_e32 v205, v169, v155, vcc
	v_cndmask_b32_e32 v204, v168, v0, vcc
	ds_read_b128 v[168:171], v180
	ds_read_b128 v[172:175], v180 offset:1024
	ds_read_b128 v[176:179], v180 offset:2048
	ds_read_b128 v[180:183], v180 offset:3072
	ds_read_b128 v[184:187], v196
	ds_read_b128 v[188:191], v196 offset:1024
	ds_read_b128 v[192:195], v196 offset:2048
	ds_read_b128 v[196:199], v196 offset:3072
	v_cndmask_b32_e32 v239, v151, v157, vcc
	v_cndmask_b32_e32 v238, v150, v154, vcc
	v_lshl_add_u64 v[250:251], v[152:153], 0, v[144:145]
	s_add_i32 m0, s21, 0xc000
	ds_read_b128 v[200:203], v166
	ds_read_b128 v[210:213], v166 offset:1024
	ds_read_b128 v[214:217], v166 offset:2048
	ds_read_b128 v[218:221], v166 offset:3072
	ds_read_b128 v[222:225], v166 offset:4096
	ds_read_b128 v[226:229], v166 offset:5120
	ds_read_b128 v[230:233], v166 offset:6144
	ds_read_b128 v[234:237], v166 offset:7168
	global_load_lds_dwordx4 v[250:251], off
	v_lshl_add_u64 v[250:251], v[250:251], 0, s[52:53]
	s_add_i32 m0, s21, 0xe000
	s_nop 0
	global_load_lds_dwordx4 v[250:251], off
	s_waitcnt vmcnt(8)
	s_waitcnt lgkmcnt(0)
	s_barrier
	s_setprio 1
	s_waitcnt lgkmcnt(0)
	v_mfma_f32_16x16x32_bf16 v[126:129], v[168:171], v[200:203], 0
	v_mfma_f32_16x16x32_bf16 v[122:125], v[176:179], v[200:203], 0
	v_mfma_f32_16x16x32_bf16 v[110:113], v[168:171], v[214:217], 0
	v_mfma_f32_16x16x32_bf16 v[106:109], v[176:179], v[214:217], 0
	v_mfma_f32_16x16x32_bf16 v[94:97], v[168:171], v[222:225], 0
	v_mfma_f32_16x16x32_bf16 v[90:93], v[176:179], v[222:225], 0
	v_mfma_f32_16x16x32_bf16 v[78:81], v[168:171], v[230:233], 0
	v_mfma_f32_16x16x32_bf16 v[74:77], v[176:179], v[230:233], 0
	v_mfma_f32_16x16x32_bf16 v[126:129], v[172:175], v[210:213], v[126:129]
	v_mfma_f32_16x16x32_bf16 v[122:125], v[180:183], v[210:213], v[122:125]
	v_mfma_f32_16x16x32_bf16 v[110:113], v[172:175], v[218:221], v[110:113]
	v_mfma_f32_16x16x32_bf16 v[106:109], v[180:183], v[218:221], v[106:109]
	v_mfma_f32_16x16x32_bf16 v[94:97], v[172:175], v[226:229], v[94:97]
	v_mfma_f32_16x16x32_bf16 v[90:93], v[180:183], v[226:229], v[90:93]
	v_mfma_f32_16x16x32_bf16 v[78:81], v[172:175], v[234:237], v[78:81]
	v_mfma_f32_16x16x32_bf16 v[74:77], v[180:183], v[234:237], v[74:77]
	s_setprio 0
	s_setprio 1
	v_mfma_f32_16x16x32_bf16 v[118:121], v[184:187], v[200:203], 0
	v_mfma_f32_16x16x32_bf16 v[114:117], v[192:195], v[200:203], 0
	v_mfma_f32_16x16x32_bf16 v[102:105], v[184:187], v[214:217], 0
	v_mfma_f32_16x16x32_bf16 v[98:101], v[192:195], v[214:217], 0
	v_mfma_f32_16x16x32_bf16 v[86:89], v[184:187], v[222:225], 0
	v_mfma_f32_16x16x32_bf16 v[82:85], v[192:195], v[222:225], 0
	v_mfma_f32_16x16x32_bf16 v[70:73], v[184:187], v[230:233], 0
	v_mfma_f32_16x16x32_bf16 v[66:69], v[192:195], v[230:233], 0
	v_mfma_f32_16x16x32_bf16 v[118:121], v[188:191], v[210:213], v[118:121]
	v_mfma_f32_16x16x32_bf16 v[114:117], v[196:199], v[210:213], v[114:117]
	v_mfma_f32_16x16x32_bf16 v[102:105], v[188:191], v[218:221], v[102:105]
	v_mfma_f32_16x16x32_bf16 v[98:101], v[196:199], v[218:221], v[98:101]
	v_mfma_f32_16x16x32_bf16 v[86:89], v[188:191], v[226:229], v[86:89]
	v_mfma_f32_16x16x32_bf16 v[82:85], v[196:199], v[226:229], v[82:85]
	v_mfma_f32_16x16x32_bf16 v[70:73], v[188:191], v[234:237], v[70:73]
	v_mfma_f32_16x16x32_bf16 v[66:69], v[196:199], v[234:237], v[66:69]
	s_setprio 0
	s_barrier
	s_add_i32 s9, s9, s20
	v_lshl_add_u64 v[238:239], v[238:239], 0, v[136:137]
	s_mov_b32 m0, s9
	ds_read_b128 v[200:203], v166 offset:16384
	ds_read_b128 v[210:213], v166 offset:17408
	ds_read_b128 v[214:217], v166 offset:18432
	ds_read_b128 v[218:221], v166 offset:19456
	ds_read_b128 v[222:225], v166 offset:20480
	ds_read_b128 v[226:229], v166 offset:21504
	ds_read_b128 v[230:233], v166 offset:22528
	ds_read_b128 v[234:237], v166 offset:23552
	global_load_lds_dwordx4 v[238:239], off
	v_lshl_add_u64 v[250:251], v[238:239], 0, s[52:53]
	s_add_i32 m0, s9, 0x2000
	s_add_i32 s9, s13, s20
	global_load_lds_dwordx4 v[250:251], off
	v_lshl_add_u64 v[250:251], v[238:239], 0, s[54:55]
	s_mov_b32 m0, s9
	v_lshl_add_u64 v[204:205], v[204:205], 0, v[134:135]
	global_load_lds_dwordx4 v[250:251], off
	v_lshl_add_u64 v[250:251], v[238:239], 0, s[56:57]
	s_add_i32 m0, s9, 0x2000
	s_nop 0
	global_load_lds_dwordx4 v[250:251], off
	s_mov_b32 m0, s21
	v_lshl_add_u64 v[250:251], v[204:205], 0, s[52:53]
	global_load_lds_dwordx4 v[204:205], off
	s_mov_b32 m0, s22
	s_nop 0
	global_load_lds_dwordx4 v[250:251], off
	s_waitcnt vmcnt(8)
	s_waitcnt lgkmcnt(0)
	s_barrier
	s_setprio 1
	s_waitcnt lgkmcnt(0)
	v_mfma_f32_16x16x32_bf16 v[62:65], v[168:171], v[200:203], 0
	v_mfma_f32_16x16x32_bf16 v[58:61], v[176:179], v[200:203], 0
	v_mfma_f32_16x16x32_bf16 v[46:49], v[168:171], v[214:217], 0
	v_mfma_f32_16x16x32_bf16 v[42:45], v[176:179], v[214:217], 0
	v_mfma_f32_16x16x32_bf16 v[30:33], v[168:171], v[222:225], 0
	v_mfma_f32_16x16x32_bf16 v[26:29], v[176:179], v[222:225], 0
	v_mfma_f32_16x16x32_bf16 v[10:13], v[168:171], v[230:233], 0
	v_mfma_f32_16x16x32_bf16 v[6:9], v[176:179], v[230:233], 0
	v_mfma_f32_16x16x32_bf16 v[62:65], v[172:175], v[210:213], v[62:65]
	v_mfma_f32_16x16x32_bf16 v[58:61], v[180:183], v[210:213], v[58:61]
	v_mfma_f32_16x16x32_bf16 v[46:49], v[172:175], v[218:221], v[46:49]
	v_mfma_f32_16x16x32_bf16 v[42:45], v[180:183], v[218:221], v[42:45]
	v_mfma_f32_16x16x32_bf16 v[30:33], v[172:175], v[226:229], v[30:33]
	v_mfma_f32_16x16x32_bf16 v[26:29], v[180:183], v[226:229], v[26:29]
	v_mfma_f32_16x16x32_bf16 v[10:13], v[172:175], v[234:237], v[10:13]
	v_mfma_f32_16x16x32_bf16 v[6:9], v[180:183], v[234:237], v[6:9]
	s_setprio 0
	s_setprio 1
	v_mfma_f32_16x16x32_bf16 v[54:57], v[184:187], v[200:203], 0
	v_mfma_f32_16x16x32_bf16 v[50:53], v[192:195], v[200:203], 0
	v_mfma_f32_16x16x32_bf16 v[38:41], v[184:187], v[214:217], 0
	v_mfma_f32_16x16x32_bf16 v[34:37], v[192:195], v[214:217], 0
	v_mfma_f32_16x16x32_bf16 v[22:25], v[184:187], v[222:225], 0
	v_mfma_f32_16x16x32_bf16 v[18:21], v[192:195], v[222:225], 0
	v_mfma_f32_16x16x32_bf16 v[2:5], v[184:187], v[230:233], 0
	v_mfma_f32_16x16x32_bf16 v[14:17], v[192:195], v[230:233], 0
	v_mfma_f32_16x16x32_bf16 v[54:57], v[188:191], v[210:213], v[54:57]
	v_mfma_f32_16x16x32_bf16 v[50:53], v[196:199], v[210:213], v[50:53]
	v_mfma_f32_16x16x32_bf16 v[38:41], v[188:191], v[218:221], v[38:41]
	v_mfma_f32_16x16x32_bf16 v[34:37], v[196:199], v[218:221], v[34:37]
	v_mfma_f32_16x16x32_bf16 v[22:25], v[188:191], v[226:229], v[22:25]
	v_mfma_f32_16x16x32_bf16 v[18:21], v[196:199], v[226:229], v[18:21]
	v_mfma_f32_16x16x32_bf16 v[2:5], v[188:191], v[234:237], v[2:5]
	v_mfma_f32_16x16x32_bf16 v[14:17], v[196:199], v[234:237], v[14:17]
	s_setprio 0
	s_barrier
	s_add_i32 s9, 0, 0x18000
	s_add_i32 s13, 0, 0x1c000
	v_add_u32_e32 v180, s9, v162
	v_add_u32_e32 v196, s13, v162
	ds_read_b128 v[168:171], v180
	ds_read_b128 v[172:175], v180 offset:1024
	ds_read_b128 v[176:179], v180 offset:2048
	ds_read_b128 v[180:183], v180 offset:3072
	ds_read_b128 v[184:187], v196
	ds_read_b128 v[188:191], v196 offset:1024
	ds_read_b128 v[192:195], v196 offset:2048
	ds_read_b128 v[196:199], v196 offset:3072
	s_mov_b32 m0, s23
	v_lshl_add_u64 v[250:251], v[204:205], 0, s[54:55]
	ds_read_b128 v[200:203], v166 offset:32768
	ds_read_b128 v[210:213], v166 offset:33792
	ds_read_b128 v[214:217], v166 offset:34816
	ds_read_b128 v[218:221], v166 offset:35840
	ds_read_b128 v[222:225], v166 offset:36864
	ds_read_b128 v[226:229], v166 offset:37888
	ds_read_b128 v[230:233], v166 offset:38912
	ds_read_b128 v[234:237], v166 offset:39936
	global_load_lds_dwordx4 v[250:251], off
	v_lshl_add_u64 v[250:251], v[204:205], 0, s[56:57]
	s_mov_b32 m0, s24
	s_nop 0
	global_load_lds_dwordx4 v[250:251], off
	s_waitcnt vmcnt(8)
	s_waitcnt lgkmcnt(0)
	s_barrier
	s_setprio 1
	s_waitcnt lgkmcnt(0)
	v_mfma_f32_16x16x32_bf16 v[126:129], v[168:171], v[200:203], v[126:129]
	v_mfma_f32_16x16x32_bf16 v[122:125], v[176:179], v[200:203], v[122:125]
	v_mfma_f32_16x16x32_bf16 v[110:113], v[168:171], v[214:217], v[110:113]
	v_mfma_f32_16x16x32_bf16 v[106:109], v[176:179], v[214:217], v[106:109]
	v_mfma_f32_16x16x32_bf16 v[94:97], v[168:171], v[222:225], v[94:97]
	v_mfma_f32_16x16x32_bf16 v[90:93], v[176:179], v[222:225], v[90:93]
	v_mfma_f32_16x16x32_bf16 v[78:81], v[168:171], v[230:233], v[78:81]
	v_mfma_f32_16x16x32_bf16 v[74:77], v[176:179], v[230:233], v[74:77]
	v_mfma_f32_16x16x32_bf16 v[126:129], v[172:175], v[210:213], v[126:129]
	v_mfma_f32_16x16x32_bf16 v[122:125], v[180:183], v[210:213], v[122:125]
	v_mfma_f32_16x16x32_bf16 v[110:113], v[172:175], v[218:221], v[110:113]
	v_mfma_f32_16x16x32_bf16 v[106:109], v[180:183], v[218:221], v[106:109]
	v_mfma_f32_16x16x32_bf16 v[94:97], v[172:175], v[226:229], v[94:97]
	v_mfma_f32_16x16x32_bf16 v[90:93], v[180:183], v[226:229], v[90:93]
	v_mfma_f32_16x16x32_bf16 v[78:81], v[172:175], v[234:237], v[78:81]
	v_mfma_f32_16x16x32_bf16 v[74:77], v[180:183], v[234:237], v[74:77]
	s_setprio 0
	s_setprio 1
	v_mfma_f32_16x16x32_bf16 v[118:121], v[184:187], v[200:203], v[118:121]
	v_mfma_f32_16x16x32_bf16 v[114:117], v[192:195], v[200:203], v[114:117]
	v_mfma_f32_16x16x32_bf16 v[102:105], v[184:187], v[214:217], v[102:105]
	v_mfma_f32_16x16x32_bf16 v[98:101], v[192:195], v[214:217], v[98:101]
	v_mfma_f32_16x16x32_bf16 v[86:89], v[184:187], v[222:225], v[86:89]
	v_mfma_f32_16x16x32_bf16 v[82:85], v[192:195], v[222:225], v[82:85]
	v_mfma_f32_16x16x32_bf16 v[70:73], v[184:187], v[230:233], v[70:73]
	v_mfma_f32_16x16x32_bf16 v[66:69], v[192:195], v[230:233], v[66:69]
	v_mfma_f32_16x16x32_bf16 v[118:121], v[188:191], v[210:213], v[118:121]
	v_mfma_f32_16x16x32_bf16 v[114:117], v[196:199], v[210:213], v[114:117]
	v_mfma_f32_16x16x32_bf16 v[102:105], v[188:191], v[218:221], v[102:105]
	v_mfma_f32_16x16x32_bf16 v[98:101], v[196:199], v[218:221], v[98:101]
	v_mfma_f32_16x16x32_bf16 v[86:89], v[188:191], v[226:229], v[86:89]
	v_mfma_f32_16x16x32_bf16 v[82:85], v[196:199], v[226:229], v[82:85]
	v_mfma_f32_16x16x32_bf16 v[70:73], v[188:191], v[234:237], v[70:73]
	v_mfma_f32_16x16x32_bf16 v[66:69], v[196:199], v[234:237], v[66:69]
	s_setprio 0
	s_barrier
	s_add_i32 s9, s9, s20
	v_lshl_add_u64 v[250:251], v[238:239], 0, s[62:63]
	s_mov_b32 m0, s9
	ds_read_b128 v[200:203], v166 offset:49152
	ds_read_b128 v[210:213], v166 offset:50176
	ds_read_b128 v[214:217], v166 offset:51200
	ds_read_b128 v[218:221], v166 offset:52224
	ds_read_b128 v[222:225], v166 offset:53248
	ds_read_b128 v[226:229], v166 offset:54272
	ds_read_b128 v[230:233], v166 offset:55296
	ds_read_b128 v[234:237], v166 offset:56320
	global_load_lds_dwordx4 v[250:251], off
	v_lshl_add_u64 v[250:251], v[238:239], 0, s[64:65]
	s_add_i32 m0, s9, 0x2000
	s_add_i32 s9, s13, s20
	global_load_lds_dwordx4 v[250:251], off
	v_lshl_add_u64 v[250:251], v[238:239], 0, s[66:67]
	s_mov_b32 m0, s9
	v_lshl_add_u64 v[238:239], v[238:239], 0, s[68:69]
	global_load_lds_dwordx4 v[250:251], off
	s_add_i32 m0, s9, 0x2000
	s_nop 0
	global_load_lds_dwordx4 v[238:239], off
	v_lshl_add_u64 v[238:239], v[204:205], 0, s[62:63]
	s_mov_b32 m0, s25
	v_lshl_add_u64 v[204:205], v[204:205], 0, s[64:65]
	global_load_lds_dwordx4 v[238:239], off
	s_mov_b32 m0, s26
	s_nop 0
	global_load_lds_dwordx4 v[204:205], off
	s_waitcnt vmcnt(8)
	s_waitcnt lgkmcnt(0)
	s_barrier
	s_setprio 1
	s_waitcnt lgkmcnt(0)
	v_mfma_f32_16x16x32_bf16 v[62:65], v[168:171], v[200:203], v[62:65]
	v_mfma_f32_16x16x32_bf16 v[58:61], v[176:179], v[200:203], v[58:61]
	v_mfma_f32_16x16x32_bf16 v[46:49], v[168:171], v[214:217], v[46:49]
	v_mfma_f32_16x16x32_bf16 v[42:45], v[176:179], v[214:217], v[42:45]
	v_mfma_f32_16x16x32_bf16 v[30:33], v[168:171], v[222:225], v[30:33]
	v_mfma_f32_16x16x32_bf16 v[26:29], v[176:179], v[222:225], v[26:29]
	v_mfma_f32_16x16x32_bf16 v[10:13], v[168:171], v[230:233], v[10:13]
	v_mfma_f32_16x16x32_bf16 v[6:9], v[176:179], v[230:233], v[6:9]
	v_mfma_f32_16x16x32_bf16 v[62:65], v[172:175], v[210:213], v[62:65]
	v_mfma_f32_16x16x32_bf16 v[58:61], v[180:183], v[210:213], v[58:61]
	v_mfma_f32_16x16x32_bf16 v[46:49], v[172:175], v[218:221], v[46:49]
	v_mfma_f32_16x16x32_bf16 v[42:45], v[180:183], v[218:221], v[42:45]
	v_mfma_f32_16x16x32_bf16 v[30:33], v[172:175], v[226:229], v[30:33]
	v_mfma_f32_16x16x32_bf16 v[26:29], v[180:183], v[226:229], v[26:29]
	v_mfma_f32_16x16x32_bf16 v[10:13], v[172:175], v[234:237], v[10:13]
	v_mfma_f32_16x16x32_bf16 v[6:9], v[180:183], v[234:237], v[6:9]
	s_setprio 0
	s_setprio 1
	v_mfma_f32_16x16x32_bf16 v[54:57], v[184:187], v[200:203], v[54:57]
	v_mfma_f32_16x16x32_bf16 v[50:53], v[192:195], v[200:203], v[50:53]
	v_mfma_f32_16x16x32_bf16 v[38:41], v[184:187], v[214:217], v[38:41]
	v_mfma_f32_16x16x32_bf16 v[34:37], v[192:195], v[214:217], v[34:37]
	v_mfma_f32_16x16x32_bf16 v[22:25], v[184:187], v[222:225], v[22:25]
	v_mfma_f32_16x16x32_bf16 v[18:21], v[192:195], v[222:225], v[18:21]
	v_mfma_f32_16x16x32_bf16 v[2:5], v[184:187], v[230:233], v[2:5]
	v_mfma_f32_16x16x32_bf16 v[14:17], v[192:195], v[230:233], v[14:17]
	v_mfma_f32_16x16x32_bf16 v[54:57], v[188:191], v[210:213], v[54:57]
	v_mfma_f32_16x16x32_bf16 v[50:53], v[196:199], v[210:213], v[50:53]
	v_mfma_f32_16x16x32_bf16 v[38:41], v[188:191], v[218:221], v[38:41]
	v_mfma_f32_16x16x32_bf16 v[34:37], v[196:199], v[218:221], v[34:37]
	v_mfma_f32_16x16x32_bf16 v[22:25], v[188:191], v[226:229], v[22:25]
	v_mfma_f32_16x16x32_bf16 v[18:21], v[196:199], v[226:229], v[18:21]
	v_mfma_f32_16x16x32_bf16 v[2:5], v[188:191], v[234:237], v[2:5]
	v_mfma_f32_16x16x32_bf16 v[14:17], v[196:199], v[234:237], v[14:17]
	s_setprio 0
	s_barrier
	s_add_i32 s8, s8, 2
	v_lshl_add_u64 v[152:153], v[152:153], 0, s[72:73]
	s_cmp_gt_u32 s8, 29
	v_lshl_add_u64 v[150:151], v[150:151], 0, s[72:73]
	s_branch .LBB0_506

.LBB0_542:
	s_andn2_b64 vcc, exec, s[6:7]
	s_mov_b64 s[2:3], -1
	s_cbranch_vccnz .LBB0_501
	s_andn2_b64 vcc, exec, s[0:1]
	s_cbranch_vccnz .LBB0_500
	s_barrier
	s_branch .LBB0_500

.LBB0_1072:
	s_waitcnt lgkmcnt(0)
	v_readlane_b32 s4, v254, 5
	v_readlane_b32 s5, v254, 6
	s_load_dword s15, s[4:5], 0x0
	s_andn2_b64 vcc, exec, s[0:1]
	s_cbranch_vccnz .LBB0_1106
	v_ashrrev_i32_e32 v3, 31, v0
	v_lshrrev_b32_e32 v3, 26, v3
	v_add_u32_e32 v3, v0, v3
	v_ashrrev_i32_e32 v140, 6, v3
	v_bfe_i32 v3, v0, 27, 1
	v_lshlrev_b32_e32 v2, 4, v0
	v_lshrrev_b32_e32 v3, 22, v3
	v_add_u32_e32 v3, v2, v3
	v_and_b32_e32 v3, 0xfffffc00, v3
	v_sub_u32_e32 v2, v2, v3
	v_lshrrev_b32_e32 v3, 4, v2
	v_bitop3_b32 v2, v3, v2, 32 bitop3:0x6c
	v_ashrrev_i32_e32 v4, 31, v2
	v_lshrrev_b32_e32 v4, 26, v4
	v_add_u32_e32 v4, v2, v4
	s_mov_b64 s[0:1], 0x12200000
	v_lshlrev_b32_e32 v3, 3, v140
	v_ashrrev_i32_e32 v142, 6, v4
	v_and_b32_e32 v4, 0xc0, v4
	s_waitcnt vmcnt(0)
	v_lshl_add_u64 v[194:195], v[134:135], 0, s[0:1]
	s_mov_b64 s[0:1], 0x1a00000
	v_and_b32_e32 v3, -16, v3
	v_sub_u32_e32 v2, v2, v4
	v_lshl_add_u64 v[196:197], v[134:135], 0, s[0:1]
	v_add_u32_e32 v3, v142, v3
	v_lshlrev_b32_e32 v5, 5, v140
	v_ashrrev_i16_sdwa v2, v241, sext(v2) dst_sel:DWORD dst_unused:UNUSED_PAD src0_sel:DWORD src1_sel:BYTE_0
	v_and_b32_e32 v6, 3, v142
	s_mov_b32 s0, 0xfffe0
	v_and_b32_e32 v141, 32, v5
	v_bfe_i32 v143, v2, 0, 16
	v_lshlrev_b32_e32 v4, 1, v3
	v_lshrrev_b32_e32 v5, 2, v3
	v_and_or_b32 v6, v3, s0, v6
	s_movk_i32 s0, 0xc00
	s_ashr_i32 s3, s2, 6
	v_add_u32_e32 v2, v141, v143
	v_and_b32_e32 v4, 24, v4
	v_and_b32_e32 v5, 4, v5
	v_mul_lo_u32 v3, v3, s0
	s_ashr_i32 s13, s12, 31
	v_or3_b32 v4, v6, v5, v4
	v_add_lshl_u32 v198, v2, v3, 1
	v_lshlrev_b32_e32 v2, 1, v2
	s_lshl_b32 s16, s3, 10
	s_lshl_b64 s[0:1], s[12:13], 20
	v_lshl_add_u32 v200, v4, 12, v2
	v_lshl_add_u64 v[130:131], v[196:197], 0, s[0:1]
	v_mov_b32_e32 v201, v1
	s_add_i32 s17, s16, 0
	v_lshl_add_u64 v[136:137], v[130:131], 0, v[200:201]
	s_add_i32 m0, s17, 0x10000
	s_nop 0
	global_load_lds_dwordx4 v[136:137], off
	v_lshl_add_u64 v[132:133], v[136:137], 0, s[52:53]
	s_add_i32 m0, s17, 0x12000
	v_mov_b32_e32 v199, v1
	global_load_lds_dwordx4 v[132:133], off
	v_lshl_add_u64 v[132:133], v[136:137], 0, s[54:55]
	s_add_i32 m0, s17, 0x14000
	s_add_i32 s18, s17, 0x2000
	global_load_lds_dwordx4 v[132:133], off
	v_lshl_add_u64 v[132:133], v[136:137], 0, s[56:57]
	s_add_i32 m0, s17, 0x16000
	s_add_i32 s19, s17, 0x4000
	global_load_lds_dwordx4 v[132:133], off
	v_mov_b32_e32 v132, 0x180000
	v_mad_i64_i32 v[132:133], s[0:1], s28, v132, v[194:195]
	v_lshl_add_u64 v[138:139], v[132:133], 0, v[198:199]
	s_mov_b32 m0, s17
	v_lshl_add_u64 v[144:145], v[138:139], 0, s[90:91]
	global_load_lds_dwordx4 v[138:139], off
	s_mov_b32 m0, s18
	s_add_i32 s20, s17, 0x6000
	global_load_lds_dwordx4 v[144:145], off
	v_lshl_add_u64 v[144:145], v[138:139], 0, s[56:57]
	s_mov_b32 m0, s19
	s_ashr_i32 s4, s2, 8
	global_load_lds_dwordx4 v[144:145], off
	v_lshl_add_u64 v[144:145], v[138:139], 0, s[78:79]
	s_mov_b32 m0, s20
	s_cmp_eq_u32 s4, 1
	global_load_lds_dwordx4 v[144:145], off
	s_cselect_b64 s[0:1], -1, 0
	s_cmp_lg_u32 s4, 1
	s_cbranch_scc1 .LBB0_1075
	s_barrier

.LBB0_1082:
	s_ashr_i32 s11, s10, 31
	s_lshl_b64 s[30:31], s[10:11], 20
	v_lshl_add_u64 v[214:215], v[196:197], 0, s[30:31]
	v_cndmask_b32_e64 v135, v131, v215, s[8:9]
	v_cndmask_b32_e64 v0, v130, v214, s[8:9]
	v_lshl_add_u64 v[132:133], v[132:133], 0, s[68:69]
	v_lshl_add_u64 v[130:131], v[130:131], 0, s[72:73]
	s_mov_b32 s8, -2
	s_cmp_eq_u32 s8, 28
	s_cselect_b64 vcc, -1, 0
	s_add_i32 s9, 0, 0x10000
	v_add_u32_e32 v134, s9, v239
	s_add_i32 s11, 0, 0x14000
	ds_read_b128 v[136:139], v134
	ds_read_b128 v[140:143], v134 offset:1024
	ds_read_b128 v[144:147], v134 offset:2048
	ds_read_b128 v[148:151], v134 offset:3072
	v_add_u32_e32 v134, s11, v239
	ds_read_b128 v[152:155], v134
	ds_read_b128 v[156:159], v134 offset:1024
	ds_read_b128 v[160:163], v134 offset:2048
	ds_read_b128 v[164:167], v134 offset:3072
	s_mov_b32 s30, 0xfff40080
	s_mov_b32 s31, -1
	v_lshl_add_u64 v[168:169], v[132:133], 0, s[30:31]
	v_cndmask_b32_e32 v193, v169, v213, vcc
	v_cndmask_b32_e32 v192, v168, v212, vcc
	v_cndmask_b32_e32 v225, v131, v135, vcc
	v_cndmask_b32_e32 v224, v130, v0, vcc
	v_lshl_add_u64 v[226:227], v[132:133], 0, v[210:211]
	s_add_i32 m0, s17, 0xc000
	ds_read_b128 v[168:171], v251
	ds_read_b128 v[172:175], v251 offset:1024
	ds_read_b128 v[176:179], v251 offset:2048
	ds_read_b128 v[180:183], v251 offset:3072
	ds_read_b128 v[184:187], v251 offset:4096
	ds_read_b128 v[188:191], v251 offset:5120
	ds_read_b128 v[216:219], v251 offset:6144
	ds_read_b128 v[220:223], v251 offset:7168
	global_load_lds_dwordx4 v[226:227], off
	v_lshl_add_u64 v[226:227], v[226:227], 0, s[90:91]
	s_add_i32 m0, s17, 0xe000
	s_nop 0
	global_load_lds_dwordx4 v[226:227], off
	s_waitcnt vmcnt(8)
	s_waitcnt lgkmcnt(0)
	s_barrier
	s_setprio 1
	s_waitcnt lgkmcnt(0)
	v_mfma_f32_16x16x32_bf16 v[122:125], v[136:139], v[168:171], 0
	v_mfma_f32_16x16x32_bf16 v[126:129], v[144:147], v[168:171], 0
	v_mfma_f32_16x16x32_bf16 v[110:113], v[136:139], v[176:179], 0
	v_mfma_f32_16x16x32_bf16 v[106:109], v[144:147], v[176:179], 0
	v_mfma_f32_16x16x32_bf16 v[94:97], v[136:139], v[184:187], 0
	v_mfma_f32_16x16x32_bf16 v[90:93], v[144:147], v[184:187], 0
	v_mfma_f32_16x16x32_bf16 v[78:81], v[136:139], v[216:219], 0
	v_mfma_f32_16x16x32_bf16 v[74:77], v[144:147], v[216:219], 0
	v_mfma_f32_16x16x32_bf16 v[122:125], v[140:143], v[172:175], v[122:125]
	v_mfma_f32_16x16x32_bf16 v[126:129], v[148:151], v[172:175], v[126:129]
	v_mfma_f32_16x16x32_bf16 v[110:113], v[140:143], v[180:183], v[110:113]
	v_mfma_f32_16x16x32_bf16 v[106:109], v[148:151], v[180:183], v[106:109]
	v_mfma_f32_16x16x32_bf16 v[94:97], v[140:143], v[188:191], v[94:97]
	v_mfma_f32_16x16x32_bf16 v[90:93], v[148:151], v[188:191], v[90:93]
	v_mfma_f32_16x16x32_bf16 v[78:81], v[140:143], v[220:223], v[78:81]
	v_mfma_f32_16x16x32_bf16 v[74:77], v[148:151], v[220:223], v[74:77]
	s_setprio 0
	s_setprio 1
	v_mfma_f32_16x16x32_bf16 v[118:121], v[152:155], v[168:171], 0
	v_mfma_f32_16x16x32_bf16 v[114:117], v[160:163], v[168:171], 0
	v_mfma_f32_16x16x32_bf16 v[102:105], v[152:155], v[176:179], 0
	v_mfma_f32_16x16x32_bf16 v[98:101], v[160:163], v[176:179], 0
	v_mfma_f32_16x16x32_bf16 v[86:89], v[152:155], v[184:187], 0
	v_mfma_f32_16x16x32_bf16 v[82:85], v[160:163], v[184:187], 0
	v_mfma_f32_16x16x32_bf16 v[70:73], v[152:155], v[216:219], 0
	v_mfma_f32_16x16x32_bf16 v[66:69], v[160:163], v[216:219], 0
	v_mfma_f32_16x16x32_bf16 v[118:121], v[156:159], v[172:175], v[118:121]
	v_mfma_f32_16x16x32_bf16 v[114:117], v[164:167], v[172:175], v[114:117]
	v_mfma_f32_16x16x32_bf16 v[102:105], v[156:159], v[180:183], v[102:105]
	v_mfma_f32_16x16x32_bf16 v[98:101], v[164:167], v[180:183], v[98:101]
	v_mfma_f32_16x16x32_bf16 v[86:89], v[156:159], v[188:191], v[86:89]
	v_mfma_f32_16x16x32_bf16 v[82:85], v[164:167], v[188:191], v[82:85]
	v_mfma_f32_16x16x32_bf16 v[70:73], v[156:159], v[220:223], v[70:73]
	v_mfma_f32_16x16x32_bf16 v[66:69], v[164:167], v[220:223], v[66:69]
	s_setprio 0
	s_barrier
	s_add_i32 s9, s9, s16
	v_lshl_add_u64 v[224:225], v[224:225], 0, v[200:201]
	s_mov_b32 m0, s9
	ds_read_b128 v[168:171], v251 offset:16384
	ds_read_b128 v[172:175], v251 offset:17408
	ds_read_b128 v[176:179], v251 offset:18432
	ds_read_b128 v[180:183], v251 offset:19456
	ds_read_b128 v[184:187], v251 offset:20480
	ds_read_b128 v[188:191], v251 offset:21504
	ds_read_b128 v[216:219], v251 offset:22528
	ds_read_b128 v[220:223], v251 offset:23552
	global_load_lds_dwordx4 v[224:225], off
	v_lshl_add_u64 v[226:227], v[224:225], 0, s[52:53]
	s_add_i32 m0, s9, 0x2000
	s_add_i32 s9, s11, s16
	global_load_lds_dwordx4 v[226:227], off
	v_lshl_add_u64 v[226:227], v[224:225], 0, s[54:55]
	s_mov_b32 m0, s9
	v_lshl_add_u64 v[192:193], v[192:193], 0, v[198:199]
	global_load_lds_dwordx4 v[226:227], off
	v_lshl_add_u64 v[226:227], v[224:225], 0, s[56:57]
	s_add_i32 m0, s9, 0x2000
	s_nop 0
	global_load_lds_dwordx4 v[226:227], off
	s_mov_b32 m0, s17
	v_lshl_add_u64 v[226:227], v[192:193], 0, s[90:91]
	global_load_lds_dwordx4 v[192:193], off
	s_mov_b32 m0, s18
	s_nop 0
	global_load_lds_dwordx4 v[226:227], off
	s_waitcnt vmcnt(8)
	s_waitcnt lgkmcnt(0)
	s_barrier
	s_setprio 1
	s_waitcnt lgkmcnt(0)
	v_mfma_f32_16x16x32_bf16 v[62:65], v[136:139], v[168:171], 0
	v_mfma_f32_16x16x32_bf16 v[58:61], v[144:147], v[168:171], 0
	v_mfma_f32_16x16x32_bf16 v[46:49], v[136:139], v[176:179], 0
	v_mfma_f32_16x16x32_bf16 v[42:45], v[144:147], v[176:179], 0
	v_mfma_f32_16x16x32_bf16 v[30:33], v[136:139], v[184:187], 0
	v_mfma_f32_16x16x32_bf16 v[26:29], v[144:147], v[184:187], 0
	v_mfma_f32_16x16x32_bf16 v[14:17], v[136:139], v[216:219], 0
	v_mfma_f32_16x16x32_bf16 v[10:13], v[144:147], v[216:219], 0
	v_mfma_f32_16x16x32_bf16 v[62:65], v[140:143], v[172:175], v[62:65]
	v_mfma_f32_16x16x32_bf16 v[58:61], v[148:151], v[172:175], v[58:61]
	v_mfma_f32_16x16x32_bf16 v[46:49], v[140:143], v[180:183], v[46:49]
	v_mfma_f32_16x16x32_bf16 v[42:45], v[148:151], v[180:183], v[42:45]
	v_mfma_f32_16x16x32_bf16 v[30:33], v[140:143], v[188:191], v[30:33]
	v_mfma_f32_16x16x32_bf16 v[26:29], v[148:151], v[188:191], v[26:29]
	v_mfma_f32_16x16x32_bf16 v[14:17], v[140:143], v[220:223], v[14:17]
	v_mfma_f32_16x16x32_bf16 v[10:13], v[148:151], v[220:223], v[10:13]
	s_setprio 0
	s_setprio 1
	v_mfma_f32_16x16x32_bf16 v[54:57], v[152:155], v[168:171], 0
	v_mfma_f32_16x16x32_bf16 v[50:53], v[160:163], v[168:171], 0
	v_mfma_f32_16x16x32_bf16 v[38:41], v[152:155], v[176:179], 0
	v_mfma_f32_16x16x32_bf16 v[34:37], v[160:163], v[176:179], 0
	v_mfma_f32_16x16x32_bf16 v[22:25], v[152:155], v[184:187], 0
	v_mfma_f32_16x16x32_bf16 v[18:21], v[160:163], v[184:187], 0
	v_mfma_f32_16x16x32_bf16 v[6:9], v[152:155], v[216:219], 0
	v_mfma_f32_16x16x32_bf16 v[2:5], v[160:163], v[216:219], 0
	v_mfma_f32_16x16x32_bf16 v[54:57], v[156:159], v[172:175], v[54:57]
	v_mfma_f32_16x16x32_bf16 v[50:53], v[164:167], v[172:175], v[50:53]
	v_mfma_f32_16x16x32_bf16 v[38:41], v[156:159], v[180:183], v[38:41]
	v_mfma_f32_16x16x32_bf16 v[34:37], v[164:167], v[180:183], v[34:37]
	v_mfma_f32_16x16x32_bf16 v[22:25], v[156:159], v[188:191], v[22:25]
	v_mfma_f32_16x16x32_bf16 v[18:21], v[164:167], v[188:191], v[18:21]
	v_mfma_f32_16x16x32_bf16 v[6:9], v[156:159], v[220:223], v[6:9]
	v_mfma_f32_16x16x32_bf16 v[2:5], v[164:167], v[220:223], v[2:5]
	s_setprio 0
	s_barrier
	s_add_i32 s9, 0, 0x18000
	v_add_u32_e32 v134, s9, v239
	s_add_i32 s11, 0, 0x1c000
	ds_read_b128 v[136:139], v134
	ds_read_b128 v[140:143], v134 offset:1024
	ds_read_b128 v[144:147], v134 offset:2048
	ds_read_b128 v[148:151], v134 offset:3072
	v_add_u32_e32 v134, s11, v239
	ds_read_b128 v[152:155], v134
	ds_read_b128 v[156:159], v134 offset:1024
	ds_read_b128 v[160:163], v134 offset:2048
	ds_read_b128 v[164:167], v134 offset:3072
	s_mov_b32 m0, s19
	v_lshl_add_u64 v[226:227], v[192:193], 0, s[56:57]
	ds_read_b128 v[168:171], v251 offset:32768
	ds_read_b128 v[172:175], v251 offset:33792
	ds_read_b128 v[176:179], v251 offset:34816
	ds_read_b128 v[180:183], v251 offset:35840
	ds_read_b128 v[184:187], v251 offset:36864
	ds_read_b128 v[188:191], v251 offset:37888
	ds_read_b128 v[216:219], v251 offset:38912
	ds_read_b128 v[220:223], v251 offset:39936
	global_load_lds_dwordx4 v[226:227], off
	v_lshl_add_u64 v[226:227], v[192:193], 0, s[78:79]
	s_mov_b32 m0, s20
	s_nop 0
	global_load_lds_dwordx4 v[226:227], off
	s_waitcnt vmcnt(8)
	s_waitcnt lgkmcnt(0)
	s_barrier
	s_setprio 1
	s_waitcnt lgkmcnt(0)
	v_mfma_f32_16x16x32_bf16 v[122:125], v[136:139], v[168:171], v[122:125]
	v_mfma_f32_16x16x32_bf16 v[126:129], v[144:147], v[168:171], v[126:129]
	v_mfma_f32_16x16x32_bf16 v[110:113], v[136:139], v[176:179], v[110:113]
	v_mfma_f32_16x16x32_bf16 v[106:109], v[144:147], v[176:179], v[106:109]
	v_mfma_f32_16x16x32_bf16 v[94:97], v[136:139], v[184:187], v[94:97]
	v_mfma_f32_16x16x32_bf16 v[90:93], v[144:147], v[184:187], v[90:93]
	v_mfma_f32_16x16x32_bf16 v[78:81], v[136:139], v[216:219], v[78:81]
	v_mfma_f32_16x16x32_bf16 v[74:77], v[144:147], v[216:219], v[74:77]
	v_mfma_f32_16x16x32_bf16 v[122:125], v[140:143], v[172:175], v[122:125]
	v_mfma_f32_16x16x32_bf16 v[126:129], v[148:151], v[172:175], v[126:129]
	v_mfma_f32_16x16x32_bf16 v[110:113], v[140:143], v[180:183], v[110:113]
	v_mfma_f32_16x16x32_bf16 v[106:109], v[148:151], v[180:183], v[106:109]
	v_mfma_f32_16x16x32_bf16 v[94:97], v[140:143], v[188:191], v[94:97]
	v_mfma_f32_16x16x32_bf16 v[90:93], v[148:151], v[188:191], v[90:93]
	v_mfma_f32_16x16x32_bf16 v[78:81], v[140:143], v[220:223], v[78:81]
	v_mfma_f32_16x16x32_bf16 v[74:77], v[148:151], v[220:223], v[74:77]
	s_setprio 0
	s_setprio 1
	v_mfma_f32_16x16x32_bf16 v[118:121], v[152:155], v[168:171], v[118:121]
	v_mfma_f32_16x16x32_bf16 v[114:117], v[160:163], v[168:171], v[114:117]
	v_mfma_f32_16x16x32_bf16 v[102:105], v[152:155], v[176:179], v[102:105]
	v_mfma_f32_16x16x32_bf16 v[98:101], v[160:163], v[176:179], v[98:101]
	v_mfma_f32_16x16x32_bf16 v[86:89], v[152:155], v[184:187], v[86:89]
	v_mfma_f32_16x16x32_bf16 v[82:85], v[160:163], v[184:187], v[82:85]
	v_mfma_f32_16x16x32_bf16 v[70:73], v[152:155], v[216:219], v[70:73]
	v_mfma_f32_16x16x32_bf16 v[66:69], v[160:163], v[216:219], v[66:69]
	v_mfma_f32_16x16x32_bf16 v[118:121], v[156:159], v[172:175], v[118:121]
	v_mfma_f32_16x16x32_bf16 v[114:117], v[164:167], v[172:175], v[114:117]
	v_mfma_f32_16x16x32_bf16 v[102:105], v[156:159], v[180:183], v[102:105]
	v_mfma_f32_16x16x32_bf16 v[98:101], v[164:167], v[180:183], v[98:101]
	v_mfma_f32_16x16x32_bf16 v[86:89], v[156:159], v[188:191], v[86:89]
	v_mfma_f32_16x16x32_bf16 v[82:85], v[164:167], v[188:191], v[82:85]
	v_mfma_f32_16x16x32_bf16 v[70:73], v[156:159], v[220:223], v[70:73]
	v_mfma_f32_16x16x32_bf16 v[66:69], v[164:167], v[220:223], v[66:69]
	s_setprio 0
	s_barrier
	s_add_i32 s9, s9, s16
	v_lshl_add_u64 v[226:227], v[224:225], 0, s[62:63]
	s_mov_b32 m0, s9
	ds_read_b128 v[168:171], v251 offset:49152
	ds_read_b128 v[172:175], v251 offset:50176
	ds_read_b128 v[176:179], v251 offset:51200
	ds_read_b128 v[180:183], v251 offset:52224
	ds_read_b128 v[184:187], v251 offset:53248
	ds_read_b128 v[188:191], v251 offset:54272
	ds_read_b128 v[216:219], v251 offset:55296
	ds_read_b128 v[220:223], v251 offset:56320
	global_load_lds_dwordx4 v[226:227], off
	v_lshl_add_u64 v[226:227], v[224:225], 0, s[64:65]
	s_add_i32 m0, s9, 0x2000
	s_add_i32 s9, s11, s16
	global_load_lds_dwordx4 v[226:227], off
	v_lshl_add_u64 v[226:227], v[224:225], 0, s[66:67]
	s_mov_b32 m0, s9
	v_lshl_add_u64 v[224:225], v[224:225], 0, s[68:69]
	global_load_lds_dwordx4 v[226:227], off
	s_add_i32 m0, s9, 0x2000
	s_nop 0
	global_load_lds_dwordx4 v[224:225], off
	v_lshl_add_u64 v[224:225], v[192:193], 0, s[62:63]
	s_mov_b32 m0, s21
	v_lshl_add_u64 v[192:193], v[192:193], 0, s[58:59]
	global_load_lds_dwordx4 v[224:225], off
	s_mov_b32 m0, s22
	s_nop 0
	global_load_lds_dwordx4 v[192:193], off
	s_waitcnt vmcnt(8)
	s_waitcnt lgkmcnt(0)
	s_barrier
	s_setprio 1
	s_waitcnt lgkmcnt(0)
	v_mfma_f32_16x16x32_bf16 v[62:65], v[136:139], v[168:171], v[62:65]
	v_mfma_f32_16x16x32_bf16 v[58:61], v[144:147], v[168:171], v[58:61]
	v_mfma_f32_16x16x32_bf16 v[46:49], v[136:139], v[176:179], v[46:49]
	v_mfma_f32_16x16x32_bf16 v[42:45], v[144:147], v[176:179], v[42:45]
	v_mfma_f32_16x16x32_bf16 v[30:33], v[136:139], v[184:187], v[30:33]
	v_mfma_f32_16x16x32_bf16 v[26:29], v[144:147], v[184:187], v[26:29]
	v_mfma_f32_16x16x32_bf16 v[14:17], v[136:139], v[216:219], v[14:17]
	v_mfma_f32_16x16x32_bf16 v[10:13], v[144:147], v[216:219], v[10:13]
	v_mfma_f32_16x16x32_bf16 v[62:65], v[140:143], v[172:175], v[62:65]
	v_mfma_f32_16x16x32_bf16 v[58:61], v[148:151], v[172:175], v[58:61]
	v_mfma_f32_16x16x32_bf16 v[46:49], v[140:143], v[180:183], v[46:49]
	v_mfma_f32_16x16x32_bf16 v[42:45], v[148:151], v[180:183], v[42:45]
	v_mfma_f32_16x16x32_bf16 v[30:33], v[140:143], v[188:191], v[30:33]
	v_mfma_f32_16x16x32_bf16 v[26:29], v[148:151], v[188:191], v[26:29]
	v_mfma_f32_16x16x32_bf16 v[14:17], v[140:143], v[220:223], v[14:17]
	v_mfma_f32_16x16x32_bf16 v[10:13], v[148:151], v[220:223], v[10:13]
	s_setprio 0
	s_setprio 1
	v_mfma_f32_16x16x32_bf16 v[54:57], v[152:155], v[168:171], v[54:57]
	v_mfma_f32_16x16x32_bf16 v[50:53], v[160:163], v[168:171], v[50:53]
	v_mfma_f32_16x16x32_bf16 v[38:41], v[152:155], v[176:179], v[38:41]
	v_mfma_f32_16x16x32_bf16 v[34:37], v[160:163], v[176:179], v[34:37]
	v_mfma_f32_16x16x32_bf16 v[22:25], v[152:155], v[184:187], v[22:25]
	v_mfma_f32_16x16x32_bf16 v[18:21], v[160:163], v[184:187], v[18:21]
	v_mfma_f32_16x16x32_bf16 v[6:9], v[152:155], v[216:219], v[6:9]
	v_mfma_f32_16x16x32_bf16 v[2:5], v[160:163], v[216:219], v[2:5]
	v_mfma_f32_16x16x32_bf16 v[54:57], v[156:159], v[172:175], v[54:57]
	v_mfma_f32_16x16x32_bf16 v[50:53], v[164:167], v[172:175], v[50:53]
	v_mfma_f32_16x16x32_bf16 v[38:41], v[156:159], v[180:183], v[38:41]
	v_mfma_f32_16x16x32_bf16 v[34:37], v[164:167], v[180:183], v[34:37]
	v_mfma_f32_16x16x32_bf16 v[22:25], v[156:159], v[188:191], v[22:25]
	v_mfma_f32_16x16x32_bf16 v[18:21], v[164:167], v[188:191], v[18:21]
	v_mfma_f32_16x16x32_bf16 v[6:9], v[156:159], v[220:223], v[6:9]
	v_mfma_f32_16x16x32_bf16 v[2:5], v[164:167], v[220:223], v[2:5]
	s_setprio 0
	s_barrier
	s_add_i32 s8, s8, 2
	v_lshl_add_u64 v[132:133], v[132:133], 0, s[72:73]
	s_cmp_gt_u32 s8, 29
	v_lshl_add_u64 v[130:131], v[130:131], 0, s[72:73]

.LBB0_1102:
	s_or_b64 exec, exec, s[12:13]
	s_and_b64 vcc, exec, s[6:7]
	s_mov_b64 s[6:7], -1
	s_cbranch_vccnz .LBB0_1077
	s_andn2_b64 vcc, exec, s[0:1]
	s_cbranch_vccnz .LBB0_1076
	s_barrier
	s_branch .LBB0_1076

.LBB0_1154:
	s_andn2_b64 vcc, exec, s[0:1]
	s_cbranch_vccnz .LBB0_1219
	v_readlane_b32 s0, v254, 0
	v_readlane_b32 s1, v254, 1
	v_readlane_b32 s2, v254, 4
	v_mbcnt_lo_u32_b32 v0, -1, 0
	v_mbcnt_hi_u32_b32 v0, -1, v0
	s_waitcnt lgkmcnt(0)
	s_mov_b32 s15, s80
	v_readlane_b32 s2, v254, 5
	v_readlane_b32 s3, v254, 6
	s_waitcnt vmcnt(0)
	v_mov_b64_e32 v[2:3], s[0:1]
	s_load_dword s14, s[2:3], 0x0
	flat_load_dwordx2 v[140:141], v[2:3] offset:224
	v_mbcnt_lo_u32_b32 v0, -1, 0
	v_mbcnt_hi_u32_b32 v0, -1, v0
	s_cmpk_gt_i32 s15, 0x13ff
	v_add_u32_e32 v0, s81, v0
	s_nop 0
	v_readfirstlane_b32 s3, v0
	s_cbranch_scc1 .LBB0_1173
	v_bfe_i32 v2, v0, 27, 1
	v_lshlrev_b32_e32 v145, 4, v0
	v_lshrrev_b32_e32 v2, 22, v2
	v_add_u32_e32 v2, v145, v2
	v_and_b32_e32 v2, 0xfffffc00, v2
	v_sub_u32_e32 v2, v145, v2
	v_lshrrev_b32_e32 v3, 4, v2
	v_ashrrev_i32_e32 v4, 31, v0
	v_bitop3_b32 v2, v3, v2, 32 bitop3:0x6c
	v_lshrrev_b32_e32 v4, 26, v4
	v_ashrrev_i32_e32 v3, 31, v2
	v_add_u32_e32 v4, v0, v4
	v_lshrrev_b32_e32 v3, 26, v3
	v_ashrrev_i32_e32 v146, 6, v4
	s_mov_b64 s[0:1], 0x2200000
	v_add_u32_e32 v3, v2, v3
	v_lshlrev_b32_e32 v4, 3, v146
	s_waitcnt vmcnt(0) lgkmcnt(0)
	v_lshl_add_u64 v[130:131], v[140:141], 0, s[0:1]
	s_mov_b64 s[0:1], 0x8200000
	v_ashrrev_i32_e32 v144, 6, v3
	v_and_b32_e32 v4, -16, v4
	v_lshl_add_u64 v[132:133], v[140:141], 0, s[0:1]
	v_add_u32_e32 v4, v144, v4
	v_and_b32_e32 v5, 3, v144
	s_mov_b32 s0, 0xfffe0
	s_ashr_i32 s17, s15, 31
	v_and_or_b32 v5, v4, s0, v5
	s_lshr_b32 s0, s17, 29
	s_add_i32 s0, s15, s0
	s_ashr_i32 s4, s3, 6
	s_ashr_i32 s1, s0, 3
	s_and_b32 s0, s0, -8
	s_ashr_i32 s5, s3, 8
	s_lshl_b32 s16, s4, 10
	s_sub_i32 s0, s15, s0
	s_cmp_lt_i32 s0, 0
	s_movk_i32 s2, 0x281
	s_cselect_b32 s2, s2, 0x280
	s_mul_i32 s0, s0, s2
	s_add_i32 s0, s0, s1
	s_ashr_i32 s1, s0, 31
	s_lshr_b32 s1, s1, 24
	s_add_i32 s1, s0, s1
	s_ashr_i32 s2, s1, 8
	s_and_b32 s1, s1, 0xff00
	s_sub_i32 s0, s0, s1
	s_sext_i32_i16 s1, s0
	s_bfe_u32 s1, s1, 0x3001c
	s_add_i32 s1, s0, s1
	v_lshrrev_b32_e32 v6, 2, v4
	v_lshlrev_b32_e32 v7, 1, v4
	v_and_b32_e32 v3, 0xc0, v3
	s_lshl_b32 s6, s2, 3
	s_sext_i32_i16 s2, s1
	s_and_b32 s1, s1, 0xfff8
	v_and_b32_e32 v6, 4, v6
	v_and_b32_e32 v7, 24, v7
	v_sub_u32_e32 v2, v2, v3
	s_sub_i32 s0, s0, s1
	v_or3_b32 v5, v5, v6, v7
	v_lshlrev_b32_e32 v6, 5, v146
	v_ashrrev_i16_sdwa v2, v241, sext(v2) dst_sel:DWORD dst_unused:UNUSED_PAD src0_sel:DWORD src1_sel:BYTE_0
	s_lshr_b32 s2, s2, 3
	s_sext_i32_i16 s0, s0
	v_and_b32_e32 v6, 32, v6
	v_bfe_i32 v147, v2, 0, 16
	s_add_i32 s10, s6, s0
	s_bfe_i64 s[6:7], s[2:3], 0x100000
	v_add_lshl_u32 v2, v6, v147, 1
	s_lshl_b64 s[6:7], s[6:7], 20
	v_lshl_add_u32 v134, v5, 12, v2
	v_lshl_add_u64 v[148:149], v[130:131], 0, s[6:7]
	v_mov_b32_e32 v135, v1
	s_add_i32 s18, s16, 0
	v_lshl_add_u64 v[138:139], v[148:149], 0, v[134:135]
	s_add_i32 m0, s18, 0x10000
	v_lshl_add_u32 v136, v4, 12, v2
	s_ashr_i32 s11, s10, 31
	global_load_lds_dwordx4 v[138:139], off
	v_lshl_add_u64 v[142:143], v[138:139], 0, s[52:53]
	s_add_i32 m0, s18, 0x12000
	s_lshl_b64 s[0:1], s[10:11], 20
	global_load_lds_dwordx4 v[142:143], off
	v_lshl_add_u64 v[142:143], v[138:139], 0, s[54:55]
	s_add_i32 m0, s18, 0x14000
	v_lshl_add_u64 v[150:151], v[132:133], 0, s[0:1]
	global_load_lds_dwordx4 v[142:143], off
	v_lshl_add_u64 v[142:143], v[138:139], 0, s[56:57]
	s_add_i32 m0, s18, 0x16000
	v_mov_b32_e32 v137, v1
	global_load_lds_dwordx4 v[142:143], off
	v_lshl_add_u64 v[142:143], v[150:151], 0, v[136:137]
	s_mov_b32 m0, s18
	s_add_i32 s19, s18, 0x2000
	global_load_lds_dwordx4 v[142:143], off
	v_lshl_add_u64 v[152:153], v[142:143], 0, s[52:53]
	s_mov_b32 m0, s19
	s_add_i32 s20, s18, 0x4000
	global_load_lds_dwordx4 v[152:153], off
	v_lshl_add_u64 v[152:153], v[142:143], 0, s[54:55]
	s_mov_b32 m0, s20
	s_add_i32 s21, s18, 0x6000
	global_load_lds_dwordx4 v[152:153], off
	v_lshl_add_u64 v[152:153], v[142:143], 0, s[56:57]
	s_mov_b32 m0, s21
	s_cmp_eq_u32 s5, 1
	global_load_lds_dwordx4 v[152:153], off
	s_cselect_b64 s[0:1], -1, 0
	s_cmp_lg_u32 s5, 1
	s_cbranch_scc1 .LBB0_1158
	s_barrier

.LBB0_1163:
	s_ashr_i32 s9, s8, 31
	s_lshl_b64 s[12:13], s[8:9], 20
	s_ashr_i32 s7, s6, 31
	v_lshl_add_u64 v[144:145], v[132:133], 0, s[12:13]
	s_lshl_b64 s[12:13], s[6:7], 20
	s_lshl_b32 s7, s10, 8
	v_add_u32_e32 v156, s7, v166
	v_ashrrev_i32_e32 v157, 31, v156
	v_lshlrev_b64 v[158:159], 6, v[156:157]
	v_add_u32_e32 v156, s7, v167
	v_ashrrev_i32_e32 v157, 31, v156
	v_lshl_add_u64 v[146:147], v[130:131], 0, s[12:13]
	v_lshlrev_b64 v[156:157], 6, v[156:157]
	v_cndmask_b32_e64 v153, v151, v145, s[4:5]
	v_cndmask_b32_e64 v0, v150, v144, s[4:5]
	v_cndmask_b32_e64 v155, v149, v147, s[4:5]
	v_cndmask_b32_e64 v152, v148, v146, s[4:5]
	v_lshl_add_u64 v[156:157], v[140:141], 0, v[156:157]
	v_lshl_add_u64 v[158:159], v[140:141], 0, v[158:159]
	v_lshl_add_u64 v[150:151], v[150:151], 0, s[66:67]
	v_lshl_add_u64 v[148:149], v[148:149], 0, s[72:73]
	s_mov_b32 s9, -2
	s_mov_b64 vcc, 0
	s_add_i32 s10, 0, 0x10000
	v_add_u32_e32 v154, s10, v163
	s_add_i32 s12, 0, 0x14000
	ds_read_b128 v[172:175], v154
	ds_read_b128 v[176:179], v154 offset:1024
	ds_read_b128 v[180:183], v154 offset:2048
	ds_read_b128 v[184:187], v154 offset:3072
	v_add_u32_e32 v154, s12, v163
	ds_read_b128 v[188:191], v154
	ds_read_b128 v[192:195], v154 offset:1024
	ds_read_b128 v[196:199], v154 offset:2048
	ds_read_b128 v[200:203], v154 offset:3072
	v_lshl_add_u64 v[164:165], v[150:151], 0, s[74:75]
	v_cndmask_b32_e32 v165, v165, v153, vcc
	v_cndmask_b32_e32 v164, v164, v0, vcc
	v_cndmask_b32_e32 v205, v149, v155, vcc
	v_cndmask_b32_e32 v204, v148, v152, vcc
	v_lshl_add_u64 v[206:207], v[150:151], 0, v[142:143]
	s_add_i32 m0, s18, 0xc000
	ds_read_b128 v[210:213], v169
	ds_read_b128 v[214:217], v169 offset:1024
	ds_read_b128 v[218:221], v169 offset:2048
	ds_read_b128 v[222:225], v169 offset:3072
	ds_read_b128 v[226:229], v169 offset:4096
	ds_read_b128 v[230:233], v169 offset:5120
	ds_read_b128 v[234:237], v169 offset:6144
	ds_read_b128 v[250:253], v169 offset:7168
	global_load_lds_dwordx4 v[206:207], off
	v_lshl_add_u64 v[206:207], v[206:207], 0, s[52:53]
	s_add_i32 m0, s18, 0xe000
	s_nop 0
	global_load_lds_dwordx4 v[206:207], off
	s_waitcnt vmcnt(8)
	s_waitcnt lgkmcnt(0)
	s_barrier
	s_setprio 1
	s_waitcnt lgkmcnt(0)
	v_mfma_f32_16x16x32_bf16 v[126:129], v[172:175], v[210:213], 0
	v_mfma_f32_16x16x32_bf16 v[122:125], v[180:183], v[210:213], 0
	v_mfma_f32_16x16x32_bf16 v[110:113], v[172:175], v[218:221], 0
	v_mfma_f32_16x16x32_bf16 v[106:109], v[180:183], v[218:221], 0
	v_mfma_f32_16x16x32_bf16 v[94:97], v[172:175], v[226:229], 0
	v_mfma_f32_16x16x32_bf16 v[90:93], v[180:183], v[226:229], 0
	v_mfma_f32_16x16x32_bf16 v[78:81], v[172:175], v[234:237], 0
	v_mfma_f32_16x16x32_bf16 v[74:77], v[180:183], v[234:237], 0
	v_mfma_f32_16x16x32_bf16 v[126:129], v[176:179], v[214:217], v[126:129]
	v_mfma_f32_16x16x32_bf16 v[122:125], v[184:187], v[214:217], v[122:125]
	v_mfma_f32_16x16x32_bf16 v[110:113], v[176:179], v[222:225], v[110:113]
	v_mfma_f32_16x16x32_bf16 v[106:109], v[184:187], v[222:225], v[106:109]
	v_mfma_f32_16x16x32_bf16 v[94:97], v[176:179], v[230:233], v[94:97]
	v_mfma_f32_16x16x32_bf16 v[90:93], v[184:187], v[230:233], v[90:93]
	v_mfma_f32_16x16x32_bf16 v[78:81], v[176:179], v[250:253], v[78:81]
	v_mfma_f32_16x16x32_bf16 v[74:77], v[184:187], v[250:253], v[74:77]
	s_setprio 0
	s_setprio 1
	v_mfma_f32_16x16x32_bf16 v[118:121], v[188:191], v[210:213], 0
	v_mfma_f32_16x16x32_bf16 v[114:117], v[196:199], v[210:213], 0
	v_mfma_f32_16x16x32_bf16 v[102:105], v[188:191], v[218:221], 0
	v_mfma_f32_16x16x32_bf16 v[98:101], v[196:199], v[218:221], 0
	v_mfma_f32_16x16x32_bf16 v[86:89], v[188:191], v[226:229], 0
	v_mfma_f32_16x16x32_bf16 v[82:85], v[196:199], v[226:229], 0
	v_mfma_f32_16x16x32_bf16 v[70:73], v[188:191], v[234:237], 0
	v_mfma_f32_16x16x32_bf16 v[66:69], v[196:199], v[234:237], 0
	v_mfma_f32_16x16x32_bf16 v[118:121], v[192:195], v[214:217], v[118:121]
	v_mfma_f32_16x16x32_bf16 v[114:117], v[200:203], v[214:217], v[114:117]
	v_mfma_f32_16x16x32_bf16 v[102:105], v[192:195], v[222:225], v[102:105]
	v_mfma_f32_16x16x32_bf16 v[98:101], v[200:203], v[222:225], v[98:101]
	v_mfma_f32_16x16x32_bf16 v[86:89], v[192:195], v[230:233], v[86:89]
	v_mfma_f32_16x16x32_bf16 v[82:85], v[200:203], v[230:233], v[82:85]
	v_mfma_f32_16x16x32_bf16 v[70:73], v[192:195], v[250:253], v[70:73]
	v_mfma_f32_16x16x32_bf16 v[66:69], v[200:203], v[250:253], v[66:69]
	s_setprio 0
	s_barrier
	s_add_i32 s10, s10, s16
	v_lshl_add_u64 v[204:205], v[204:205], 0, v[134:135]
	s_mov_b32 m0, s10
	ds_read_b128 v[210:213], v169 offset:16384
	ds_read_b128 v[214:217], v169 offset:17408
	ds_read_b128 v[218:221], v169 offset:18432
	ds_read_b128 v[222:225], v169 offset:19456
	ds_read_b128 v[226:229], v169 offset:20480
	ds_read_b128 v[230:233], v169 offset:21504
	ds_read_b128 v[234:237], v169 offset:22528
	ds_read_b128 v[250:253], v169 offset:23552
	global_load_lds_dwordx4 v[204:205], off
	v_lshl_add_u64 v[206:207], v[204:205], 0, s[52:53]
	s_add_i32 m0, s10, 0x2000
	s_add_i32 s10, s12, s16
	global_load_lds_dwordx4 v[206:207], off
	v_lshl_add_u64 v[206:207], v[204:205], 0, s[54:55]
	s_mov_b32 m0, s10
	v_lshl_add_u64 v[164:165], v[164:165], 0, v[136:137]
	global_load_lds_dwordx4 v[206:207], off
	v_lshl_add_u64 v[206:207], v[204:205], 0, s[56:57]
	s_add_i32 m0, s10, 0x2000
	s_nop 0
	global_load_lds_dwordx4 v[206:207], off
	s_mov_b32 m0, s18
	v_lshl_add_u64 v[206:207], v[164:165], 0, s[52:53]
	global_load_lds_dwordx4 v[164:165], off
	s_mov_b32 m0, s19
	s_nop 0
	global_load_lds_dwordx4 v[206:207], off
	s_waitcnt vmcnt(8)
	s_waitcnt lgkmcnt(0)
	s_barrier
	s_setprio 1
	s_waitcnt lgkmcnt(0)
	v_mfma_f32_16x16x32_bf16 v[62:65], v[172:175], v[210:213], 0
	v_mfma_f32_16x16x32_bf16 v[58:61], v[180:183], v[210:213], 0
	v_mfma_f32_16x16x32_bf16 v[46:49], v[172:175], v[218:221], 0
	v_mfma_f32_16x16x32_bf16 v[42:45], v[180:183], v[218:221], 0
	v_mfma_f32_16x16x32_bf16 v[30:33], v[172:175], v[226:229], 0
	v_mfma_f32_16x16x32_bf16 v[26:29], v[180:183], v[226:229], 0
	v_mfma_f32_16x16x32_bf16 v[14:17], v[172:175], v[234:237], 0
	v_mfma_f32_16x16x32_bf16 v[10:13], v[180:183], v[234:237], 0
	v_mfma_f32_16x16x32_bf16 v[62:65], v[176:179], v[214:217], v[62:65]
	v_mfma_f32_16x16x32_bf16 v[58:61], v[184:187], v[214:217], v[58:61]
	v_mfma_f32_16x16x32_bf16 v[46:49], v[176:179], v[222:225], v[46:49]
	v_mfma_f32_16x16x32_bf16 v[42:45], v[184:187], v[222:225], v[42:45]
	v_mfma_f32_16x16x32_bf16 v[30:33], v[176:179], v[230:233], v[30:33]
	v_mfma_f32_16x16x32_bf16 v[26:29], v[184:187], v[230:233], v[26:29]
	v_mfma_f32_16x16x32_bf16 v[14:17], v[176:179], v[250:253], v[14:17]
	v_mfma_f32_16x16x32_bf16 v[10:13], v[184:187], v[250:253], v[10:13]
	s_setprio 0
	s_setprio 1
	v_mfma_f32_16x16x32_bf16 v[54:57], v[188:191], v[210:213], 0
	v_mfma_f32_16x16x32_bf16 v[50:53], v[196:199], v[210:213], 0
	v_mfma_f32_16x16x32_bf16 v[38:41], v[188:191], v[218:221], 0
	v_mfma_f32_16x16x32_bf16 v[34:37], v[196:199], v[218:221], 0
	v_mfma_f32_16x16x32_bf16 v[22:25], v[188:191], v[226:229], 0
	v_mfma_f32_16x16x32_bf16 v[18:21], v[196:199], v[226:229], 0
	v_mfma_f32_16x16x32_bf16 v[2:5], v[188:191], v[234:237], 0
	v_mfma_f32_16x16x32_bf16 v[6:9], v[196:199], v[234:237], 0
	v_mfma_f32_16x16x32_bf16 v[54:57], v[192:195], v[214:217], v[54:57]
	v_mfma_f32_16x16x32_bf16 v[50:53], v[200:203], v[214:217], v[50:53]
	v_mfma_f32_16x16x32_bf16 v[38:41], v[192:195], v[222:225], v[38:41]
	v_mfma_f32_16x16x32_bf16 v[34:37], v[200:203], v[222:225], v[34:37]
	v_mfma_f32_16x16x32_bf16 v[22:25], v[192:195], v[230:233], v[22:25]
	v_mfma_f32_16x16x32_bf16 v[18:21], v[200:203], v[230:233], v[18:21]
	v_mfma_f32_16x16x32_bf16 v[2:5], v[192:195], v[250:253], v[2:5]
	v_mfma_f32_16x16x32_bf16 v[6:9], v[200:203], v[250:253], v[6:9]
	s_setprio 0
	s_barrier
	s_add_i32 s10, 0, 0x18000
	v_add_u32_e32 v154, s10, v163
	s_add_i32 s12, 0, 0x1c000
	ds_read_b128 v[172:175], v154
	ds_read_b128 v[176:179], v154 offset:1024
	ds_read_b128 v[180:183], v154 offset:2048
	ds_read_b128 v[184:187], v154 offset:3072
	v_add_u32_e32 v154, s12, v163
	ds_read_b128 v[188:191], v154
	ds_read_b128 v[192:195], v154 offset:1024
	ds_read_b128 v[196:199], v154 offset:2048
	ds_read_b128 v[200:203], v154 offset:3072
	s_mov_b32 m0, s20
	v_lshl_add_u64 v[206:207], v[164:165], 0, s[54:55]
	ds_read_b128 v[210:213], v169 offset:32768
	ds_read_b128 v[214:217], v169 offset:33792
	ds_read_b128 v[218:221], v169 offset:34816
	ds_read_b128 v[222:225], v169 offset:35840
	ds_read_b128 v[226:229], v169 offset:36864
	ds_read_b128 v[230:233], v169 offset:37888
	ds_read_b128 v[234:237], v169 offset:38912
	ds_read_b128 v[250:253], v169 offset:39936
	global_load_lds_dwordx4 v[206:207], off
	v_lshl_add_u64 v[206:207], v[164:165], 0, s[56:57]
	s_mov_b32 m0, s21
	s_nop 0
	global_load_lds_dwordx4 v[206:207], off
	s_waitcnt vmcnt(8)
	s_waitcnt lgkmcnt(0)
	s_barrier
	s_setprio 1
	s_waitcnt lgkmcnt(0)
	v_mfma_f32_16x16x32_bf16 v[126:129], v[172:175], v[210:213], v[126:129]
	v_mfma_f32_16x16x32_bf16 v[122:125], v[180:183], v[210:213], v[122:125]
	v_mfma_f32_16x16x32_bf16 v[110:113], v[172:175], v[218:221], v[110:113]
	v_mfma_f32_16x16x32_bf16 v[106:109], v[180:183], v[218:221], v[106:109]
	v_mfma_f32_16x16x32_bf16 v[94:97], v[172:175], v[226:229], v[94:97]
	v_mfma_f32_16x16x32_bf16 v[90:93], v[180:183], v[226:229], v[90:93]
	v_mfma_f32_16x16x32_bf16 v[78:81], v[172:175], v[234:237], v[78:81]
	v_mfma_f32_16x16x32_bf16 v[74:77], v[180:183], v[234:237], v[74:77]
	v_mfma_f32_16x16x32_bf16 v[126:129], v[176:179], v[214:217], v[126:129]
	v_mfma_f32_16x16x32_bf16 v[122:125], v[184:187], v[214:217], v[122:125]
	v_mfma_f32_16x16x32_bf16 v[110:113], v[176:179], v[222:225], v[110:113]
	v_mfma_f32_16x16x32_bf16 v[106:109], v[184:187], v[222:225], v[106:109]
	v_mfma_f32_16x16x32_bf16 v[94:97], v[176:179], v[230:233], v[94:97]
	v_mfma_f32_16x16x32_bf16 v[90:93], v[184:187], v[230:233], v[90:93]
	v_mfma_f32_16x16x32_bf16 v[78:81], v[176:179], v[250:253], v[78:81]
	v_mfma_f32_16x16x32_bf16 v[74:77], v[184:187], v[250:253], v[74:77]
	s_setprio 0
	s_setprio 1
	v_mfma_f32_16x16x32_bf16 v[118:121], v[188:191], v[210:213], v[118:121]
	v_mfma_f32_16x16x32_bf16 v[114:117], v[196:199], v[210:213], v[114:117]
	v_mfma_f32_16x16x32_bf16 v[102:105], v[188:191], v[218:221], v[102:105]
	v_mfma_f32_16x16x32_bf16 v[98:101], v[196:199], v[218:221], v[98:101]
	v_mfma_f32_16x16x32_bf16 v[86:89], v[188:191], v[226:229], v[86:89]
	v_mfma_f32_16x16x32_bf16 v[82:85], v[196:199], v[226:229], v[82:85]
	v_mfma_f32_16x16x32_bf16 v[70:73], v[188:191], v[234:237], v[70:73]
	v_mfma_f32_16x16x32_bf16 v[66:69], v[196:199], v[234:237], v[66:69]
	v_mfma_f32_16x16x32_bf16 v[118:121], v[192:195], v[214:217], v[118:121]
	v_mfma_f32_16x16x32_bf16 v[114:117], v[200:203], v[214:217], v[114:117]
	v_mfma_f32_16x16x32_bf16 v[102:105], v[192:195], v[222:225], v[102:105]
	v_mfma_f32_16x16x32_bf16 v[98:101], v[200:203], v[222:225], v[98:101]
	v_mfma_f32_16x16x32_bf16 v[86:89], v[192:195], v[230:233], v[86:89]
	v_mfma_f32_16x16x32_bf16 v[82:85], v[200:203], v[230:233], v[82:85]
	v_mfma_f32_16x16x32_bf16 v[70:73], v[192:195], v[250:253], v[70:73]
	v_mfma_f32_16x16x32_bf16 v[66:69], v[200:203], v[250:253], v[66:69]
	s_setprio 0
	s_barrier
	s_add_i32 s10, s10, s16
	v_lshl_add_u64 v[206:207], v[204:205], 0, s[62:63]
	s_mov_b32 m0, s10
	ds_read_b128 v[210:213], v169 offset:49152
	ds_read_b128 v[214:217], v169 offset:50176
	ds_read_b128 v[218:221], v169 offset:51200
	ds_read_b128 v[222:225], v169 offset:52224
	ds_read_b128 v[226:229], v169 offset:53248
	ds_read_b128 v[230:233], v169 offset:54272
	ds_read_b128 v[234:237], v169 offset:55296
	ds_read_b128 v[250:253], v169 offset:56320
	global_load_lds_dwordx4 v[206:207], off
	v_lshl_add_u64 v[206:207], v[204:205], 0, s[64:65]
	s_add_i32 m0, s10, 0x2000
	s_add_i32 s10, s12, s16
	global_load_lds_dwordx4 v[206:207], off
	v_lshl_add_u64 v[206:207], v[204:205], 0, s[66:67]
	s_mov_b32 m0, s10
	v_lshl_add_u64 v[204:205], v[204:205], 0, s[68:69]
	global_load_lds_dwordx4 v[206:207], off
	s_add_i32 m0, s10, 0x2000
	s_nop 0
	global_load_lds_dwordx4 v[204:205], off
	v_lshl_add_u64 v[204:205], v[164:165], 0, s[62:63]
	s_mov_b32 m0, s22
	v_lshl_add_u64 v[164:165], v[164:165], 0, s[64:65]
	global_load_lds_dwordx4 v[204:205], off
	s_mov_b32 m0, s23
	s_nop 0
	global_load_lds_dwordx4 v[164:165], off
	s_waitcnt vmcnt(8)
	s_waitcnt lgkmcnt(0)
	s_barrier
	s_setprio 1
	s_waitcnt lgkmcnt(0)
	v_mfma_f32_16x16x32_bf16 v[62:65], v[172:175], v[210:213], v[62:65]
	v_mfma_f32_16x16x32_bf16 v[58:61], v[180:183], v[210:213], v[58:61]
	v_mfma_f32_16x16x32_bf16 v[46:49], v[172:175], v[218:221], v[46:49]
	v_mfma_f32_16x16x32_bf16 v[42:45], v[180:183], v[218:221], v[42:45]
	v_mfma_f32_16x16x32_bf16 v[30:33], v[172:175], v[226:229], v[30:33]
	v_mfma_f32_16x16x32_bf16 v[26:29], v[180:183], v[226:229], v[26:29]
	v_mfma_f32_16x16x32_bf16 v[14:17], v[172:175], v[234:237], v[14:17]
	v_mfma_f32_16x16x32_bf16 v[10:13], v[180:183], v[234:237], v[10:13]
	v_mfma_f32_16x16x32_bf16 v[62:65], v[176:179], v[214:217], v[62:65]
	v_mfma_f32_16x16x32_bf16 v[58:61], v[184:187], v[214:217], v[58:61]
	v_mfma_f32_16x16x32_bf16 v[46:49], v[176:179], v[222:225], v[46:49]
	v_mfma_f32_16x16x32_bf16 v[42:45], v[184:187], v[222:225], v[42:45]
	v_mfma_f32_16x16x32_bf16 v[30:33], v[176:179], v[230:233], v[30:33]
	v_mfma_f32_16x16x32_bf16 v[26:29], v[184:187], v[230:233], v[26:29]
	v_mfma_f32_16x16x32_bf16 v[14:17], v[176:179], v[250:253], v[14:17]
	v_mfma_f32_16x16x32_bf16 v[10:13], v[184:187], v[250:253], v[10:13]
	s_setprio 0
	s_setprio 1
	v_mfma_f32_16x16x32_bf16 v[54:57], v[188:191], v[210:213], v[54:57]
	v_mfma_f32_16x16x32_bf16 v[50:53], v[196:199], v[210:213], v[50:53]
	v_mfma_f32_16x16x32_bf16 v[38:41], v[188:191], v[218:221], v[38:41]
	v_mfma_f32_16x16x32_bf16 v[34:37], v[196:199], v[218:221], v[34:37]
	v_mfma_f32_16x16x32_bf16 v[22:25], v[188:191], v[226:229], v[22:25]
	v_mfma_f32_16x16x32_bf16 v[18:21], v[196:199], v[226:229], v[18:21]
	v_mfma_f32_16x16x32_bf16 v[2:5], v[188:191], v[234:237], v[2:5]
	v_mfma_f32_16x16x32_bf16 v[6:9], v[196:199], v[234:237], v[6:9]
	v_mfma_f32_16x16x32_bf16 v[54:57], v[192:195], v[214:217], v[54:57]
	v_mfma_f32_16x16x32_bf16 v[50:53], v[200:203], v[214:217], v[50:53]
	v_mfma_f32_16x16x32_bf16 v[38:41], v[192:195], v[222:225], v[38:41]
	v_mfma_f32_16x16x32_bf16 v[34:37], v[200:203], v[222:225], v[34:37]
	v_mfma_f32_16x16x32_bf16 v[22:25], v[192:195], v[230:233], v[22:25]
	v_mfma_f32_16x16x32_bf16 v[18:21], v[200:203], v[230:233], v[18:21]
	v_mfma_f32_16x16x32_bf16 v[2:5], v[192:195], v[250:253], v[2:5]
	v_mfma_f32_16x16x32_bf16 v[6:9], v[200:203], v[250:253], v[6:9]
	s_setprio 0
	s_barrier
	s_add_i32 s9, s9, 2
	v_lshl_add_u64 v[150:151], v[150:151], 0, s[72:73]
	s_cmp_gt_u32 s9, 29
	v_lshl_add_u64 v[148:149], v[148:149], 0, s[72:73]
	s_branch .LBB0_1165

.LBB0_1169:
	ds_read_b128 v[150:153], v170
	ds_read_b128 v[154:157], v170 offset:2048
	v_add_u32_e32 v148, s7, v161
	v_lshl_or_b32 v164, s11, 8, v168
	v_ashrrev_i32_e32 v165, 31, v164
	s_waitcnt lgkmcnt(0)
	v_lshlrev_b32_e32 v0, 16, v150
	v_and_b32_e32 v149, 0xffff0000, v150
	v_add_f32_e32 v0, v0, v149
	v_lshlrev_b32_e32 v149, 16, v151
	v_and_b32_e32 v150, 0xffff0000, v151
	v_add_f32_e32 v149, v149, v150
	v_add_f32_e32 v0, v0, v149
	v_lshlrev_b32_e32 v149, 16, v152
	v_and_b32_e32 v150, 0xffff0000, v152
	v_add_f32_e32 v149, v149, v150
	v_lshlrev_b32_e32 v150, 16, v153
	v_and_b32_e32 v151, 0xffff0000, v153
	v_add_f32_e32 v150, v150, v151
	v_add_f32_e32 v149, v149, v150
	v_add_f32_e32 v0, v0, v149
	v_mov_b32_e32 v149, v0
	ds_read_b128 v[150:153], v170 offset:1024
	ds_read_b128 v[172:175], v170 offset:8192
	v_permlane16_swap_b32_e32 v0, v149
	v_add_f32_e32 v0, v0, v149
	v_mov_b32_e32 v149, v0
	s_nop 1
	v_permlane32_swap_b32_e32 v0, v149
	v_add_f32_e32 v0, v0, v149
	s_waitcnt lgkmcnt(0)
	v_lshlrev_b32_e32 v149, 16, v150
	v_and_b32_e32 v150, 0xffff0000, v150
	v_add_f32_e32 v149, v149, v150
	v_lshlrev_b32_e32 v150, 16, v151
	v_and_b32_e32 v151, 0xffff0000, v151
	v_add_f32_e32 v150, v150, v151
	v_add_f32_e32 v149, v149, v150
	v_lshlrev_b32_e32 v150, 16, v152
	v_and_b32_e32 v151, 0xffff0000, v152
	v_add_f32_e32 v150, v150, v151
	v_lshlrev_b32_e32 v151, 16, v153
	v_and_b32_e32 v152, 0xffff0000, v153
	v_add_f32_e32 v151, v151, v152
	v_add_f32_e32 v150, v150, v151
	v_add_f32_e32 v149, v149, v150
	v_mov_b32_e32 v150, v149
	s_nop 1
	v_permlane16_swap_b32_e32 v149, v150
	v_add_f32_e32 v149, v149, v150
	v_mov_b32_e32 v150, v149
	s_nop 1
	v_permlane32_swap_b32_e32 v149, v150
	v_add_f32_e32 v149, v149, v150
	v_fmamk_f32 v149, v149, 0x3a000000, v240
	v_rsq_f32_e32 v152, v149
	v_lshlrev_b32_e32 v149, 16, v154
	v_and_b32_e32 v150, 0xffff0000, v154
	v_add_f32_e32 v149, v149, v150
	v_lshlrev_b32_e32 v150, 16, v155
	v_and_b32_e32 v151, 0xffff0000, v155
	v_add_f32_e32 v150, v150, v151
	v_add_f32_e32 v149, v149, v150
	v_lshlrev_b32_e32 v150, 16, v156
	v_and_b32_e32 v151, 0xffff0000, v156
	v_add_f32_e32 v150, v150, v151
	v_lshlrev_b32_e32 v151, 16, v157
	v_and_b32_e32 v153, 0xffff0000, v157
	v_add_f32_e32 v151, v151, v153
	v_add_f32_e32 v150, v150, v151
	v_add_f32_e32 v149, v149, v150
	v_mov_b32_e32 v150, v149
	s_nop 1
	v_permlane16_swap_b32_e32 v149, v150
	v_add_f32_e32 v149, v149, v150
	ds_read_b128 v[154:157], v170 offset:3072
	v_mov_b32_e32 v150, v149
	s_nop 1
	v_permlane32_swap_b32_e32 v149, v150
	v_add_f32_e32 v149, v149, v150
	v_fmamk_f32 v149, v149, 0x3a000000, v240
	v_rsq_f32_e32 v150, v149
	s_waitcnt lgkmcnt(0)
	v_lshlrev_b32_e32 v149, 16, v154
	v_and_b32_e32 v151, 0xffff0000, v154
	v_add_f32_e32 v149, v149, v151
	v_lshlrev_b32_e32 v151, 16, v155
	v_and_b32_e32 v153, 0xffff0000, v155
	v_add_f32_e32 v151, v151, v153
	v_add_f32_e32 v149, v149, v151
	v_lshlrev_b32_e32 v151, 16, v156
	v_and_b32_e32 v153, 0xffff0000, v156
	v_add_f32_e32 v151, v151, v153
	v_lshlrev_b32_e32 v153, 16, v157
	v_and_b32_e32 v154, 0xffff0000, v157
	v_add_f32_e32 v153, v153, v154
	v_add_f32_e32 v151, v151, v153
	v_add_f32_e32 v149, v149, v151
	v_mov_b32_e32 v151, v149
	s_nop 1
	v_permlane16_swap_b32_e32 v149, v151
	v_add_f32_e32 v149, v149, v151
	v_mov_b32_e32 v151, v149
	s_nop 1
	v_permlane32_swap_b32_e32 v149, v151
	v_add_f32_e32 v149, v149, v151
	v_fmamk_f32 v149, v149, 0x3a000000, v240
	v_rsq_f32_e32 v156, v149
	v_lshlrev_b32_e32 v149, 16, v172
	v_and_b32_e32 v151, 0xffff0000, v172
	v_add_f32_e32 v149, v149, v151
	v_lshlrev_b32_e32 v151, 16, v173
	v_and_b32_e32 v153, 0xffff0000, v173
	v_add_f32_e32 v151, v151, v153
	v_add_f32_e32 v149, v149, v151
	v_lshlrev_b32_e32 v151, 16, v174
	v_and_b32_e32 v153, 0xffff0000, v174
	v_add_f32_e32 v151, v151, v153
	v_lshlrev_b32_e32 v153, 16, v175
	v_and_b32_e32 v154, 0xffff0000, v175
	v_add_f32_e32 v153, v153, v154
	v_add_f32_e32 v151, v151, v153
	v_add_f32_e32 v149, v149, v151
	v_mov_b32_e32 v151, v149
	s_nop 1
	v_permlane16_swap_b32_e32 v149, v151
	v_add_f32_e32 v149, v149, v151
	ds_read_b128 v[172:175], v170 offset:9216
	v_mov_b32_e32 v151, v149
	s_nop 1
	v_permlane32_swap_b32_e32 v149, v151
	v_add_f32_e32 v149, v149, v151
	v_fmamk_f32 v149, v149, 0x3a000000, v240
	v_rsq_f32_e32 v154, v149
	s_waitcnt lgkmcnt(0)
	v_lshlrev_b32_e32 v149, 16, v172
	v_and_b32_e32 v151, 0xffff0000, v172
	v_add_f32_e32 v149, v149, v151
	v_lshlrev_b32_e32 v151, 16, v173
	v_and_b32_e32 v153, 0xffff0000, v173
	v_add_f32_e32 v151, v151, v153
	v_add_f32_e32 v149, v149, v151
	v_lshlrev_b32_e32 v151, 16, v174
	v_and_b32_e32 v153, 0xffff0000, v174
	v_add_f32_e32 v151, v151, v153
	v_lshlrev_b32_e32 v153, 16, v175
	v_and_b32_e32 v155, 0xffff0000, v175
	v_add_f32_e32 v153, v153, v155
	v_add_f32_e32 v151, v151, v153
	v_add_f32_e32 v149, v149, v151
	v_mov_b32_e32 v151, v149
	s_nop 1
	v_permlane16_swap_b32_e32 v149, v151
	v_add_f32_e32 v149, v149, v151
	ds_read_b128 v[172:175], v170 offset:10240
	v_mov_b32_e32 v151, v149
	s_nop 1
	v_permlane32_swap_b32_e32 v149, v151
	v_add_f32_e32 v149, v149, v151
	v_fmamk_f32 v149, v149, 0x3a000000, v240
	v_rsq_f32_e32 v160, v149
	s_waitcnt lgkmcnt(0)
	v_lshlrev_b32_e32 v149, 16, v172
	v_and_b32_e32 v151, 0xffff0000, v172
	v_add_f32_e32 v149, v149, v151
	v_lshlrev_b32_e32 v151, 16, v173
	v_and_b32_e32 v153, 0xffff0000, v173
	v_add_f32_e32 v151, v151, v153
	v_add_f32_e32 v149, v149, v151
	v_lshlrev_b32_e32 v151, 16, v174
	v_and_b32_e32 v153, 0xffff0000, v174
	v_add_f32_e32 v151, v151, v153
	v_lshlrev_b32_e32 v153, 16, v175
	v_and_b32_e32 v155, 0xffff0000, v175
	v_add_f32_e32 v153, v153, v155
	v_add_f32_e32 v151, v151, v153
	v_add_f32_e32 v149, v149, v151
	v_mov_b32_e32 v151, v149
	s_nop 1
	v_permlane16_swap_b32_e32 v149, v151
	v_add_f32_e32 v149, v149, v151
	ds_read_b128 v[172:175], v170 offset:11264
	v_mov_b32_e32 v151, v149
	s_nop 1
	v_permlane32_swap_b32_e32 v149, v151
	v_add_f32_e32 v149, v149, v151
	v_fmamk_f32 v149, v149, 0x3a000000, v240
	v_rsq_f32_e32 v158, v149
	s_waitcnt lgkmcnt(0)
	v_lshlrev_b32_e32 v149, 16, v172
	v_and_b32_e32 v151, 0xffff0000, v172
	v_add_f32_e32 v149, v149, v151
	v_lshlrev_b32_e32 v151, 16, v173
	v_and_b32_e32 v153, 0xffff0000, v173
	v_add_f32_e32 v151, v151, v153
	v_add_f32_e32 v149, v149, v151
	v_lshlrev_b32_e32 v151, 16, v174
	v_and_b32_e32 v153, 0xffff0000, v174
	v_add_f32_e32 v151, v151, v153
	v_lshlrev_b32_e32 v153, 16, v175
	v_and_b32_e32 v155, 0xffff0000, v175
	v_add_f32_e32 v153, v153, v155
	v_add_f32_e32 v151, v151, v153
	v_add_f32_e32 v149, v149, v151
	v_mov_b32_e32 v151, v149
	v_fmamk_f32 v0, v0, 0x3a000000, v240
	s_nop 0
	v_permlane16_swap_b32_e32 v149, v151
	v_rsq_f32_e32 v0, v0
	v_add_f32_e32 v149, v149, v151
	v_mov_b32_e32 v151, v149
	s_nop 1
	v_permlane32_swap_b32_e32 v149, v151
	v_add_f32_e32 v149, v149, v151
	v_fmamk_f32 v149, v149, 0x3a000000, v240
	v_pk_mul_f32 v[122:123], v[122:123], v[0:1] op_sel_hi:[1,0]
	v_rsq_f32_e32 v162, v149
	v_ashrrev_i32_e32 v149, 31, v148
	v_max_f32_e32 v122, 0, v122
	v_lshl_add_u64 v[172:173], v[164:165], 1, v[138:139]
	v_lshlrev_b64 v[164:165], 14, v[148:149]
	v_pk_mul_f32 v[124:125], v[124:125], v[0:1] op_sel_hi:[1,0]
	v_mul_f32_e32 v149, v122, v122
	v_max_f32_e32 v122, 0, v123
	v_pk_mul_f32 v[126:127], v[126:127], v[0:1] op_sel_hi:[1,0]
	v_mul_f32_e32 v151, v122, v122
	v_max_f32_e32 v122, 0, v124
	v_pk_mul_f32 v[114:115], v[114:115], v[0:1] op_sel_hi:[1,0]
	v_pk_mul_f32 v[128:129], v[128:129], v[0:1] op_sel_hi:[1,0]
	v_max_f32_e32 v126, 0, v126
	v_max_f32_e32 v127, 0, v127
	v_mul_f32_e32 v153, v122, v122
	v_max_f32_e32 v122, 0, v125
	v_pk_mul_f32 v[120:121], v[120:121], v[0:1] op_sel_hi:[1,0]
	v_pk_mul_f32 v[118:119], v[118:119], v[0:1] op_sel_hi:[1,0]
	v_max_f32_e32 v114, 0, v114
	v_lshl_add_u64 v[164:165], v[172:173], 0, v[164:165]
	v_mul_f32_e32 v126, v126, v126
	v_mul_f32_e32 v127, v127, v127
	v_max_f32_e32 v128, 0, v128
	v_max_f32_e32 v129, 0, v129
	v_mul_f32_e32 v125, v122, v122
	v_cvt_pk_bf16_f32 v122, v126, v127
	v_pk_mul_f32 v[116:117], v[116:117], v[0:1] op_sel_hi:[1,0]
	v_max_f32_e32 v0, 0, v118
	v_max_f32_e32 v118, 0, v119
	v_max_f32_e32 v119, 0, v120
	v_max_f32_e32 v120, 0, v121
	v_mul_f32_e32 v121, v114, v114
	v_max_f32_e32 v114, 0, v115
	v_mul_f32_e32 v128, v128, v128
	v_mul_f32_e32 v129, v129, v129
	v_cvt_pk_bf16_f32 v123, v128, v129
	v_cvt_pk_bf16_f32 v124, v149, v151
	v_cvt_pk_bf16_f32 v125, v153, v125
	global_store_dwordx4 v[164:165], v[122:125], off
	v_pk_mul_f32 v[106:107], v[106:107], v[152:153] op_sel_hi:[1,0]
	v_mul_f32_e32 v0, v0, v0
	v_mul_f32_e32 v122, v114, v114
	v_max_f32_e32 v114, 0, v116
	v_mul_f32_e32 v123, v114, v114
	v_max_f32_e32 v114, 0, v117
	v_mul_f32_e32 v118, v118, v118
	v_mul_f32_e32 v117, v114, v114
	v_cvt_pk_bf16_f32 v114, v0, v118
	v_pk_mul_f32 v[112:113], v[112:113], v[152:153] op_sel_hi:[1,0]
	v_pk_mul_f32 v[110:111], v[110:111], v[152:153] op_sel_hi:[1,0]
	v_max_f32_e32 v106, 0, v106
	v_mul_f32_e32 v119, v119, v119
	v_mul_f32_e32 v120, v120, v120
	v_cvt_pk_bf16_f32 v115, v119, v120
	v_cvt_pk_bf16_f32 v116, v121, v122
	v_cvt_pk_bf16_f32 v117, v123, v117
	global_store_dwordx4 v[164:165], v[114:117], off offset:256
	v_pk_mul_f32 v[108:109], v[108:109], v[152:153] op_sel_hi:[1,0]
	v_max_f32_e32 v0, 0, v110
	v_or_b32_e32 v114, 16, v148
	v_max_f32_e32 v110, 0, v111
	v_max_f32_e32 v111, 0, v112
	v_max_f32_e32 v112, 0, v113
	v_mul_f32_e32 v113, v106, v106
	v_max_f32_e32 v106, 0, v107
	v_ashrrev_i32_e32 v115, 31, v114
	v_mul_f32_e32 v116, v106, v106
	v_max_f32_e32 v106, 0, v108
	v_pk_mul_f32 v[98:99], v[98:99], v[152:153] op_sel_hi:[1,0]
	v_lshlrev_b64 v[114:115], 14, v[114:115]
	v_mul_f32_e32 v0, v0, v0
	v_mul_f32_e32 v117, v106, v106
	v_max_f32_e32 v106, 0, v109
	v_pk_mul_f32 v[104:105], v[104:105], v[152:153] op_sel_hi:[1,0]
	v_pk_mul_f32 v[102:103], v[102:103], v[152:153] op_sel_hi:[1,0]
	v_max_f32_e32 v98, 0, v98
	v_lshl_add_u64 v[114:115], v[172:173], 0, v[114:115]
	v_mul_f32_e32 v110, v110, v110
	v_mul_f32_e32 v109, v106, v106
	v_cvt_pk_bf16_f32 v106, v0, v110
	v_pk_mul_f32 v[100:101], v[100:101], v[152:153] op_sel_hi:[1,0]
	v_max_f32_e32 v0, 0, v102
	v_max_f32_e32 v102, 0, v103
	v_max_f32_e32 v103, 0, v104
	v_max_f32_e32 v104, 0, v105
	v_mul_f32_e32 v105, v98, v98
	v_max_f32_e32 v98, 0, v99
	v_mul_f32_e32 v111, v111, v111
	v_mul_f32_e32 v112, v112, v112
	v_cvt_pk_bf16_f32 v107, v111, v112
	v_cvt_pk_bf16_f32 v108, v113, v116
	v_cvt_pk_bf16_f32 v109, v117, v109
	global_store_dwordx4 v[114:115], v[106:109], off
	v_pk_mul_f32 v[90:91], v[90:91], v[150:151] op_sel_hi:[1,0]
	v_mul_f32_e32 v0, v0, v0
	v_mul_f32_e32 v106, v98, v98
	v_max_f32_e32 v98, 0, v100
	v_mul_f32_e32 v107, v98, v98
	v_max_f32_e32 v98, 0, v101
	v_mul_f32_e32 v102, v102, v102
	v_mul_f32_e32 v101, v98, v98
	v_cvt_pk_bf16_f32 v98, v0, v102
	v_pk_mul_f32 v[96:97], v[96:97], v[150:151] op_sel_hi:[1,0]
	v_pk_mul_f32 v[94:95], v[94:95], v[150:151] op_sel_hi:[1,0]
	v_max_f32_e32 v90, 0, v90
	v_mul_f32_e32 v103, v103, v103
	v_mul_f32_e32 v104, v104, v104
	v_cvt_pk_bf16_f32 v99, v103, v104
	v_cvt_pk_bf16_f32 v100, v105, v106
	v_cvt_pk_bf16_f32 v101, v107, v101
	global_store_dwordx4 v[114:115], v[98:101], off offset:256
	v_pk_mul_f32 v[92:93], v[92:93], v[150:151] op_sel_hi:[1,0]
	v_max_f32_e32 v0, 0, v94
	v_or_b32_e32 v98, 32, v148
	v_max_f32_e32 v94, 0, v95
	v_max_f32_e32 v95, 0, v96
	v_max_f32_e32 v96, 0, v97
	v_mul_f32_e32 v97, v90, v90
	v_max_f32_e32 v90, 0, v91
	v_ashrrev_i32_e32 v99, 31, v98
	v_mul_f32_e32 v100, v90, v90
	v_max_f32_e32 v90, 0, v92
	v_pk_mul_f32 v[82:83], v[82:83], v[150:151] op_sel_hi:[1,0]
	v_lshlrev_b64 v[98:99], 14, v[98:99]
	v_mul_f32_e32 v0, v0, v0
	v_mul_f32_e32 v101, v90, v90
	v_max_f32_e32 v90, 0, v93
	v_pk_mul_f32 v[88:89], v[88:89], v[150:151] op_sel_hi:[1,0]
	v_pk_mul_f32 v[86:87], v[86:87], v[150:151] op_sel_hi:[1,0]
	v_max_f32_e32 v82, 0, v82
	v_lshl_add_u64 v[98:99], v[172:173], 0, v[98:99]
	v_mul_f32_e32 v94, v94, v94
	v_mul_f32_e32 v93, v90, v90
	v_cvt_pk_bf16_f32 v90, v0, v94
	v_pk_mul_f32 v[84:85], v[84:85], v[150:151] op_sel_hi:[1,0]
	v_max_f32_e32 v0, 0, v86
	v_max_f32_e32 v86, 0, v87
	v_max_f32_e32 v87, 0, v88
	v_max_f32_e32 v88, 0, v89
	v_mul_f32_e32 v89, v82, v82
	v_max_f32_e32 v82, 0, v83
	v_mul_f32_e32 v95, v95, v95
	v_mul_f32_e32 v96, v96, v96
	v_cvt_pk_bf16_f32 v91, v95, v96
	v_cvt_pk_bf16_f32 v92, v97, v100
	v_cvt_pk_bf16_f32 v93, v101, v93
	global_store_dwordx4 v[98:99], v[90:93], off
	v_pk_mul_f32 v[74:75], v[74:75], v[156:157] op_sel_hi:[1,0]
	v_mul_f32_e32 v0, v0, v0
	v_mul_f32_e32 v90, v82, v82
	v_max_f32_e32 v82, 0, v84
	v_mul_f32_e32 v91, v82, v82
	v_max_f32_e32 v82, 0, v85
	v_mul_f32_e32 v86, v86, v86
	v_mul_f32_e32 v85, v82, v82
	v_cvt_pk_bf16_f32 v82, v0, v86
	v_pk_mul_f32 v[80:81], v[80:81], v[156:157] op_sel_hi:[1,0]
	v_pk_mul_f32 v[78:79], v[78:79], v[156:157] op_sel_hi:[1,0]
	v_max_f32_e32 v74, 0, v74
	v_mul_f32_e32 v87, v87, v87
	v_mul_f32_e32 v88, v88, v88
	v_cvt_pk_bf16_f32 v83, v87, v88
	v_cvt_pk_bf16_f32 v84, v89, v90
	v_cvt_pk_bf16_f32 v85, v91, v85
	global_store_dwordx4 v[98:99], v[82:85], off offset:256
	v_pk_mul_f32 v[76:77], v[76:77], v[156:157] op_sel_hi:[1,0]
	v_max_f32_e32 v0, 0, v78
	v_or_b32_e32 v82, 48, v148
	v_max_f32_e32 v78, 0, v79
	v_max_f32_e32 v79, 0, v80
	v_max_f32_e32 v80, 0, v81
	v_mul_f32_e32 v81, v74, v74
	v_max_f32_e32 v74, 0, v75
	v_ashrrev_i32_e32 v83, 31, v82
	v_mul_f32_e32 v84, v74, v74
	v_max_f32_e32 v74, 0, v76
	v_pk_mul_f32 v[66:67], v[66:67], v[156:157] op_sel_hi:[1,0]
	v_lshlrev_b64 v[82:83], 14, v[82:83]
	v_mul_f32_e32 v0, v0, v0
	v_mul_f32_e32 v85, v74, v74
	v_max_f32_e32 v74, 0, v77
	v_pk_mul_f32 v[72:73], v[72:73], v[156:157] op_sel_hi:[1,0]
	v_pk_mul_f32 v[70:71], v[70:71], v[156:157] op_sel_hi:[1,0]
	v_max_f32_e32 v66, 0, v66
	v_lshl_add_u64 v[82:83], v[172:173], 0, v[82:83]
	v_mul_f32_e32 v78, v78, v78
	v_mul_f32_e32 v77, v74, v74
	v_cvt_pk_bf16_f32 v74, v0, v78
	v_pk_mul_f32 v[68:69], v[68:69], v[156:157] op_sel_hi:[1,0]
	v_max_f32_e32 v0, 0, v70
	v_max_f32_e32 v70, 0, v71
	v_max_f32_e32 v71, 0, v72
	v_max_f32_e32 v72, 0, v73
	v_mul_f32_e32 v73, v66, v66
	v_max_f32_e32 v66, 0, v67
	v_mul_f32_e32 v79, v79, v79
	v_mul_f32_e32 v80, v80, v80
	v_cvt_pk_bf16_f32 v75, v79, v80
	v_cvt_pk_bf16_f32 v76, v81, v84
	v_cvt_pk_bf16_f32 v77, v85, v77
	global_store_dwordx4 v[82:83], v[74:77], off
	v_pk_mul_f32 v[58:59], v[58:59], v[154:155] op_sel_hi:[1,0]
	v_mul_f32_e32 v0, v0, v0
	v_mul_f32_e32 v74, v66, v66
	v_max_f32_e32 v66, 0, v68
	v_mul_f32_e32 v75, v66, v66
	v_max_f32_e32 v66, 0, v69
	v_pk_mul_f32 v[64:65], v[64:65], v[154:155] op_sel_hi:[1,0]
	v_pk_mul_f32 v[62:63], v[62:63], v[154:155] op_sel_hi:[1,0]
	v_max_f32_e32 v58, 0, v58
	v_mul_f32_e32 v70, v70, v70
	v_mul_f32_e32 v71, v71, v71
	v_mul_f32_e32 v72, v72, v72
	v_mul_f32_e32 v69, v66, v66
	v_cvt_pk_bf16_f32 v66, v0, v70
	v_cvt_pk_bf16_f32 v67, v71, v72
	v_cvt_pk_bf16_f32 v68, v73, v74
	v_pk_mul_f32 v[60:61], v[60:61], v[154:155] op_sel_hi:[1,0]
	v_max_f32_e32 v0, 0, v62
	v_max_f32_e32 v62, 0, v63
	v_max_f32_e32 v63, 0, v64
	v_max_f32_e32 v64, 0, v65
	v_mul_f32_e32 v65, v58, v58
	v_max_f32_e32 v58, 0, v59
	v_cvt_pk_bf16_f32 v69, v75, v69
	global_store_dwordx4 v[82:83], v[66:69], off offset:256
	v_mul_f32_e32 v62, v62, v62
	s_mov_b32 s7, 0x200000
	v_mul_f32_e32 v68, v58, v58
	v_max_f32_e32 v58, 0, v60
	v_mul_f32_e32 v69, v58, v58
	v_max_f32_e32 v58, 0, v61
	v_pk_mul_f32 v[50:51], v[50:51], v[154:155] op_sel_hi:[1,0]
	v_mul_f32_e32 v0, v0, v0
	v_mul_f32_e32 v63, v63, v63
	v_mul_f32_e32 v61, v58, v58
	v_cvt_pk_bf16_f32 v58, v0, v62
	v_add_co_u32_e32 v62, vcc, s7, v164
	v_pk_mul_f32 v[56:57], v[56:57], v[154:155] op_sel_hi:[1,0]
	v_pk_mul_f32 v[54:55], v[54:55], v[154:155] op_sel_hi:[1,0]
	v_max_f32_e32 v50, 0, v50
	v_mul_f32_e32 v64, v64, v64
	v_cvt_pk_bf16_f32 v59, v63, v64
	v_addc_co_u32_e32 v63, vcc, 0, v165, vcc
	v_pk_mul_f32 v[52:53], v[52:53], v[154:155] op_sel_hi:[1,0]
	v_max_f32_e32 v0, 0, v54
	v_max_f32_e32 v54, 0, v55
	v_max_f32_e32 v55, 0, v56
	v_max_f32_e32 v56, 0, v57
	v_mul_f32_e32 v57, v50, v50
	v_max_f32_e32 v50, 0, v51
	v_cvt_pk_bf16_f32 v60, v65, v68
	v_cvt_pk_bf16_f32 v61, v69, v61
	global_store_dwordx4 v[62:63], v[58:61], off
	v_pk_mul_f32 v[42:43], v[42:43], v[160:161] op_sel_hi:[1,0]
	v_mul_f32_e32 v0, v0, v0
	v_mul_f32_e32 v58, v50, v50
	v_max_f32_e32 v50, 0, v52
	v_mul_f32_e32 v59, v50, v50
	v_max_f32_e32 v50, 0, v53
	v_pk_mul_f32 v[48:49], v[48:49], v[160:161] op_sel_hi:[1,0]
	v_pk_mul_f32 v[46:47], v[46:47], v[160:161] op_sel_hi:[1,0]
	v_max_f32_e32 v42, 0, v42
	v_lshl_add_u64 v[66:67], v[164:165], 0, s[50:51]
	v_mul_f32_e32 v54, v54, v54
	v_mul_f32_e32 v55, v55, v55
	v_mul_f32_e32 v56, v56, v56
	v_mul_f32_e32 v53, v50, v50
	v_cvt_pk_bf16_f32 v50, v0, v54
	v_cvt_pk_bf16_f32 v51, v55, v56
	v_cvt_pk_bf16_f32 v52, v57, v58
	v_pk_mul_f32 v[44:45], v[44:45], v[160:161] op_sel_hi:[1,0]
	v_max_f32_e32 v0, 0, v46
	v_max_f32_e32 v46, 0, v47
	v_max_f32_e32 v47, 0, v48
	v_max_f32_e32 v48, 0, v49
	v_mul_f32_e32 v49, v42, v42
	v_max_f32_e32 v42, 0, v43
	v_cvt_pk_bf16_f32 v53, v59, v53
	global_store_dwordx4 v[66:67], v[50:53], off offset:256
	v_mul_f32_e32 v46, v46, v46
	s_mov_b32 s7, 0x240000
	v_mul_f32_e32 v52, v42, v42
	v_max_f32_e32 v42, 0, v44
	v_mul_f32_e32 v53, v42, v42
	v_max_f32_e32 v42, 0, v45
	v_pk_mul_f32 v[34:35], v[34:35], v[160:161] op_sel_hi:[1,0]
	v_mul_f32_e32 v0, v0, v0
	v_mul_f32_e32 v47, v47, v47
	v_mul_f32_e32 v45, v42, v42
	v_cvt_pk_bf16_f32 v42, v0, v46
	v_add_co_u32_e32 v46, vcc, s7, v164
	v_pk_mul_f32 v[40:41], v[40:41], v[160:161] op_sel_hi:[1,0]
	v_pk_mul_f32 v[38:39], v[38:39], v[160:161] op_sel_hi:[1,0]
	v_max_f32_e32 v34, 0, v34
	v_mul_f32_e32 v48, v48, v48
	v_cvt_pk_bf16_f32 v43, v47, v48
	v_addc_co_u32_e32 v47, vcc, 0, v165, vcc
	v_pk_mul_f32 v[36:37], v[36:37], v[160:161] op_sel_hi:[1,0]
	v_max_f32_e32 v0, 0, v38
	v_max_f32_e32 v38, 0, v39
	v_max_f32_e32 v39, 0, v40
	v_max_f32_e32 v40, 0, v41
	v_mul_f32_e32 v41, v34, v34
	v_max_f32_e32 v34, 0, v35
	v_cvt_pk_bf16_f32 v44, v49, v52
	v_cvt_pk_bf16_f32 v45, v53, v45
	global_store_dwordx4 v[46:47], v[42:45], off
	v_pk_mul_f32 v[26:27], v[26:27], v[158:159] op_sel_hi:[1,0]
	s_mov_b64 s[10:11], 0x240000
	v_mul_f32_e32 v42, v34, v34
	v_max_f32_e32 v34, 0, v36
	v_mul_f32_e32 v0, v0, v0
	v_mul_f32_e32 v43, v34, v34
	v_max_f32_e32 v34, 0, v37
	v_pk_mul_f32 v[32:33], v[32:33], v[158:159] op_sel_hi:[1,0]
	v_pk_mul_f32 v[30:31], v[30:31], v[158:159] op_sel_hi:[1,0]
	v_max_f32_e32 v26, 0, v26
	v_lshl_add_u64 v[50:51], v[164:165], 0, s[10:11]
	v_mul_f32_e32 v38, v38, v38
	v_mul_f32_e32 v39, v39, v39
	v_mul_f32_e32 v40, v40, v40
	v_mul_f32_e32 v37, v34, v34
	v_cvt_pk_bf16_f32 v34, v0, v38
	v_cvt_pk_bf16_f32 v35, v39, v40
	v_cvt_pk_bf16_f32 v36, v41, v42
	v_pk_mul_f32 v[28:29], v[28:29], v[158:159] op_sel_hi:[1,0]
	v_max_f32_e32 v0, 0, v30
	v_max_f32_e32 v30, 0, v31
	v_max_f32_e32 v31, 0, v32
	v_max_f32_e32 v32, 0, v33
	v_mul_f32_e32 v33, v26, v26
	v_max_f32_e32 v26, 0, v27
	v_cvt_pk_bf16_f32 v37, v43, v37
	global_store_dwordx4 v[50:51], v[34:37], off offset:256
	v_mul_f32_e32 v30, v30, v30
	s_mov_b32 s7, 0x280000
	v_mul_f32_e32 v36, v26, v26
	v_max_f32_e32 v26, 0, v28
	v_mul_f32_e32 v37, v26, v26
	v_max_f32_e32 v26, 0, v29
	v_pk_mul_f32 v[18:19], v[18:19], v[158:159] op_sel_hi:[1,0]
	v_mul_f32_e32 v0, v0, v0
	v_mul_f32_e32 v31, v31, v31
	v_mul_f32_e32 v29, v26, v26
	v_cvt_pk_bf16_f32 v26, v0, v30
	v_add_co_u32_e32 v30, vcc, s7, v164
	v_pk_mul_f32 v[24:25], v[24:25], v[158:159] op_sel_hi:[1,0]
	v_pk_mul_f32 v[22:23], v[22:23], v[158:159] op_sel_hi:[1,0]
	v_max_f32_e32 v18, 0, v18
	v_mul_f32_e32 v32, v32, v32
	v_cvt_pk_bf16_f32 v27, v31, v32
	v_addc_co_u32_e32 v31, vcc, 0, v165, vcc
	v_pk_mul_f32 v[20:21], v[20:21], v[158:159] op_sel_hi:[1,0]
	v_max_f32_e32 v0, 0, v22
	v_max_f32_e32 v22, 0, v23
	v_max_f32_e32 v23, 0, v24
	v_max_f32_e32 v24, 0, v25
	v_mul_f32_e32 v25, v18, v18
	v_max_f32_e32 v18, 0, v19
	v_cvt_pk_bf16_f32 v28, v33, v36
	v_cvt_pk_bf16_f32 v29, v37, v29
	global_store_dwordx4 v[30:31], v[26:29], off
	v_pk_mul_f32 v[10:11], v[10:11], v[162:163] op_sel_hi:[1,0]
	s_mov_b64 s[10:11], 0x280000
	v_mul_f32_e32 v26, v18, v18
	v_max_f32_e32 v18, 0, v20
	v_mul_f32_e32 v0, v0, v0
	v_mul_f32_e32 v27, v18, v18
	v_max_f32_e32 v18, 0, v21
	v_pk_mul_f32 v[16:17], v[16:17], v[162:163] op_sel_hi:[1,0]
	v_pk_mul_f32 v[14:15], v[14:15], v[162:163] op_sel_hi:[1,0]
	v_max_f32_e32 v10, 0, v10
	v_lshl_add_u64 v[34:35], v[164:165], 0, s[10:11]
	v_mul_f32_e32 v22, v22, v22
	v_mul_f32_e32 v23, v23, v23
	v_mul_f32_e32 v24, v24, v24
	v_mul_f32_e32 v21, v18, v18
	v_cvt_pk_bf16_f32 v18, v0, v22
	v_cvt_pk_bf16_f32 v19, v23, v24
	v_cvt_pk_bf16_f32 v20, v25, v26
	v_pk_mul_f32 v[12:13], v[12:13], v[162:163] op_sel_hi:[1,0]
	v_max_f32_e32 v0, 0, v14
	v_max_f32_e32 v14, 0, v15
	v_max_f32_e32 v15, 0, v16
	v_max_f32_e32 v16, 0, v17
	v_mul_f32_e32 v17, v10, v10
	v_max_f32_e32 v10, 0, v11
	v_cvt_pk_bf16_f32 v21, v27, v21
	global_store_dwordx4 v[34:35], v[18:21], off offset:256
	v_mul_f32_e32 v0, v0, v0
	v_mul_f32_e32 v14, v14, v14
	v_mul_f32_e32 v20, v10, v10
	v_max_f32_e32 v10, 0, v12
	v_mul_f32_e32 v21, v10, v10
	v_max_f32_e32 v10, 0, v13
	s_mov_b32 s7, 0x2c0000
	v_pk_mul_f32 v[4:5], v[4:5], v[162:163] op_sel_hi:[1,0]
	v_pk_mul_f32 v[2:3], v[2:3], v[162:163] op_sel_hi:[1,0]
	v_pk_mul_f32 v[6:7], v[6:7], v[162:163] op_sel_hi:[1,0]
	v_mul_f32_e32 v15, v15, v15
	v_mul_f32_e32 v13, v10, v10
	v_cvt_pk_bf16_f32 v10, v0, v14
	v_add_co_u32_e32 v14, vcc, s7, v164
	v_pk_mul_f32 v[8:9], v[8:9], v[162:163] op_sel_hi:[1,0]
	v_max_f32_e32 v0, 0, v2
	v_max_f32_e32 v2, 0, v3
	v_max_f32_e32 v3, 0, v4
	v_max_f32_e32 v4, 0, v5
	v_max_f32_e32 v5, 0, v6
	s_mov_b64 s[10:11], 0x2c0000
	v_mul_f32_e32 v16, v16, v16
	v_cvt_pk_bf16_f32 v11, v15, v16
	v_addc_co_u32_e32 v15, vcc, 0, v165, vcc
	v_mul_f32_e32 v2, v2, v2
	v_mul_f32_e32 v3, v3, v3
	v_mul_f32_e32 v4, v4, v4
	v_mul_f32_e32 v5, v5, v5
	v_max_f32_e32 v6, 0, v7
	v_max_f32_e32 v7, 0, v8
	v_max_f32_e32 v8, 0, v9
	v_lshl_add_u64 v[18:19], v[164:165], 0, s[10:11]
	v_cvt_pk_bf16_f32 v12, v17, v20
	v_cvt_pk_bf16_f32 v13, v21, v13
	global_store_dwordx4 v[14:15], v[10:13], off
	v_mul_f32_e32 v0, v0, v0
	v_mul_f32_e32 v6, v6, v6
	v_mul_f32_e32 v7, v7, v7
	v_mul_f32_e32 v8, v8, v8
	v_cvt_pk_bf16_f32 v2, v0, v2
	v_cvt_pk_bf16_f32 v3, v3, v4
	v_cvt_pk_bf16_f32 v4, v5, v6
	v_cvt_pk_bf16_f32 v5, v7, v8
	s_mov_b64 s[10:11], -1
	s_andn2_b64 vcc, exec, s[4:5]
	global_store_dwordx4 v[18:19], v[2:5], off offset:256
	s_cbranch_vccnz .LBB0_1160
	s_andn2_b64 vcc, exec, s[0:1]
	s_cbranch_vccnz .LBB0_1159
	s_barrier
	s_branch .LBB0_1159

.LBB0_1225:
	s_andn2_b64 vcc, exec, s[0:1]
	s_cbranch_vccnz .LBB0_1257
	v_ashrrev_i32_e32 v7, 31, v0
	v_lshrrev_b32_e32 v7, 26, v7
	v_add_u32_e32 v7, v0, v7
	v_ashrrev_i32_e32 v142, 6, v7
	v_bfe_i32 v7, v0, 27, 1
	v_lshlrev_b32_e32 v6, 4, v0
	v_lshrrev_b32_e32 v7, 22, v7
	v_add_u32_e32 v7, v6, v7
	v_and_b32_e32 v7, 0xfffffc00, v7
	v_sub_u32_e32 v6, v6, v7
	v_lshrrev_b32_e32 v7, 4, v6
	v_bitop3_b32 v6, v7, v6, 32 bitop3:0x6c
	v_ashrrev_i32_e32 v8, 31, v6
	v_lshrrev_b32_e32 v8, 26, v8
	v_add_u32_e32 v8, v6, v8
	v_lshlrev_b32_e32 v7, 3, v142
	v_ashrrev_i32_e32 v143, 6, v8
	v_and_b32_e32 v8, 0xc0, v8
	v_and_b32_e32 v7, -16, v7
	v_sub_u32_e32 v6, v6, v8
	v_add_u32_e32 v7, v143, v7
	v_ashrrev_i16_sdwa v6, v241, sext(v6) dst_sel:DWORD dst_unused:UNUSED_PAD src0_sel:DWORD src1_sel:BYTE_0
	v_lshlrev_b32_e32 v9, 5, v142
	v_bfe_i32 v144, v6, 0, 16
	v_lshlrev_b32_e32 v6, 1, v7
	v_lshrrev_b32_e32 v8, 2, v7
	v_and_b32_e32 v10, 3, v143
	s_mov_b32 s0, 0x3ffe0
	s_ashr_i32 s3, s2, 6
	v_and_b32_e32 v9, 32, v9
	v_and_b32_e32 v6, 24, v6
	v_and_b32_e32 v8, 4, v8
	v_and_or_b32 v10, v7, s0, v10
	s_ashr_i32 s13, s12, 31
	v_or3_b32 v6, v10, v8, v6
	v_add_lshl_u32 v8, v9, v144, 1
	s_lshl_b32 s20, s3, 10
	s_lshl_b64 s[4:5], s[12:13], 22
	v_lshl_add_u32 v210, v6, 14, v8
	v_lshl_add_u64 v[134:135], v[198:199], 0, s[4:5]
	v_mov_b32_e32 v211, v1
	s_add_i32 s21, s20, 0
	v_lshl_add_u64 v[136:137], v[134:135], 0, v[210:211]
	s_add_i32 m0, s21, 0x10000
	v_lshl_add_u32 v204, v7, 14, v8
	s_ashr_i32 s15, s14, 31
	global_load_lds_dwordx4 v[136:137], off
	v_lshl_add_u64 v[138:139], v[136:137], 0, s[84:85]
	s_add_i32 m0, s21, 0x12000
	s_lshl_b64 s[0:1], s[14:15], 22
	global_load_lds_dwordx4 v[138:139], off
	v_lshl_add_u64 v[138:139], v[136:137], 0, s[50:51]
	s_add_i32 m0, s21, 0x14000
	v_lshl_add_u64 v[140:141], v[202:203], 0, s[0:1]
	global_load_lds_dwordx4 v[138:139], off
	v_lshl_add_u64 v[138:139], v[136:137], 0, s[94:95]
	s_add_i32 m0, s21, 0x16000
	v_mov_b32_e32 v205, v1
	global_load_lds_dwordx4 v[138:139], off
	v_lshl_add_u64 v[138:139], v[140:141], 0, v[204:205]
	s_mov_b32 m0, s21
	s_add_i32 s22, s21, 0x2000
	global_load_lds_dwordx4 v[138:139], off
	v_lshl_add_u64 v[146:147], v[138:139], 0, s[84:85]
	s_mov_b32 m0, s22
	s_add_i32 s23, s21, 0x4000
	global_load_lds_dwordx4 v[146:147], off
	v_lshl_add_u64 v[146:147], v[138:139], 0, s[50:51]
	s_mov_b32 m0, s23
	s_add_i32 s24, s21, 0x6000
	global_load_lds_dwordx4 v[146:147], off
	v_lshl_add_u64 v[146:147], v[138:139], 0, s[94:95]
	s_mov_b32 m0, s24
	s_ashr_i32 s4, s2, 8
	global_load_lds_dwordx4 v[146:147], off
	s_cmp_eq_u32 s4, 1
	s_cselect_b64 s[0:1], -1, 0
	s_cmp_lg_u32 s4, 1
	s_cbranch_scc1 .LBB0_1228
	s_barrier

.LBB0_1233:
	s_ashr_i32 s11, s10, 31
	s_lshl_b64 s[16:17], s[10:11], 22
	s_ashr_i32 s9, s8, 31
	v_lshl_add_u64 v[214:215], v[202:203], 0, s[16:17]
	s_lshl_b64 s[16:17], s[8:9], 22
	v_lshl_add_u64 v[216:217], v[198:199], 0, s[16:17]
	v_cndmask_b32_e64 v137, v141, v215, s[6:7]
	v_cndmask_b32_e64 v0, v140, v214, s[6:7]
	v_cndmask_b32_e64 v139, v135, v217, s[6:7]
	v_cndmask_b32_e64 v136, v134, v216, s[6:7]
	v_lshl_add_u64 v[140:141], v[140:141], 0, s[96:97]
	v_lshl_add_u64 v[134:135], v[134:135], 0, s[72:73]
	s_mov_b32 s9, -2
	s_cmpk_eq_i32 s9, 0x7c
	s_cselect_b64 vcc, -1, 0
	s_add_i32 s11, 0, 0x10000
	v_lshl_add_u64 v[142:143], v[140:141], 0, s[48:49]
	v_add_u32_e32 v138, s11, v251
	s_add_i32 s13, 0, 0x14000
	v_cndmask_b32_e32 v207, v143, v137, vcc
	v_cndmask_b32_e32 v206, v142, v0, vcc
	ds_read_b128 v[142:145], v138
	ds_read_b128 v[146:149], v138 offset:1024
	ds_read_b128 v[150:153], v138 offset:2048
	ds_read_b128 v[154:157], v138 offset:3072
	v_add_u32_e32 v138, s13, v251
	ds_read_b128 v[158:161], v138
	ds_read_b128 v[162:165], v138 offset:1024
	ds_read_b128 v[166:169], v138 offset:2048
	ds_read_b128 v[170:173], v138 offset:3072
	v_cndmask_b32_e32 v227, v135, v139, vcc
	v_cndmask_b32_e32 v226, v134, v136, vcc
	v_lshl_add_u64 v[228:229], v[140:141], 0, v[212:213]
	s_add_i32 m0, s21, 0xc000
	ds_read_b128 v[174:177], v253
	ds_read_b128 v[178:181], v253 offset:1024
	ds_read_b128 v[182:185], v253 offset:2048
	ds_read_b128 v[186:189], v253 offset:3072
	ds_read_b128 v[190:193], v253 offset:4096
	ds_read_b128 v[194:197], v253 offset:5120
	ds_read_b128 v[218:221], v253 offset:6144
	ds_read_b128 v[222:225], v253 offset:7168
	global_load_lds_dwordx4 v[228:229], off
	v_lshl_add_u64 v[228:229], v[228:229], 0, s[84:85]
	s_add_i32 m0, s21, 0xe000
	s_nop 0
	global_load_lds_dwordx4 v[228:229], off
	s_waitcnt vmcnt(8)
	s_waitcnt lgkmcnt(0)
	s_barrier
	s_setprio 1
	s_waitcnt lgkmcnt(0)
	v_mfma_f32_16x16x32_bf16 v[126:129], v[142:145], v[174:177], 0
	v_mfma_f32_16x16x32_bf16 v[130:133], v[150:153], v[174:177], 0
	v_mfma_f32_16x16x32_bf16 v[114:117], v[142:145], v[182:185], 0
	v_mfma_f32_16x16x32_bf16 v[110:113], v[150:153], v[182:185], 0
	v_mfma_f32_16x16x32_bf16 v[98:101], v[142:145], v[190:193], 0
	v_mfma_f32_16x16x32_bf16 v[94:97], v[150:153], v[190:193], 0
	v_mfma_f32_16x16x32_bf16 v[82:85], v[142:145], v[218:221], 0
	v_mfma_f32_16x16x32_bf16 v[78:81], v[150:153], v[218:221], 0
	v_mfma_f32_16x16x32_bf16 v[126:129], v[146:149], v[178:181], v[126:129]
	v_mfma_f32_16x16x32_bf16 v[130:133], v[154:157], v[178:181], v[130:133]
	v_mfma_f32_16x16x32_bf16 v[114:117], v[146:149], v[186:189], v[114:117]
	v_mfma_f32_16x16x32_bf16 v[110:113], v[154:157], v[186:189], v[110:113]
	v_mfma_f32_16x16x32_bf16 v[98:101], v[146:149], v[194:197], v[98:101]
	v_mfma_f32_16x16x32_bf16 v[94:97], v[154:157], v[194:197], v[94:97]
	v_mfma_f32_16x16x32_bf16 v[82:85], v[146:149], v[222:225], v[82:85]
	v_mfma_f32_16x16x32_bf16 v[78:81], v[154:157], v[222:225], v[78:81]
	s_setprio 0
	s_setprio 1
	v_mfma_f32_16x16x32_bf16 v[122:125], v[158:161], v[174:177], 0
	v_mfma_f32_16x16x32_bf16 v[118:121], v[166:169], v[174:177], 0
	v_mfma_f32_16x16x32_bf16 v[106:109], v[158:161], v[182:185], 0
	v_mfma_f32_16x16x32_bf16 v[102:105], v[166:169], v[182:185], 0
	v_mfma_f32_16x16x32_bf16 v[90:93], v[158:161], v[190:193], 0
	v_mfma_f32_16x16x32_bf16 v[86:89], v[166:169], v[190:193], 0
	v_mfma_f32_16x16x32_bf16 v[74:77], v[158:161], v[218:221], 0
	v_mfma_f32_16x16x32_bf16 v[70:73], v[166:169], v[218:221], 0
	v_mfma_f32_16x16x32_bf16 v[122:125], v[162:165], v[178:181], v[122:125]
	v_mfma_f32_16x16x32_bf16 v[118:121], v[170:173], v[178:181], v[118:121]
	v_mfma_f32_16x16x32_bf16 v[106:109], v[162:165], v[186:189], v[106:109]
	v_mfma_f32_16x16x32_bf16 v[102:105], v[170:173], v[186:189], v[102:105]
	v_mfma_f32_16x16x32_bf16 v[90:93], v[162:165], v[194:197], v[90:93]
	v_mfma_f32_16x16x32_bf16 v[86:89], v[170:173], v[194:197], v[86:89]
	v_mfma_f32_16x16x32_bf16 v[74:77], v[162:165], v[222:225], v[74:77]
	v_mfma_f32_16x16x32_bf16 v[70:73], v[170:173], v[222:225], v[70:73]
	s_setprio 0
	s_barrier
	s_add_i32 s11, s11, s20
	v_lshl_add_u64 v[226:227], v[226:227], 0, v[210:211]
	s_mov_b32 m0, s11
	ds_read_b128 v[174:177], v253 offset:16384
	ds_read_b128 v[178:181], v253 offset:17408
	ds_read_b128 v[182:185], v253 offset:18432
	ds_read_b128 v[186:189], v253 offset:19456
	ds_read_b128 v[190:193], v253 offset:20480
	ds_read_b128 v[194:197], v253 offset:21504
	ds_read_b128 v[218:221], v253 offset:22528
	ds_read_b128 v[222:225], v253 offset:23552
	global_load_lds_dwordx4 v[226:227], off
	v_lshl_add_u64 v[228:229], v[226:227], 0, s[84:85]
	s_add_i32 m0, s11, 0x2000
	s_add_i32 s11, s13, s20
	global_load_lds_dwordx4 v[228:229], off
	v_lshl_add_u64 v[228:229], v[226:227], 0, s[50:51]
	s_mov_b32 m0, s11
	v_lshl_add_u64 v[206:207], v[206:207], 0, v[204:205]
	global_load_lds_dwordx4 v[228:229], off
	v_lshl_add_u64 v[228:229], v[226:227], 0, s[94:95]
	s_add_i32 m0, s11, 0x2000
	s_nop 0
	global_load_lds_dwordx4 v[228:229], off
	s_mov_b32 m0, s21
	v_lshl_add_u64 v[228:229], v[206:207], 0, s[84:85]
	global_load_lds_dwordx4 v[206:207], off
	s_mov_b32 m0, s22
	s_nop 0
	global_load_lds_dwordx4 v[228:229], off
	s_waitcnt vmcnt(8)
	s_waitcnt lgkmcnt(0)
	s_barrier
	s_setprio 1
	s_waitcnt lgkmcnt(0)
	v_mfma_f32_16x16x32_bf16 v[66:69], v[142:145], v[174:177], 0
	v_mfma_f32_16x16x32_bf16 v[62:65], v[150:153], v[174:177], 0
	v_mfma_f32_16x16x32_bf16 v[50:53], v[142:145], v[182:185], 0
	v_mfma_f32_16x16x32_bf16 v[46:49], v[150:153], v[182:185], 0
	v_mfma_f32_16x16x32_bf16 v[34:37], v[142:145], v[190:193], 0
	v_mfma_f32_16x16x32_bf16 v[30:33], v[150:153], v[190:193], 0
	v_mfma_f32_16x16x32_bf16 v[18:21], v[142:145], v[218:221], 0
	v_mfma_f32_16x16x32_bf16 v[14:17], v[150:153], v[218:221], 0
	v_mfma_f32_16x16x32_bf16 v[66:69], v[146:149], v[178:181], v[66:69]
	v_mfma_f32_16x16x32_bf16 v[62:65], v[154:157], v[178:181], v[62:65]
	v_mfma_f32_16x16x32_bf16 v[50:53], v[146:149], v[186:189], v[50:53]
	v_mfma_f32_16x16x32_bf16 v[46:49], v[154:157], v[186:189], v[46:49]
	v_mfma_f32_16x16x32_bf16 v[34:37], v[146:149], v[194:197], v[34:37]
	v_mfma_f32_16x16x32_bf16 v[30:33], v[154:157], v[194:197], v[30:33]
	v_mfma_f32_16x16x32_bf16 v[18:21], v[146:149], v[222:225], v[18:21]
	v_mfma_f32_16x16x32_bf16 v[14:17], v[154:157], v[222:225], v[14:17]
	s_setprio 0
	s_setprio 1
	v_mfma_f32_16x16x32_bf16 v[58:61], v[158:161], v[174:177], 0
	v_mfma_f32_16x16x32_bf16 v[54:57], v[166:169], v[174:177], 0
	v_mfma_f32_16x16x32_bf16 v[42:45], v[158:161], v[182:185], 0
	v_mfma_f32_16x16x32_bf16 v[38:41], v[166:169], v[182:185], 0
	v_mfma_f32_16x16x32_bf16 v[26:29], v[158:161], v[190:193], 0
	v_mfma_f32_16x16x32_bf16 v[22:25], v[166:169], v[190:193], 0
	v_mfma_f32_16x16x32_bf16 v[10:13], v[158:161], v[218:221], 0
	v_mfma_f32_16x16x32_bf16 v[6:9], v[166:169], v[218:221], 0
	v_mfma_f32_16x16x32_bf16 v[58:61], v[162:165], v[178:181], v[58:61]
	v_mfma_f32_16x16x32_bf16 v[54:57], v[170:173], v[178:181], v[54:57]
	v_mfma_f32_16x16x32_bf16 v[42:45], v[162:165], v[186:189], v[42:45]
	v_mfma_f32_16x16x32_bf16 v[38:41], v[170:173], v[186:189], v[38:41]
	v_mfma_f32_16x16x32_bf16 v[26:29], v[162:165], v[194:197], v[26:29]
	v_mfma_f32_16x16x32_bf16 v[22:25], v[170:173], v[194:197], v[22:25]
	v_mfma_f32_16x16x32_bf16 v[10:13], v[162:165], v[222:225], v[10:13]
	v_mfma_f32_16x16x32_bf16 v[6:9], v[170:173], v[222:225], v[6:9]
	s_setprio 0
	s_barrier
	s_add_i32 s11, 0, 0x18000
	v_add_u32_e32 v138, s11, v251
	s_add_i32 s13, 0, 0x1c000
	ds_read_b128 v[142:145], v138
	ds_read_b128 v[146:149], v138 offset:1024
	ds_read_b128 v[150:153], v138 offset:2048
	ds_read_b128 v[154:157], v138 offset:3072
	v_add_u32_e32 v138, s13, v251
	ds_read_b128 v[158:161], v138
	ds_read_b128 v[162:165], v138 offset:1024
	ds_read_b128 v[166:169], v138 offset:2048
	ds_read_b128 v[170:173], v138 offset:3072
	s_mov_b32 m0, s23
	v_lshl_add_u64 v[228:229], v[206:207], 0, s[50:51]
	ds_read_b128 v[174:177], v253 offset:32768
	ds_read_b128 v[178:181], v253 offset:33792
	ds_read_b128 v[182:185], v253 offset:34816
	ds_read_b128 v[186:189], v253 offset:35840
	ds_read_b128 v[190:193], v253 offset:36864
	ds_read_b128 v[194:197], v253 offset:37888
	ds_read_b128 v[218:221], v253 offset:38912
	ds_read_b128 v[222:225], v253 offset:39936
	global_load_lds_dwordx4 v[228:229], off
	v_lshl_add_u64 v[228:229], v[206:207], 0, s[94:95]
	s_mov_b32 m0, s24
	s_nop 0
	global_load_lds_dwordx4 v[228:229], off
	s_waitcnt vmcnt(8)
	s_waitcnt lgkmcnt(0)
	s_barrier
	s_setprio 1
	s_waitcnt lgkmcnt(0)
	v_mfma_f32_16x16x32_bf16 v[126:129], v[142:145], v[174:177], v[126:129]
	v_mfma_f32_16x16x32_bf16 v[130:133], v[150:153], v[174:177], v[130:133]
	v_mfma_f32_16x16x32_bf16 v[114:117], v[142:145], v[182:185], v[114:117]
	v_mfma_f32_16x16x32_bf16 v[110:113], v[150:153], v[182:185], v[110:113]
	v_mfma_f32_16x16x32_bf16 v[98:101], v[142:145], v[190:193], v[98:101]
	v_mfma_f32_16x16x32_bf16 v[94:97], v[150:153], v[190:193], v[94:97]
	v_mfma_f32_16x16x32_bf16 v[82:85], v[142:145], v[218:221], v[82:85]
	v_mfma_f32_16x16x32_bf16 v[78:81], v[150:153], v[218:221], v[78:81]
	v_mfma_f32_16x16x32_bf16 v[126:129], v[146:149], v[178:181], v[126:129]
	v_mfma_f32_16x16x32_bf16 v[130:133], v[154:157], v[178:181], v[130:133]
	v_mfma_f32_16x16x32_bf16 v[114:117], v[146:149], v[186:189], v[114:117]
	v_mfma_f32_16x16x32_bf16 v[110:113], v[154:157], v[186:189], v[110:113]
	v_mfma_f32_16x16x32_bf16 v[98:101], v[146:149], v[194:197], v[98:101]
	v_mfma_f32_16x16x32_bf16 v[94:97], v[154:157], v[194:197], v[94:97]
	v_mfma_f32_16x16x32_bf16 v[82:85], v[146:149], v[222:225], v[82:85]
	v_mfma_f32_16x16x32_bf16 v[78:81], v[154:157], v[222:225], v[78:81]
	s_setprio 0
	s_setprio 1
	v_mfma_f32_16x16x32_bf16 v[122:125], v[158:161], v[174:177], v[122:125]
	v_mfma_f32_16x16x32_bf16 v[118:121], v[166:169], v[174:177], v[118:121]
	v_mfma_f32_16x16x32_bf16 v[106:109], v[158:161], v[182:185], v[106:109]
	v_mfma_f32_16x16x32_bf16 v[102:105], v[166:169], v[182:185], v[102:105]
	v_mfma_f32_16x16x32_bf16 v[90:93], v[158:161], v[190:193], v[90:93]
	v_mfma_f32_16x16x32_bf16 v[86:89], v[166:169], v[190:193], v[86:89]
	v_mfma_f32_16x16x32_bf16 v[74:77], v[158:161], v[218:221], v[74:77]
	v_mfma_f32_16x16x32_bf16 v[70:73], v[166:169], v[218:221], v[70:73]
	v_mfma_f32_16x16x32_bf16 v[122:125], v[162:165], v[178:181], v[122:125]
	v_mfma_f32_16x16x32_bf16 v[118:121], v[170:173], v[178:181], v[118:121]
	v_mfma_f32_16x16x32_bf16 v[106:109], v[162:165], v[186:189], v[106:109]
	v_mfma_f32_16x16x32_bf16 v[102:105], v[170:173], v[186:189], v[102:105]
	v_mfma_f32_16x16x32_bf16 v[90:93], v[162:165], v[194:197], v[90:93]
	v_mfma_f32_16x16x32_bf16 v[86:89], v[170:173], v[194:197], v[86:89]
	v_mfma_f32_16x16x32_bf16 v[74:77], v[162:165], v[222:225], v[74:77]
	v_mfma_f32_16x16x32_bf16 v[70:73], v[170:173], v[222:225], v[70:73]
	s_setprio 0
	s_barrier
	s_add_i32 s11, s11, s20
	v_lshl_add_u64 v[228:229], v[226:227], 0, s[62:63]
	s_mov_b32 m0, s11
	ds_read_b128 v[174:177], v253 offset:49152
	ds_read_b128 v[178:181], v253 offset:50176
	ds_read_b128 v[182:185], v253 offset:51200
	ds_read_b128 v[186:189], v253 offset:52224
	ds_read_b128 v[190:193], v253 offset:53248
	ds_read_b128 v[194:197], v253 offset:54272
	ds_read_b128 v[218:221], v253 offset:55296
	ds_read_b128 v[222:225], v253 offset:56320
	global_load_lds_dwordx4 v[228:229], off
	v_lshl_add_u64 v[228:229], v[226:227], 0, s[70:71]
	s_add_i32 m0, s11, 0x2000
	s_add_i32 s11, s13, s20
	global_load_lds_dwordx4 v[228:229], off
	v_lshl_add_u64 v[228:229], v[226:227], 0, s[96:97]
	s_mov_b32 m0, s11
	v_lshl_add_u64 v[226:227], v[226:227], 0, s[88:89]
	global_load_lds_dwordx4 v[228:229], off
	s_add_i32 m0, s11, 0x2000
	s_nop 0
	global_load_lds_dwordx4 v[226:227], off
	v_lshl_add_u64 v[226:227], v[206:207], 0, s[62:63]
	s_mov_b32 m0, s25
	v_lshl_add_u64 v[206:207], v[206:207], 0, s[70:71]
	global_load_lds_dwordx4 v[226:227], off
	s_mov_b32 m0, s26
	s_nop 0
	global_load_lds_dwordx4 v[206:207], off
	s_waitcnt vmcnt(8)
	s_waitcnt lgkmcnt(0)
	s_barrier
	s_setprio 1
	s_waitcnt lgkmcnt(0)
	v_mfma_f32_16x16x32_bf16 v[66:69], v[142:145], v[174:177], v[66:69]
	v_mfma_f32_16x16x32_bf16 v[62:65], v[150:153], v[174:177], v[62:65]
	v_mfma_f32_16x16x32_bf16 v[50:53], v[142:145], v[182:185], v[50:53]
	v_mfma_f32_16x16x32_bf16 v[46:49], v[150:153], v[182:185], v[46:49]
	v_mfma_f32_16x16x32_bf16 v[34:37], v[142:145], v[190:193], v[34:37]
	v_mfma_f32_16x16x32_bf16 v[30:33], v[150:153], v[190:193], v[30:33]
	v_mfma_f32_16x16x32_bf16 v[18:21], v[142:145], v[218:221], v[18:21]
	v_mfma_f32_16x16x32_bf16 v[14:17], v[150:153], v[218:221], v[14:17]
	v_mfma_f32_16x16x32_bf16 v[66:69], v[146:149], v[178:181], v[66:69]
	v_mfma_f32_16x16x32_bf16 v[62:65], v[154:157], v[178:181], v[62:65]
	v_mfma_f32_16x16x32_bf16 v[50:53], v[146:149], v[186:189], v[50:53]
	v_mfma_f32_16x16x32_bf16 v[46:49], v[154:157], v[186:189], v[46:49]
	v_mfma_f32_16x16x32_bf16 v[34:37], v[146:149], v[194:197], v[34:37]
	v_mfma_f32_16x16x32_bf16 v[30:33], v[154:157], v[194:197], v[30:33]
	v_mfma_f32_16x16x32_bf16 v[18:21], v[146:149], v[222:225], v[18:21]
	v_mfma_f32_16x16x32_bf16 v[14:17], v[154:157], v[222:225], v[14:17]
	s_setprio 0
	s_setprio 1
	v_mfma_f32_16x16x32_bf16 v[58:61], v[158:161], v[174:177], v[58:61]
	v_mfma_f32_16x16x32_bf16 v[54:57], v[166:169], v[174:177], v[54:57]
	v_mfma_f32_16x16x32_bf16 v[42:45], v[158:161], v[182:185], v[42:45]
	v_mfma_f32_16x16x32_bf16 v[38:41], v[166:169], v[182:185], v[38:41]
	v_mfma_f32_16x16x32_bf16 v[26:29], v[158:161], v[190:193], v[26:29]
	v_mfma_f32_16x16x32_bf16 v[22:25], v[166:169], v[190:193], v[22:25]
	v_mfma_f32_16x16x32_bf16 v[10:13], v[158:161], v[218:221], v[10:13]
	v_mfma_f32_16x16x32_bf16 v[6:9], v[166:169], v[218:221], v[6:9]
	v_mfma_f32_16x16x32_bf16 v[58:61], v[162:165], v[178:181], v[58:61]
	v_mfma_f32_16x16x32_bf16 v[54:57], v[170:173], v[178:181], v[54:57]
	v_mfma_f32_16x16x32_bf16 v[42:45], v[162:165], v[186:189], v[42:45]
	v_mfma_f32_16x16x32_bf16 v[38:41], v[170:173], v[186:189], v[38:41]
	v_mfma_f32_16x16x32_bf16 v[26:29], v[162:165], v[194:197], v[26:29]
	v_mfma_f32_16x16x32_bf16 v[22:25], v[170:173], v[194:197], v[22:25]
	v_mfma_f32_16x16x32_bf16 v[10:13], v[162:165], v[222:225], v[10:13]
	v_mfma_f32_16x16x32_bf16 v[6:9], v[170:173], v[222:225], v[6:9]
	s_setprio 0
	s_barrier
	s_add_i32 s9, s9, 2
	v_lshl_add_u64 v[140:141], v[140:141], 0, s[72:73]
	s_cmpk_gt_u32 s9, 0x7d
	v_lshl_add_u64 v[134:135], v[134:135], 0, s[72:73]

.LBB0_1253:
	s_or_b64 exec, exec, s[14:15]
	s_andn2_b64 vcc, exec, s[6:7]
	s_mov_b64 s[6:7], -1
	s_cbranch_vccnz .LBB0_1230
	s_andn2_b64 vcc, exec, s[0:1]
	s_cbranch_vccnz .LBB0_1229
	s_barrier
	s_branch .LBB0_1229

.LBB0_1258:
	s_and_b64 vcc, exec, s[0:1]
	s_cbranch_vccz .LBB0_1275
	v_mbcnt_lo_u32_b32 v0, -1, 0
	v_mbcnt_hi_u32_b32 v0, -1, v0
	s_cmpk_gt_i32 s19, 0x4ff
	v_add_u32_e32 v0, s81, v0
	s_nop 0
	v_readfirstlane_b32 s3, v0
	s_cbranch_scc1 .LBB0_1275
	v_bfe_i32 v5, v0, 27, 1
	v_lshlrev_b32_e32 v4, 4, v0
	v_lshrrev_b32_e32 v5, 22, v5
	v_add_u32_e32 v5, v4, v5
	v_and_b32_e32 v5, 0xfffffc00, v5
	v_sub_u32_e32 v4, v4, v5
	v_lshrrev_b32_e32 v5, 4, v4
	v_ashrrev_i32_e32 v6, 31, v0
	v_bitop3_b32 v4, v5, v4, 32 bitop3:0x6c
	v_lshrrev_b32_e32 v6, 26, v6
	v_ashrrev_i32_e32 v5, 31, v4
	v_add_u32_e32 v6, v0, v6
	v_lshrrev_b32_e32 v5, 26, v5
	v_ashrrev_i32_e32 v141, 6, v6
	v_add_u32_e32 v5, v4, v5
	v_lshlrev_b32_e32 v6, 3, v141
	v_ashrrev_i32_e32 v140, 6, v5
	v_and_b32_e32 v6, -16, v6
	v_add_u32_e32 v6, v140, v6
	v_and_b32_e32 v7, 3, v140
	s_mov_b32 s0, 0x3ffe0
	s_ashr_i32 s15, s19, 31
	v_and_or_b32 v7, v6, s0, v7
	s_lshr_b32 s0, s15, 29
	s_add_i32 s0, s19, s0
	s_ashr_i32 s4, s3, 6
	s_ashr_i32 s1, s0, 3
	s_and_b32 s0, s0, -8
	s_ashr_i32 s5, s3, 8
	s_lshl_b32 s14, s4, 10
	s_sub_i32 s0, s19, s0
	s_cmp_lt_i32 s0, 0
	s_movk_i32 s2, 0xa1
	s_cselect_b32 s2, s2, 0xa0
	s_mul_i32 s0, s0, s2
	s_add_i32 s0, s0, s1
	s_ashr_i32 s1, s0, 31
	s_lshr_b32 s1, s1, 26
	s_add_i32 s1, s0, s1
	s_ashr_i32 s2, s1, 5
	s_and_b32 s1, s1, 0xffe0
	s_sub_i32 s0, s0, s1
	s_bfe_i32 s1, s0, 0x80000
	s_bfe_u32 s1, s1, 0x3000c
	s_add_i32 s1, s0, s1
	v_lshrrev_b32_e32 v8, 2, v6
	v_lshlrev_b32_e32 v9, 1, v6
	v_and_b32_e32 v5, 0xc0, v5
	s_lshl_b32 s6, s2, 2
	s_bfe_i32 s2, s1, 0x80000
	s_and_b32 s1, s1, 0xfc
	v_and_b32_e32 v8, 4, v8
	v_and_b32_e32 v9, 24, v9
	v_sub_u32_e32 v4, v4, v5
	s_sext_i32_i16 s2, s2
	s_sub_i32 s0, s0, s1
	v_or3_b32 v7, v7, v8, v9
	v_lshlrev_b32_e32 v8, 5, v141
	v_ashrrev_i16_sdwa v4, v241, sext(v4) dst_sel:DWORD dst_unused:UNUSED_PAD src0_sel:DWORD src1_sel:BYTE_0
	s_lshr_b32 s2, s2, 2
	s_sext_i32_i8 s0, s0
	v_and_b32_e32 v8, 32, v8
	v_bfe_i32 v142, v4, 0, 16
	s_add_i32 s10, s6, s0
	s_bfe_i64 s[6:7], s[2:3], 0x100000
	v_add_lshl_u32 v4, v8, v142, 1
	s_lshl_b64 s[6:7], s[6:7], 22
	v_lshl_add_u32 v192, v7, 14, v4
	v_lshl_add_u64 v[132:133], v[198:199], 0, s[6:7]
	v_mov_b32_e32 v193, v1
	s_add_i32 s16, s14, 0
	v_lshl_add_u64 v[134:135], v[132:133], 0, v[192:193]
	s_add_i32 m0, s16, 0x10000
	v_lshl_add_u32 v194, v6, 14, v4
	s_ashr_i32 s11, s10, 31
	global_load_lds_dwordx4 v[134:135], off
	v_lshl_add_u64 v[136:137], v[134:135], 0, s[84:85]
	s_add_i32 m0, s16, 0x12000
	s_lshl_b64 s[0:1], s[10:11], 22
	global_load_lds_dwordx4 v[136:137], off
	v_lshl_add_u64 v[136:137], v[134:135], 0, s[50:51]
	s_add_i32 m0, s16, 0x14000
	v_lshl_add_u64 v[138:139], v[202:203], 0, s[0:1]
	global_load_lds_dwordx4 v[136:137], off
	v_lshl_add_u64 v[136:137], v[134:135], 0, s[94:95]
	s_add_i32 m0, s16, 0x16000
	v_mov_b32_e32 v195, v1
	global_load_lds_dwordx4 v[136:137], off
	v_lshl_add_u64 v[136:137], v[138:139], 0, v[194:195]
	s_mov_b32 m0, s16
	s_add_i32 s17, s16, 0x2000
	global_load_lds_dwordx4 v[136:137], off
	v_lshl_add_u64 v[144:145], v[136:137], 0, s[84:85]
	s_mov_b32 m0, s17
	s_add_i32 s20, s16, 0x4000
	global_load_lds_dwordx4 v[144:145], off
	v_lshl_add_u64 v[144:145], v[136:137], 0, s[50:51]
	s_mov_b32 m0, s20
	s_add_i32 s21, s16, 0x6000
	global_load_lds_dwordx4 v[144:145], off
	v_lshl_add_u64 v[144:145], v[136:137], 0, s[94:95]
	s_mov_b32 m0, s21
	s_cmp_eq_u32 s5, 1
	global_load_lds_dwordx4 v[144:145], off
	s_cselect_b64 s[0:1], -1, 0
	s_cmp_lg_u32 s5, 1
	s_cbranch_scc1 .LBB0_1262
	s_barrier

.LBB0_1267:
	s_ashr_i32 s9, s8, 31
	s_lshl_b64 s[12:13], s[8:9], 22
	s_ashr_i32 s7, s6, 31
	v_lshl_add_u64 v[204:205], v[202:203], 0, s[12:13]
	s_lshl_b64 s[12:13], s[6:7], 22
	v_lshl_add_u64 v[210:211], v[198:199], 0, s[12:13]
	v_cndmask_b32_e64 v135, v139, v205, s[4:5]
	v_cndmask_b32_e64 v0, v138, v204, s[4:5]
	v_cndmask_b32_e64 v137, v133, v211, s[4:5]
	v_cndmask_b32_e64 v134, v132, v210, s[4:5]
	v_lshl_add_u64 v[138:139], v[138:139], 0, s[96:97]
	v_lshl_add_u64 v[132:133], v[132:133], 0, s[72:73]
	s_mov_b32 s7, -2
	s_cmpk_eq_i32 s7, 0x7c
	s_cselect_b64 vcc, -1, 0
	s_add_i32 s9, 0, 0x10000
	v_lshl_add_u64 v[140:141], v[138:139], 0, s[48:49]
	v_add_u32_e32 v136, s9, v231
	s_add_i32 s12, 0, 0x14000
	v_cndmask_b32_e32 v207, v141, v135, vcc
	v_cndmask_b32_e32 v206, v140, v0, vcc
	ds_read_b128 v[140:143], v136
	ds_read_b128 v[144:147], v136 offset:1024
	ds_read_b128 v[148:151], v136 offset:2048
	ds_read_b128 v[152:155], v136 offset:3072
	v_add_u32_e32 v136, s12, v231
	ds_read_b128 v[156:159], v136
	ds_read_b128 v[160:163], v136 offset:1024
	ds_read_b128 v[164:167], v136 offset:2048
	ds_read_b128 v[168:171], v136 offset:3072
	v_cndmask_b32_e32 v209, v133, v137, vcc
	v_cndmask_b32_e32 v208, v132, v134, vcc
	v_lshl_add_u64 v[224:225], v[138:139], 0, v[196:197]
	s_add_i32 m0, s16, 0xc000
	ds_read_b128 v[172:175], v233
	ds_read_b128 v[176:179], v233 offset:1024
	ds_read_b128 v[180:183], v233 offset:2048
	ds_read_b128 v[184:187], v233 offset:3072
	ds_read_b128 v[188:191], v233 offset:4096
	ds_read_b128 v[212:215], v233 offset:5120
	ds_read_b128 v[216:219], v233 offset:6144
	ds_read_b128 v[220:223], v233 offset:7168
	global_load_lds_dwordx4 v[224:225], off
	v_lshl_add_u64 v[224:225], v[224:225], 0, s[84:85]
	s_add_i32 m0, s16, 0xe000
	s_nop 0
	global_load_lds_dwordx4 v[224:225], off
	s_waitcnt vmcnt(8)
	s_waitcnt lgkmcnt(0)
	s_barrier
	s_setprio 1
	s_waitcnt lgkmcnt(0)
	v_mfma_f32_16x16x32_bf16 v[124:127], v[140:143], v[172:175], 0
	v_mfma_f32_16x16x32_bf16 v[128:131], v[148:151], v[172:175], 0
	v_mfma_f32_16x16x32_bf16 v[112:115], v[140:143], v[180:183], 0
	v_mfma_f32_16x16x32_bf16 v[108:111], v[148:151], v[180:183], 0
	v_mfma_f32_16x16x32_bf16 v[96:99], v[140:143], v[188:191], 0
	v_mfma_f32_16x16x32_bf16 v[92:95], v[148:151], v[188:191], 0
	v_mfma_f32_16x16x32_bf16 v[80:83], v[140:143], v[216:219], 0
	v_mfma_f32_16x16x32_bf16 v[76:79], v[148:151], v[216:219], 0
	v_mfma_f32_16x16x32_bf16 v[124:127], v[144:147], v[176:179], v[124:127]
	v_mfma_f32_16x16x32_bf16 v[128:131], v[152:155], v[176:179], v[128:131]
	v_mfma_f32_16x16x32_bf16 v[112:115], v[144:147], v[184:187], v[112:115]
	v_mfma_f32_16x16x32_bf16 v[108:111], v[152:155], v[184:187], v[108:111]
	v_mfma_f32_16x16x32_bf16 v[96:99], v[144:147], v[212:215], v[96:99]
	v_mfma_f32_16x16x32_bf16 v[92:95], v[152:155], v[212:215], v[92:95]
	v_mfma_f32_16x16x32_bf16 v[80:83], v[144:147], v[220:223], v[80:83]
	v_mfma_f32_16x16x32_bf16 v[76:79], v[152:155], v[220:223], v[76:79]
	s_setprio 0
	s_setprio 1
	v_mfma_f32_16x16x32_bf16 v[120:123], v[156:159], v[172:175], 0
	v_mfma_f32_16x16x32_bf16 v[116:119], v[164:167], v[172:175], 0
	v_mfma_f32_16x16x32_bf16 v[104:107], v[156:159], v[180:183], 0
	v_mfma_f32_16x16x32_bf16 v[100:103], v[164:167], v[180:183], 0
	v_mfma_f32_16x16x32_bf16 v[88:91], v[156:159], v[188:191], 0
	v_mfma_f32_16x16x32_bf16 v[84:87], v[164:167], v[188:191], 0
	v_mfma_f32_16x16x32_bf16 v[72:75], v[156:159], v[216:219], 0
	v_mfma_f32_16x16x32_bf16 v[68:71], v[164:167], v[216:219], 0
	v_mfma_f32_16x16x32_bf16 v[120:123], v[160:163], v[176:179], v[120:123]
	v_mfma_f32_16x16x32_bf16 v[116:119], v[168:171], v[176:179], v[116:119]
	v_mfma_f32_16x16x32_bf16 v[104:107], v[160:163], v[184:187], v[104:107]
	v_mfma_f32_16x16x32_bf16 v[100:103], v[168:171], v[184:187], v[100:103]
	v_mfma_f32_16x16x32_bf16 v[88:91], v[160:163], v[212:215], v[88:91]
	v_mfma_f32_16x16x32_bf16 v[84:87], v[168:171], v[212:215], v[84:87]
	v_mfma_f32_16x16x32_bf16 v[72:75], v[160:163], v[220:223], v[72:75]
	v_mfma_f32_16x16x32_bf16 v[68:71], v[168:171], v[220:223], v[68:71]
	s_setprio 0
	s_barrier
	s_add_i32 s9, s9, s14
	v_lshl_add_u64 v[208:209], v[208:209], 0, v[192:193]
	s_mov_b32 m0, s9
	ds_read_b128 v[172:175], v233 offset:16384
	ds_read_b128 v[176:179], v233 offset:17408
	ds_read_b128 v[180:183], v233 offset:18432
	ds_read_b128 v[184:187], v233 offset:19456
	ds_read_b128 v[188:191], v233 offset:20480
	ds_read_b128 v[212:215], v233 offset:21504
	ds_read_b128 v[216:219], v233 offset:22528
	ds_read_b128 v[220:223], v233 offset:23552
	global_load_lds_dwordx4 v[208:209], off
	v_lshl_add_u64 v[224:225], v[208:209], 0, s[84:85]
	s_add_i32 m0, s9, 0x2000
	s_add_i32 s9, s12, s14
	global_load_lds_dwordx4 v[224:225], off
	v_lshl_add_u64 v[224:225], v[208:209], 0, s[50:51]
	s_mov_b32 m0, s9
	v_lshl_add_u64 v[206:207], v[206:207], 0, v[194:195]
	global_load_lds_dwordx4 v[224:225], off
	v_lshl_add_u64 v[224:225], v[208:209], 0, s[94:95]
	s_add_i32 m0, s9, 0x2000
	s_nop 0
	global_load_lds_dwordx4 v[224:225], off
	s_mov_b32 m0, s16
	v_lshl_add_u64 v[224:225], v[206:207], 0, s[84:85]
	global_load_lds_dwordx4 v[206:207], off
	s_mov_b32 m0, s17
	s_nop 0
	global_load_lds_dwordx4 v[224:225], off
	s_waitcnt vmcnt(8)
	s_waitcnt lgkmcnt(0)
	s_barrier
	s_setprio 1
	s_waitcnt lgkmcnt(0)
	v_mfma_f32_16x16x32_bf16 v[64:67], v[140:143], v[172:175], 0
	v_mfma_f32_16x16x32_bf16 v[60:63], v[148:151], v[172:175], 0
	v_mfma_f32_16x16x32_bf16 v[48:51], v[140:143], v[180:183], 0
	v_mfma_f32_16x16x32_bf16 v[44:47], v[148:151], v[180:183], 0
	v_mfma_f32_16x16x32_bf16 v[32:35], v[140:143], v[188:191], 0
	v_mfma_f32_16x16x32_bf16 v[28:31], v[148:151], v[188:191], 0
	v_mfma_f32_16x16x32_bf16 v[16:19], v[140:143], v[216:219], 0
	v_mfma_f32_16x16x32_bf16 v[12:15], v[148:151], v[216:219], 0
	v_mfma_f32_16x16x32_bf16 v[64:67], v[144:147], v[176:179], v[64:67]
	v_mfma_f32_16x16x32_bf16 v[60:63], v[152:155], v[176:179], v[60:63]
	v_mfma_f32_16x16x32_bf16 v[48:51], v[144:147], v[184:187], v[48:51]
	v_mfma_f32_16x16x32_bf16 v[44:47], v[152:155], v[184:187], v[44:47]
	v_mfma_f32_16x16x32_bf16 v[32:35], v[144:147], v[212:215], v[32:35]
	v_mfma_f32_16x16x32_bf16 v[28:31], v[152:155], v[212:215], v[28:31]
	v_mfma_f32_16x16x32_bf16 v[16:19], v[144:147], v[220:223], v[16:19]
	v_mfma_f32_16x16x32_bf16 v[12:15], v[152:155], v[220:223], v[12:15]
	s_setprio 0
	s_setprio 1
	v_mfma_f32_16x16x32_bf16 v[56:59], v[156:159], v[172:175], 0
	v_mfma_f32_16x16x32_bf16 v[52:55], v[164:167], v[172:175], 0
	v_mfma_f32_16x16x32_bf16 v[40:43], v[156:159], v[180:183], 0
	v_mfma_f32_16x16x32_bf16 v[36:39], v[164:167], v[180:183], 0
	v_mfma_f32_16x16x32_bf16 v[24:27], v[156:159], v[188:191], 0
	v_mfma_f32_16x16x32_bf16 v[20:23], v[164:167], v[188:191], 0
	v_mfma_f32_16x16x32_bf16 v[8:11], v[156:159], v[216:219], 0
	v_mfma_f32_16x16x32_bf16 v[4:7], v[164:167], v[216:219], 0
	v_mfma_f32_16x16x32_bf16 v[56:59], v[160:163], v[176:179], v[56:59]
	v_mfma_f32_16x16x32_bf16 v[52:55], v[168:171], v[176:179], v[52:55]
	v_mfma_f32_16x16x32_bf16 v[40:43], v[160:163], v[184:187], v[40:43]
	v_mfma_f32_16x16x32_bf16 v[36:39], v[168:171], v[184:187], v[36:39]
	v_mfma_f32_16x16x32_bf16 v[24:27], v[160:163], v[212:215], v[24:27]
	v_mfma_f32_16x16x32_bf16 v[20:23], v[168:171], v[212:215], v[20:23]
	v_mfma_f32_16x16x32_bf16 v[8:11], v[160:163], v[220:223], v[8:11]
	v_mfma_f32_16x16x32_bf16 v[4:7], v[168:171], v[220:223], v[4:7]
	s_setprio 0
	s_barrier
	s_add_i32 s9, 0, 0x18000
	v_add_u32_e32 v136, s9, v231
	s_add_i32 s12, 0, 0x1c000
	ds_read_b128 v[140:143], v136
	ds_read_b128 v[144:147], v136 offset:1024
	ds_read_b128 v[148:151], v136 offset:2048
	ds_read_b128 v[152:155], v136 offset:3072
	v_add_u32_e32 v136, s12, v231
	ds_read_b128 v[156:159], v136
	ds_read_b128 v[160:163], v136 offset:1024
	ds_read_b128 v[164:167], v136 offset:2048
	ds_read_b128 v[168:171], v136 offset:3072
	s_mov_b32 m0, s20
	v_lshl_add_u64 v[224:225], v[206:207], 0, s[50:51]
	ds_read_b128 v[172:175], v233 offset:32768
	ds_read_b128 v[176:179], v233 offset:33792
	ds_read_b128 v[180:183], v233 offset:34816
	ds_read_b128 v[184:187], v233 offset:35840
	ds_read_b128 v[188:191], v233 offset:36864
	ds_read_b128 v[212:215], v233 offset:37888
	ds_read_b128 v[216:219], v233 offset:38912
	ds_read_b128 v[220:223], v233 offset:39936
	global_load_lds_dwordx4 v[224:225], off
	v_lshl_add_u64 v[224:225], v[206:207], 0, s[94:95]
	s_mov_b32 m0, s21
	s_nop 0
	global_load_lds_dwordx4 v[224:225], off
	s_waitcnt vmcnt(8)
	s_waitcnt lgkmcnt(0)
	s_barrier
	s_setprio 1
	s_waitcnt lgkmcnt(0)
	v_mfma_f32_16x16x32_bf16 v[124:127], v[140:143], v[172:175], v[124:127]
	v_mfma_f32_16x16x32_bf16 v[128:131], v[148:151], v[172:175], v[128:131]
	v_mfma_f32_16x16x32_bf16 v[112:115], v[140:143], v[180:183], v[112:115]
	v_mfma_f32_16x16x32_bf16 v[108:111], v[148:151], v[180:183], v[108:111]
	v_mfma_f32_16x16x32_bf16 v[96:99], v[140:143], v[188:191], v[96:99]
	v_mfma_f32_16x16x32_bf16 v[92:95], v[148:151], v[188:191], v[92:95]
	v_mfma_f32_16x16x32_bf16 v[80:83], v[140:143], v[216:219], v[80:83]
	v_mfma_f32_16x16x32_bf16 v[76:79], v[148:151], v[216:219], v[76:79]
	v_mfma_f32_16x16x32_bf16 v[124:127], v[144:147], v[176:179], v[124:127]
	v_mfma_f32_16x16x32_bf16 v[128:131], v[152:155], v[176:179], v[128:131]
	v_mfma_f32_16x16x32_bf16 v[112:115], v[144:147], v[184:187], v[112:115]
	v_mfma_f32_16x16x32_bf16 v[108:111], v[152:155], v[184:187], v[108:111]
	v_mfma_f32_16x16x32_bf16 v[96:99], v[144:147], v[212:215], v[96:99]
	v_mfma_f32_16x16x32_bf16 v[92:95], v[152:155], v[212:215], v[92:95]
	v_mfma_f32_16x16x32_bf16 v[80:83], v[144:147], v[220:223], v[80:83]
	v_mfma_f32_16x16x32_bf16 v[76:79], v[152:155], v[220:223], v[76:79]
	s_setprio 0
	s_setprio 1
	v_mfma_f32_16x16x32_bf16 v[120:123], v[156:159], v[172:175], v[120:123]
	v_mfma_f32_16x16x32_bf16 v[116:119], v[164:167], v[172:175], v[116:119]
	v_mfma_f32_16x16x32_bf16 v[104:107], v[156:159], v[180:183], v[104:107]
	v_mfma_f32_16x16x32_bf16 v[100:103], v[164:167], v[180:183], v[100:103]
	v_mfma_f32_16x16x32_bf16 v[88:91], v[156:159], v[188:191], v[88:91]
	v_mfma_f32_16x16x32_bf16 v[84:87], v[164:167], v[188:191], v[84:87]
	v_mfma_f32_16x16x32_bf16 v[72:75], v[156:159], v[216:219], v[72:75]
	v_mfma_f32_16x16x32_bf16 v[68:71], v[164:167], v[216:219], v[68:71]
	v_mfma_f32_16x16x32_bf16 v[120:123], v[160:163], v[176:179], v[120:123]
	v_mfma_f32_16x16x32_bf16 v[116:119], v[168:171], v[176:179], v[116:119]
	v_mfma_f32_16x16x32_bf16 v[104:107], v[160:163], v[184:187], v[104:107]
	v_mfma_f32_16x16x32_bf16 v[100:103], v[168:171], v[184:187], v[100:103]
	v_mfma_f32_16x16x32_bf16 v[88:91], v[160:163], v[212:215], v[88:91]
	v_mfma_f32_16x16x32_bf16 v[84:87], v[168:171], v[212:215], v[84:87]
	v_mfma_f32_16x16x32_bf16 v[72:75], v[160:163], v[220:223], v[72:75]
	v_mfma_f32_16x16x32_bf16 v[68:71], v[168:171], v[220:223], v[68:71]
	s_setprio 0
	s_barrier
	s_add_i32 s9, s9, s14
	v_lshl_add_u64 v[224:225], v[208:209], 0, s[62:63]
	s_mov_b32 m0, s9
	ds_read_b128 v[172:175], v233 offset:49152
	ds_read_b128 v[176:179], v233 offset:50176
	ds_read_b128 v[180:183], v233 offset:51200
	ds_read_b128 v[184:187], v233 offset:52224
	ds_read_b128 v[188:191], v233 offset:53248
	ds_read_b128 v[212:215], v233 offset:54272
	ds_read_b128 v[216:219], v233 offset:55296
	ds_read_b128 v[220:223], v233 offset:56320
	global_load_lds_dwordx4 v[224:225], off
	v_lshl_add_u64 v[224:225], v[208:209], 0, s[70:71]
	s_add_i32 m0, s9, 0x2000
	s_add_i32 s9, s12, s14
	global_load_lds_dwordx4 v[224:225], off
	v_lshl_add_u64 v[224:225], v[208:209], 0, s[96:97]
	s_mov_b32 m0, s9
	v_lshl_add_u64 v[208:209], v[208:209], 0, s[88:89]
	global_load_lds_dwordx4 v[224:225], off
	s_add_i32 m0, s9, 0x2000
	s_nop 0
	global_load_lds_dwordx4 v[208:209], off
	v_lshl_add_u64 v[208:209], v[206:207], 0, s[62:63]
	s_mov_b32 m0, s22
	v_lshl_add_u64 v[206:207], v[206:207], 0, s[70:71]
	global_load_lds_dwordx4 v[208:209], off
	s_mov_b32 m0, s23
	s_nop 0
	global_load_lds_dwordx4 v[206:207], off
	s_waitcnt vmcnt(8)
	s_waitcnt lgkmcnt(0)
	s_barrier
	s_setprio 1
	s_waitcnt lgkmcnt(0)
	v_mfma_f32_16x16x32_bf16 v[64:67], v[140:143], v[172:175], v[64:67]
	v_mfma_f32_16x16x32_bf16 v[60:63], v[148:151], v[172:175], v[60:63]
	v_mfma_f32_16x16x32_bf16 v[48:51], v[140:143], v[180:183], v[48:51]
	v_mfma_f32_16x16x32_bf16 v[44:47], v[148:151], v[180:183], v[44:47]
	v_mfma_f32_16x16x32_bf16 v[32:35], v[140:143], v[188:191], v[32:35]
	v_mfma_f32_16x16x32_bf16 v[28:31], v[148:151], v[188:191], v[28:31]
	v_mfma_f32_16x16x32_bf16 v[16:19], v[140:143], v[216:219], v[16:19]
	v_mfma_f32_16x16x32_bf16 v[12:15], v[148:151], v[216:219], v[12:15]
	v_mfma_f32_16x16x32_bf16 v[64:67], v[144:147], v[176:179], v[64:67]
	v_mfma_f32_16x16x32_bf16 v[60:63], v[152:155], v[176:179], v[60:63]
	v_mfma_f32_16x16x32_bf16 v[48:51], v[144:147], v[184:187], v[48:51]
	v_mfma_f32_16x16x32_bf16 v[44:47], v[152:155], v[184:187], v[44:47]
	v_mfma_f32_16x16x32_bf16 v[32:35], v[144:147], v[212:215], v[32:35]
	v_mfma_f32_16x16x32_bf16 v[28:31], v[152:155], v[212:215], v[28:31]
	v_mfma_f32_16x16x32_bf16 v[16:19], v[144:147], v[220:223], v[16:19]
	v_mfma_f32_16x16x32_bf16 v[12:15], v[152:155], v[220:223], v[12:15]
	s_setprio 0
	s_setprio 1
	v_mfma_f32_16x16x32_bf16 v[56:59], v[156:159], v[172:175], v[56:59]
	v_mfma_f32_16x16x32_bf16 v[52:55], v[164:167], v[172:175], v[52:55]
	v_mfma_f32_16x16x32_bf16 v[40:43], v[156:159], v[180:183], v[40:43]
	v_mfma_f32_16x16x32_bf16 v[36:39], v[164:167], v[180:183], v[36:39]
	v_mfma_f32_16x16x32_bf16 v[24:27], v[156:159], v[188:191], v[24:27]
	v_mfma_f32_16x16x32_bf16 v[20:23], v[164:167], v[188:191], v[20:23]
	v_mfma_f32_16x16x32_bf16 v[8:11], v[156:159], v[216:219], v[8:11]
	v_mfma_f32_16x16x32_bf16 v[4:7], v[164:167], v[216:219], v[4:7]
	v_mfma_f32_16x16x32_bf16 v[56:59], v[160:163], v[176:179], v[56:59]
	v_mfma_f32_16x16x32_bf16 v[52:55], v[168:171], v[176:179], v[52:55]
	v_mfma_f32_16x16x32_bf16 v[40:43], v[160:163], v[184:187], v[40:43]
	v_mfma_f32_16x16x32_bf16 v[36:39], v[168:171], v[184:187], v[36:39]
	v_mfma_f32_16x16x32_bf16 v[24:27], v[160:163], v[212:215], v[24:27]
	v_mfma_f32_16x16x32_bf16 v[20:23], v[168:171], v[212:215], v[20:23]
	v_mfma_f32_16x16x32_bf16 v[8:11], v[160:163], v[220:223], v[8:11]
	v_mfma_f32_16x16x32_bf16 v[4:7], v[168:171], v[220:223], v[4:7]
	s_setprio 0
	s_barrier
	s_add_i32 s7, s7, 2
	v_lshl_add_u64 v[138:139], v[138:139], 0, s[72:73]
	s_cmpk_gt_u32 s7, 0x7d
	v_lshl_add_u64 v[132:133], v[132:133], 0, s[72:73]

.LBB0_1271:
	v_lshl_add_u32 v228, s10, 8, v230
	v_lshl_or_b32 v226, s11, 8, v232
	v_ashrrev_i32_e32 v227, 31, v226
	v_ashrrev_i32_e32 v229, 31, v228
	v_lshl_add_u64 v[132:133], v[226:227], 1, v[200:201]
	v_lshlrev_b64 v[134:135], 12, v[228:229]
	v_lshl_add_u64 v[134:135], v[132:133], 0, v[134:135]
	global_load_dwordx4 v[234:237], v[134:135], off
	global_load_dwordx4 v[188:191], v[134:135], off offset:256
	v_or_b32_e32 v224, 16, v228
	v_ashrrev_i32_e32 v225, 31, v224
	v_lshlrev_b64 v[134:135], 12, v[224:225]
	v_lshl_add_u64 v[134:135], v[132:133], 0, v[134:135]
	global_load_dwordx4 v[184:187], v[134:135], off
	global_load_dwordx4 v[180:183], v[134:135], off offset:256
	v_or_b32_e32 v222, 32, v228
	v_ashrrev_i32_e32 v223, 31, v222
	v_lshlrev_b64 v[134:135], 12, v[222:223]
	v_lshl_add_u64 v[134:135], v[132:133], 0, v[134:135]
	global_load_dwordx4 v[176:179], v[134:135], off
	global_load_dwordx4 v[172:175], v[134:135], off offset:256
	v_or_b32_e32 v220, 48, v228
	v_ashrrev_i32_e32 v221, 31, v220
	v_lshlrev_b64 v[134:135], 12, v[220:221]
	v_lshl_add_u64 v[134:135], v[132:133], 0, v[134:135]
	global_load_dwordx4 v[168:171], v[134:135], off
	global_load_dwordx4 v[164:167], v[134:135], off offset:256
	v_add_u32_e32 v218, 0x80, v228
	v_ashrrev_i32_e32 v219, 31, v218
	v_lshlrev_b64 v[134:135], 12, v[218:219]
	v_lshl_add_u64 v[134:135], v[132:133], 0, v[134:135]
	global_load_dwordx4 v[160:163], v[134:135], off
	global_load_dwordx4 v[156:159], v[134:135], off offset:256
	v_add_u32_e32 v216, 0x90, v228
	v_ashrrev_i32_e32 v217, 31, v216
	v_lshlrev_b64 v[134:135], 12, v[216:217]
	v_lshl_add_u64 v[134:135], v[132:133], 0, v[134:135]
	global_load_dwordx4 v[152:155], v[134:135], off
	global_load_dwordx4 v[148:151], v[134:135], off offset:256
	v_add_u32_e32 v214, 0xa0, v228
	v_ashrrev_i32_e32 v215, 31, v214
	v_lshlrev_b64 v[134:135], 12, v[214:215]
	v_lshl_add_u64 v[134:135], v[132:133], 0, v[134:135]
	global_load_dwordx4 v[144:147], v[134:135], off
	global_load_dwordx4 v[136:139], v[134:135], off offset:256
	v_add_u32_e32 v212, 0xb0, v228
	v_ashrrev_i32_e32 v213, 31, v212
	v_lshlrev_b64 v[134:135], 12, v[212:213]
	v_lshl_add_u64 v[132:133], v[132:133], 0, v[134:135]
	global_load_dwordx4 v[140:143], v[132:133], off
	s_nop 0
	global_load_dwordx4 v[132:135], v[132:133], off offset:256
	s_mov_b64 s[10:11], -1
	s_andn2_b64 vcc, exec, s[4:5]
	s_waitcnt vmcnt(0)
	v_lshlrev_b32_e32 v206, 16, v234
	v_and_b32_e32 v207, 0xffff0000, v234
	v_lshlrev_b32_e32 v208, 16, v235
	v_and_b32_e32 v209, 0xffff0000, v235
	v_pk_add_f32 v[234:235], v[124:125], v[206:207]
	v_lshlrev_b64 v[124:125], 13, v[228:229]
	v_lshlrev_b32_e32 v238, 16, v236
	v_and_b32_e32 v239, 0xffff0000, v236
	v_lshlrev_b32_e32 v250, 16, v237
	v_and_b32_e32 v251, 0xffff0000, v237
	v_pk_add_f32 v[236:237], v[126:127], v[208:209]
	v_lshl_add_u64 v[126:127], v[2:3], 0, v[124:125]
	v_lshlrev_b64 v[124:125], 2, v[226:227]
	v_pk_add_f32 v[130:131], v[130:131], v[250:251]
	v_pk_add_f32 v[128:129], v[128:129], v[238:239]
	v_lshl_add_u64 v[126:127], v[126:127], 0, v[124:125]
	global_store_dwordx4 v[126:127], v[234:237], off
	global_store_dwordx4 v[126:127], v[128:131], off offset:16
	s_nop 1
	v_lshlrev_b32_e32 v128, 16, v188
	v_and_b32_e32 v129, 0xffff0000, v188
	v_lshlrev_b32_e32 v130, 16, v189
	v_and_b32_e32 v131, 0xffff0000, v189
	v_lshlrev_b32_e32 v188, 16, v190
	v_and_b32_e32 v189, 0xffff0000, v190
	v_lshlrev_b32_e32 v190, 16, v191
	v_and_b32_e32 v191, 0xffff0000, v191
	v_pk_add_f32 v[122:123], v[122:123], v[130:131]
	v_pk_add_f32 v[120:121], v[120:121], v[128:129]
	v_pk_add_f32 v[116:117], v[116:117], v[188:189]
	v_pk_add_f32 v[118:119], v[118:119], v[190:191]
	global_store_dwordx4 v[126:127], v[120:123], off offset:512
	global_store_dwordx4 v[126:127], v[116:119], off offset:528
	s_nop 0
	v_lshlrev_b32_e32 v120, 16, v186
	v_lshlrev_b32_e32 v116, 16, v184
	v_and_b32_e32 v117, 0xffff0000, v184
	v_pk_add_f32 v[112:113], v[112:113], v[116:117]
	v_lshlrev_b64 v[116:117], 13, v[224:225]
	v_lshlrev_b32_e32 v118, 16, v185
	v_and_b32_e32 v119, 0xffff0000, v185
	v_and_b32_e32 v121, 0xffff0000, v186
	v_lshlrev_b32_e32 v122, 16, v187
	v_and_b32_e32 v123, 0xffff0000, v187
	v_lshl_add_u64 v[116:117], v[2:3], 0, v[116:117]
	v_pk_add_f32 v[114:115], v[114:115], v[118:119]
	v_pk_add_f32 v[110:111], v[110:111], v[122:123]
	v_pk_add_f32 v[108:109], v[108:109], v[120:121]
	v_lshl_add_u64 v[116:117], v[116:117], 0, v[124:125]
	global_store_dwordx4 v[116:117], v[112:115], off
	global_store_dwordx4 v[116:117], v[108:111], off offset:16
	s_nop 0
	v_lshlrev_b32_e32 v112, 16, v182
	v_lshlrev_b32_e32 v108, 16, v180
	v_and_b32_e32 v109, 0xffff0000, v180
	v_lshlrev_b32_e32 v110, 16, v181
	v_and_b32_e32 v111, 0xffff0000, v181
	v_and_b32_e32 v113, 0xffff0000, v182
	v_lshlrev_b32_e32 v114, 16, v183
	v_and_b32_e32 v115, 0xffff0000, v183
	v_pk_add_f32 v[106:107], v[106:107], v[110:111]
	v_pk_add_f32 v[104:105], v[104:105], v[108:109]
	v_pk_add_f32 v[100:101], v[100:101], v[112:113]
	v_pk_add_f32 v[102:103], v[102:103], v[114:115]
	global_store_dwordx4 v[116:117], v[104:107], off offset:512
	global_store_dwordx4 v[116:117], v[100:103], off offset:528
	s_nop 0
	v_lshlrev_b32_e32 v104, 16, v178
	v_lshlrev_b32_e32 v100, 16, v176
	v_and_b32_e32 v101, 0xffff0000, v176
	v_pk_add_f32 v[96:97], v[96:97], v[100:101]
	v_lshlrev_b64 v[100:101], 13, v[222:223]
	v_lshlrev_b32_e32 v102, 16, v177
	v_and_b32_e32 v103, 0xffff0000, v177
	v_and_b32_e32 v105, 0xffff0000, v178
	v_lshlrev_b32_e32 v106, 16, v179
	v_and_b32_e32 v107, 0xffff0000, v179
	v_lshl_add_u64 v[100:101], v[2:3], 0, v[100:101]
	v_pk_add_f32 v[98:99], v[98:99], v[102:103]
	v_pk_add_f32 v[94:95], v[94:95], v[106:107]
	v_pk_add_f32 v[92:93], v[92:93], v[104:105]
	v_lshl_add_u64 v[100:101], v[100:101], 0, v[124:125]
	global_store_dwordx4 v[100:101], v[96:99], off
	global_store_dwordx4 v[100:101], v[92:95], off offset:16
	s_nop 0
	v_lshlrev_b32_e32 v96, 16, v174
	v_lshlrev_b32_e32 v92, 16, v172
	v_and_b32_e32 v93, 0xffff0000, v172
	v_lshlrev_b32_e32 v94, 16, v173
	v_and_b32_e32 v95, 0xffff0000, v173
	v_and_b32_e32 v97, 0xffff0000, v174
	v_lshlrev_b32_e32 v98, 16, v175
	v_and_b32_e32 v99, 0xffff0000, v175
	v_pk_add_f32 v[90:91], v[90:91], v[94:95]
	v_pk_add_f32 v[88:89], v[88:89], v[92:93]
	v_pk_add_f32 v[84:85], v[84:85], v[96:97]
	v_pk_add_f32 v[86:87], v[86:87], v[98:99]
	global_store_dwordx4 v[100:101], v[88:91], off offset:512
	global_store_dwordx4 v[100:101], v[84:87], off offset:528
	s_nop 0
	v_lshlrev_b32_e32 v88, 16, v170
	v_lshlrev_b32_e32 v84, 16, v168
	v_and_b32_e32 v85, 0xffff0000, v168
	v_pk_add_f32 v[80:81], v[80:81], v[84:85]
	v_lshlrev_b64 v[84:85], 13, v[220:221]
	v_lshlrev_b32_e32 v86, 16, v169
	v_and_b32_e32 v87, 0xffff0000, v169
	v_and_b32_e32 v89, 0xffff0000, v170
	v_lshlrev_b32_e32 v90, 16, v171
	v_and_b32_e32 v91, 0xffff0000, v171
	v_lshl_add_u64 v[84:85], v[2:3], 0, v[84:85]
	v_pk_add_f32 v[82:83], v[82:83], v[86:87]
	v_pk_add_f32 v[78:79], v[78:79], v[90:91]
	v_pk_add_f32 v[76:77], v[76:77], v[88:89]
	v_lshl_add_u64 v[84:85], v[84:85], 0, v[124:125]
	global_store_dwordx4 v[84:85], v[80:83], off
	global_store_dwordx4 v[84:85], v[76:79], off offset:16
	s_nop 0
	v_lshlrev_b32_e32 v80, 16, v166
	v_lshlrev_b32_e32 v76, 16, v164
	v_and_b32_e32 v77, 0xffff0000, v164
	v_lshlrev_b32_e32 v78, 16, v165
	v_and_b32_e32 v79, 0xffff0000, v165
	v_and_b32_e32 v81, 0xffff0000, v166
	v_lshlrev_b32_e32 v82, 16, v167
	v_and_b32_e32 v83, 0xffff0000, v167
	v_pk_add_f32 v[74:75], v[74:75], v[78:79]
	v_pk_add_f32 v[72:73], v[72:73], v[76:77]
	v_pk_add_f32 v[68:69], v[68:69], v[80:81]
	v_pk_add_f32 v[70:71], v[70:71], v[82:83]
	global_store_dwordx4 v[84:85], v[72:75], off offset:512
	global_store_dwordx4 v[84:85], v[68:71], off offset:528
	s_nop 0
	v_lshlrev_b32_e32 v72, 16, v162
	v_lshlrev_b32_e32 v68, 16, v160
	v_and_b32_e32 v69, 0xffff0000, v160
	v_pk_add_f32 v[64:65], v[64:65], v[68:69]
	v_lshlrev_b64 v[68:69], 13, v[218:219]
	v_lshlrev_b32_e32 v70, 16, v161
	v_and_b32_e32 v71, 0xffff0000, v161
	v_and_b32_e32 v73, 0xffff0000, v162
	v_lshlrev_b32_e32 v74, 16, v163
	v_and_b32_e32 v75, 0xffff0000, v163
	v_lshl_add_u64 v[68:69], v[2:3], 0, v[68:69]
	v_pk_add_f32 v[66:67], v[66:67], v[70:71]
	v_pk_add_f32 v[62:63], v[62:63], v[74:75]
	v_pk_add_f32 v[60:61], v[60:61], v[72:73]
	v_lshl_add_u64 v[68:69], v[68:69], 0, v[124:125]
	global_store_dwordx4 v[68:69], v[64:67], off
	global_store_dwordx4 v[68:69], v[60:63], off offset:16
	s_nop 0
	v_lshlrev_b32_e32 v64, 16, v158
	v_lshlrev_b32_e32 v60, 16, v156
	v_and_b32_e32 v61, 0xffff0000, v156
	v_lshlrev_b32_e32 v62, 16, v157
	v_and_b32_e32 v63, 0xffff0000, v157
	v_and_b32_e32 v65, 0xffff0000, v158
	v_lshlrev_b32_e32 v66, 16, v159
	v_and_b32_e32 v67, 0xffff0000, v159
	v_pk_add_f32 v[58:59], v[58:59], v[62:63]
	v_pk_add_f32 v[56:57], v[56:57], v[60:61]
	v_pk_add_f32 v[52:53], v[52:53], v[64:65]
	v_pk_add_f32 v[54:55], v[54:55], v[66:67]
	global_store_dwordx4 v[68:69], v[56:59], off offset:512
	global_store_dwordx4 v[68:69], v[52:55], off offset:528
	s_nop 0
	v_lshlrev_b32_e32 v56, 16, v154
	v_lshlrev_b32_e32 v52, 16, v152
	v_and_b32_e32 v53, 0xffff0000, v152
	v_pk_add_f32 v[48:49], v[48:49], v[52:53]
	v_lshlrev_b64 v[52:53], 13, v[216:217]
	v_lshlrev_b32_e32 v54, 16, v153
	v_and_b32_e32 v55, 0xffff0000, v153
	v_and_b32_e32 v57, 0xffff0000, v154
	v_lshlrev_b32_e32 v58, 16, v155
	v_and_b32_e32 v59, 0xffff0000, v155
	v_lshl_add_u64 v[52:53], v[2:3], 0, v[52:53]
	v_pk_add_f32 v[50:51], v[50:51], v[54:55]
	v_pk_add_f32 v[46:47], v[46:47], v[58:59]
	v_pk_add_f32 v[44:45], v[44:45], v[56:57]
	v_lshl_add_u64 v[52:53], v[52:53], 0, v[124:125]
	global_store_dwordx4 v[52:53], v[48:51], off
	global_store_dwordx4 v[52:53], v[44:47], off offset:16
	s_nop 0
	v_lshlrev_b32_e32 v48, 16, v150
	v_lshlrev_b32_e32 v44, 16, v148
	v_and_b32_e32 v45, 0xffff0000, v148
	v_lshlrev_b32_e32 v46, 16, v149
	v_and_b32_e32 v47, 0xffff0000, v149
	v_and_b32_e32 v49, 0xffff0000, v150
	v_lshlrev_b32_e32 v50, 16, v151
	v_and_b32_e32 v51, 0xffff0000, v151
	v_pk_add_f32 v[42:43], v[42:43], v[46:47]
	v_pk_add_f32 v[40:41], v[40:41], v[44:45]
	v_pk_add_f32 v[36:37], v[36:37], v[48:49]
	v_pk_add_f32 v[38:39], v[38:39], v[50:51]
	global_store_dwordx4 v[52:53], v[40:43], off offset:512
	global_store_dwordx4 v[52:53], v[36:39], off offset:528
	s_nop 0
	v_lshlrev_b32_e32 v40, 16, v146
	v_lshlrev_b32_e32 v36, 16, v144
	v_and_b32_e32 v37, 0xffff0000, v144
	v_pk_add_f32 v[32:33], v[32:33], v[36:37]
	v_lshlrev_b64 v[36:37], 13, v[214:215]
	v_lshlrev_b32_e32 v38, 16, v145
	v_and_b32_e32 v39, 0xffff0000, v145
	v_and_b32_e32 v41, 0xffff0000, v146
	v_lshlrev_b32_e32 v42, 16, v147
	v_and_b32_e32 v43, 0xffff0000, v147
	v_lshl_add_u64 v[36:37], v[2:3], 0, v[36:37]
	v_pk_add_f32 v[34:35], v[34:35], v[38:39]
	v_pk_add_f32 v[30:31], v[30:31], v[42:43]
	v_pk_add_f32 v[28:29], v[28:29], v[40:41]
	v_lshl_add_u64 v[36:37], v[36:37], 0, v[124:125]
	global_store_dwordx4 v[36:37], v[32:35], off
	global_store_dwordx4 v[36:37], v[28:31], off offset:16
	s_nop 0
	v_lshlrev_b32_e32 v32, 16, v138
	v_lshlrev_b32_e32 v28, 16, v136
	v_and_b32_e32 v29, 0xffff0000, v136
	v_lshlrev_b32_e32 v30, 16, v137
	v_and_b32_e32 v31, 0xffff0000, v137
	v_and_b32_e32 v33, 0xffff0000, v138
	v_lshlrev_b32_e32 v34, 16, v139
	v_and_b32_e32 v35, 0xffff0000, v139
	v_pk_add_f32 v[26:27], v[26:27], v[30:31]
	v_pk_add_f32 v[24:25], v[24:25], v[28:29]
	v_pk_add_f32 v[20:21], v[20:21], v[32:33]
	v_pk_add_f32 v[22:23], v[22:23], v[34:35]
	global_store_dwordx4 v[36:37], v[24:27], off offset:512
	global_store_dwordx4 v[36:37], v[20:23], off offset:528
	s_nop 0
	v_lshlrev_b32_e32 v24, 16, v142
	v_lshlrev_b32_e32 v20, 16, v140
	v_and_b32_e32 v21, 0xffff0000, v140
	v_pk_add_f32 v[16:17], v[16:17], v[20:21]
	v_lshlrev_b64 v[20:21], 13, v[212:213]
	v_lshlrev_b32_e32 v22, 16, v141
	v_and_b32_e32 v23, 0xffff0000, v141
	v_and_b32_e32 v25, 0xffff0000, v142
	v_lshlrev_b32_e32 v26, 16, v143
	v_and_b32_e32 v27, 0xffff0000, v143
	v_lshl_add_u64 v[20:21], v[2:3], 0, v[20:21]
	v_pk_add_f32 v[18:19], v[18:19], v[22:23]
	v_pk_add_f32 v[14:15], v[14:15], v[26:27]
	v_pk_add_f32 v[12:13], v[12:13], v[24:25]
	v_lshl_add_u64 v[20:21], v[20:21], 0, v[124:125]
	global_store_dwordx4 v[20:21], v[16:19], off
	global_store_dwordx4 v[20:21], v[12:15], off offset:16
	s_nop 0
	v_lshlrev_b32_e32 v16, 16, v134
	v_lshlrev_b32_e32 v12, 16, v132
	v_and_b32_e32 v13, 0xffff0000, v132
	v_lshlrev_b32_e32 v14, 16, v133
	v_and_b32_e32 v15, 0xffff0000, v133
	v_and_b32_e32 v17, 0xffff0000, v134
	v_lshlrev_b32_e32 v18, 16, v135
	v_and_b32_e32 v19, 0xffff0000, v135
	v_pk_add_f32 v[10:11], v[10:11], v[14:15]
	v_pk_add_f32 v[8:9], v[8:9], v[12:13]
	v_pk_add_f32 v[6:7], v[6:7], v[18:19]
	v_pk_add_f32 v[4:5], v[4:5], v[16:17]
	global_store_dwordx4 v[20:21], v[8:11], off offset:512
	global_store_dwordx4 v[20:21], v[4:7], off offset:528
	s_cbranch_vccnz .LBB0_1264
	s_andn2_b64 vcc, exec, s[0:1]
	s_cbranch_vccnz .LBB0_1263
	s_barrier
	s_branch .LBB0_1263
